# P1 conv epilogue: weight LDS reads issued at block top into dedicated registers, one lgkm wait per block
# baseline (speedup 1.0000x reference)
; #define LAS __attribute__((address_space(3)))
;     __device__ __forceinline__ void operator()(const f32x4 (&acc)[2][2][4][2], const Unit& u, int wr, int wc, int fr, int fq, LAS unsigned char* hb) const {
;     ...
;         asm volatile("s_waitcnt lgkmcnt(0)" ::: "memory"); __builtin_amdgcn_s_barrier(); asm volatile("" ::: "memory");
;         const int hr1 = H - 1, hr2 = (H - 2 + fr) < (H - 1) ? (H - 2 + fr) : (H - 1), hr3 = (H - 3 + fr) < (H - 1) ? (H - 3 + fr) : (H - 1);
;         const int ch0 = (u.pn - 4) * BM + chl;
; #pragma unroll
;         for (int ai = 0; ai < 2; ++ai)
; #pragma unroll
;             for (int m = 0; m < 4; ++m) { asm volatile("" ::: "memory"); __builtin_amdgcn_sched_barrier(0);
;                 const int q = 8 * ai + 4 * wr + m, prev = q > 0 ? q - 1 : 0; const int lr = ai * HALF + wr * 64 + m * 16 + fr, R = R0 + lr;
;                 const int Rc = R < 0 ? 0 : R; const int b = Rc / LL, p = Rc - b * LL;
;                 const bool ok = (lr >= H && R < TT);
;                 const unsigned ooff = ((unsigned)Rc * (unsigned)LDP + (unsigned)(OFF_XBC + ch0)) * 2u;
; #pragma unroll
;                 for (int bn = 0; bn < 4; ++bn) { const int bj = bn >> 1, n = bn & 1; const int co = bj * HALF + 4 * n;
;                     const unsigned woff = (unsigned)(ch0 + co) * 4u;
;                     const f32x4 w0 = *(const f32x4*)((const char*)cw + woff), w1 = *(const f32x4*)((const char*)cw + woff + XBCW * 4), w2 = *(const f32x4*)((const char*)cw + woff + 2 * XBCW * 4), w3 = *(const f32x4*)((const char*)cw + woff + 3 * XBCW * 4), bs = *(const f32x4*)((const char*)cb + woff);
;                     const LAS unsigned char* hp = hb + (prev * H * NCH + chl + co) * 2;
;                     const u32x2 q1 = *(const LAS u32x2*)(hp + hr1 * NCH * 2), q2 = *(const LAS u32x2*)(hp + hr2 * NCH * 2), q3 = *(const LAS u32x2*)(hp + hr3 * NCH * 2);
;                     const float h1[4] = {__builtin_bit_cast(float, q1.x << 16), __builtin_bit_cast(float, q1.x & 0xffff0000u), __builtin_bit_cast(float, q1.y << 16), __builtin_bit_cast(float, q1.y & 0xffff0000u)};
;                     const float h2[4] = {__builtin_bit_cast(float, q2.x << 16), __builtin_bit_cast(float, q2.x & 0xffff0000u), __builtin_bit_cast(float, q2.y << 16), __builtin_bit_cast(float, q2.y & 0xffff0000u)};
.Lp1w_skipstore:
	s_waitcnt lgkmcnt(0)
	s_barrier
	v_min_i32_e32 v136, 1, v149
	v_min_i32_e32 v146, 2, v149
	s_lshl_b32 s2, s2, 8
	s_add_i32 s22, s2, 0x3ffffc00
	v_add_u32_e32 v164, s2, v148
	v_add_u32_e32 v165, 0xfffffd00, v148
	v_lshlrev_b32_e32 v163, 9, v136
	v_lshlrev_b32_e32 v162, 9, v146
	v_add_u32_e32 v136, s17, v161
	v_max_i32_e32 v146, 0, v136
	v_mul_hi_u32 v147, v146, s56
	v_lshrrev_b32_e32 v147, 11, v147
	v_mul_u32_u24_e32 v147, 0x1010, v147
	v_sub_u32_e32 v147, v146, v147
	v_cmp_gt_i32_e64 s[4:5], s50, v136
	v_mul_lo_u32 v136, v146, s51
	v_add_u32_e32 v146, s37, v165
	v_lshl_add_u32 v166, v146, 1, s53
	v_cmp_lt_i32_e32 vcc, 2, v161
	v_add_u32_e32 v167, v166, v163
	s_and_b64 s[2:3], vcc, s[4:5]
	v_add_lshl_u32 v150, v136, v164, 1
	v_cmp_eq_u32_e64 s[8:9], 0, v147
	v_cmp_lt_u32_e64 s[6:7], 1, v147
	v_cmp_lt_u32_e64 s[4:5], 2, v147
	v_add_lshl_u32 v136, s22, v148, 2
	ds_read_b64 v[146:147], v166 offset:1024
	v_add_u32_e32 v168, v166, v162
	ds_read_b64 v[148:149], v167 offset:512
	ds_read_b64 v[184:185], v168
	ds_read_b128 v[208:211], v238 offset:4096
	ds_read_b128 v[212:215], v238 offset:3072
	ds_read_b128 v[216:219], v238 offset:2048
	ds_read_b128 v[220:223], v238 offset:1024
	ds_read_b128 v[224:227], v238
	v_readlane_b32 s22, v237, 58
	v_mov_b32_e32 v151, v137
	s_waitcnt lgkmcnt(0)
	v_lshlrev_b32_e32 v179, 16, v146
	v_and_b32_e32 v182, 0xffff0000, v146
	v_lshlrev_b32_e32 v173, 16, v147
	v_and_b32_e32 v174, 0xffff0000, v147
	v_lshlrev_b32_e32 v177, 16, v148
	v_and_b32_e32 v178, 0xffff0000, v148
	v_lshlrev_b32_e32 v171, 16, v149
	v_and_b32_e32 v172, 0xffff0000, v149
	v_lshlrev_b32_e32 v175, 16, v184
	v_and_b32_e32 v176, 0xffff0000, v184
	v_lshlrev_b32_e32 v169, 16, v185
	v_and_b32_e32 v170, 0xffff0000, v185
	v_readlane_b32 s23, v237, 59
	v_mov_b32_dpp v179, v124 row_shr:1 row_mask:0xf bank_mask:0xf
	v_mov_b32_dpp v177, v124 row_shr:2 row_mask:0xf bank_mask:0xf
	v_mov_b32_dpp v175, v124 row_shr:3 row_mask:0xf bank_mask:0xf
	v_mov_b32_dpp v182, v125 row_shr:1 row_mask:0xf bank_mask:0xf
	v_mov_b32_dpp v178, v125 row_shr:2 row_mask:0xf bank_mask:0xf
	v_mov_b32_dpp v176, v125 row_shr:3 row_mask:0xf bank_mask:0xf
	v_mov_b32_dpp v173, v126 row_shr:1 row_mask:0xf bank_mask:0xf
	v_mov_b32_dpp v171, v126 row_shr:2 row_mask:0xf bank_mask:0xf
	v_mov_b32_dpp v169, v126 row_shr:3 row_mask:0xf bank_mask:0xf
	v_mov_b32_dpp v174, v127 row_shr:1 row_mask:0xf bank_mask:0xf
	v_mov_b32_dpp v172, v127 row_shr:2 row_mask:0xf bank_mask:0xf
	v_mov_b32_dpp v170, v127 row_shr:3 row_mask:0xf bank_mask:0xf
	v_lshl_add_u64 v[150:151], s[22:23], 0, v[150:151]
	s_and_saveexec_b64 s[22:23], s[2:3]
	s_cbranch_execz .LBB0_185
	v_cndmask_b32_e64 v183, v182, 0, s[8:9]
	s_nop 0
	v_cndmask_b32_e64 v182, v179, 0, s[8:9]
	v_cndmask_b32_e64 v179, 0, v178, s[6:7]
	v_cndmask_b32_e64 v178, 0, v177, s[6:7]
	v_cndmask_b32_e64 v177, 0, v176, s[4:5]
	v_cndmask_b32_e64 v176, 0, v175, s[4:5]
	v_pk_fma_f32 v[124:125], v[124:125], v[212:213], v[208:209]
	v_pk_fma_f32 v[126:127], v[126:127], v[214:215], v[210:211]
	v_pk_fma_f32 v[124:125], v[182:183], v[216:217], v[124:125]
	s_nop 0
	v_pk_fma_f32 v[124:125], v[178:179], v[220:221], v[124:125]
	s_nop 0
	v_pk_fma_f32 v[124:125], v[176:177], v[224:225], v[124:125]
	s_nop 0
	v_mul_f32_e32 v175, 0xbfb8aa3b, v125
	v_exp_f32_e32 v175, v175
	s_nop 0
	v_add_f32_e32 v175, 1.0, v175
	v_rcp_f32_e32 v177, v175
	v_mul_f32_e32 v175, 0xbfb8aa3b, v124
	v_exp_f32_e32 v175, v175
	s_nop 0
	v_add_f32_e32 v175, 1.0, v175
	v_rcp_f32_e32 v176, v175
	v_cndmask_b32_e64 v175, v174, 0, s[8:9]
	v_cndmask_b32_e64 v174, v173, 0, s[8:9]
	v_pk_fma_f32 v[126:127], v[174:175], v[218:219], v[126:127]
	v_cndmask_b32_e64 v173, 0, v172, s[6:7]
	v_cndmask_b32_e64 v172, 0, v171, s[6:7]
	v_pk_fma_f32 v[126:127], v[172:173], v[222:223], v[126:127]
	v_cndmask_b32_e64 v171, 0, v170, s[4:5]
	v_cndmask_b32_e64 v170, 0, v169, s[4:5]
	v_pk_mul_f32 v[124:125], v[124:125], v[176:177]
	v_pk_fma_f32 v[126:127], v[170:171], v[226:227], v[126:127]
	v_cvt_pk_bf16_f32 v124, v124, v125
	v_mul_f32_e32 v125, 0xbfb8aa3b, v127
	v_exp_f32_e32 v125, v125
	s_nop 0
	v_add_f32_e32 v125, 1.0, v125
	v_rcp_f32_e32 v171, v125
	v_mul_f32_e32 v125, 0xbfb8aa3b, v126
	v_exp_f32_e32 v125, v125
	s_nop 0
	v_add_f32_e32 v125, 1.0, v125
	v_rcp_f32_e32 v170, v125
	s_nop 0
	v_pk_mul_f32 v[126:127], v[126:127], v[170:171]
	s_nop 0
	v_cvt_pk_bf16_f32 v125, v126, v127
	global_store_dwordx2 v[150:151], v[124:125], off
;     __device__ __forceinline__ void operator()(const f32x4 (&acc)[2][2][4][2], const Unit& u, int wr, int wc, int fr, int fq, LAS unsigned char* hb) const {
;     ...
;                 for (int bn = 0; bn < 4; ++bn) { const int bj = bn >> 1, n = bn & 1; const int co = bj * HALF + 4 * n;
;                     const unsigned woff = (unsigned)(ch0 + co) * 4u;
;                     const f32x4 w0 = *(const f32x4*)((const char*)cw + woff), w1 = *(const f32x4*)((const char*)cw + woff + XBCW * 4), w2 = *(const f32x4*)((const char*)cw + woff + 2 * XBCW * 4), w3 = *(const f32x4*)((const char*)cw + woff + 3 * XBCW * 4), bs = *(const f32x4*)((const char*)cb + woff);
;                     const LAS unsigned char* hp = hb + (prev * H * NCH + chl + co) * 2;
;                     const u32x2 q1 = *(const LAS u32x2*)(hp + hr1 * NCH * 2), q2 = *(const LAS u32x2*)(hp + hr2 * NCH * 2), q3 = *(const LAS u32x2*)(hp + hr3 * NCH * 2);
;                     const float h1[4] = {__builtin_bit_cast(float, q1.x << 16), __builtin_bit_cast(float, q1.x & 0xffff0000u), __builtin_bit_cast(float, q1.y << 16), __builtin_bit_cast(float, q1.y & 0xffff0000u)};
;                     const float h2[4] = {__builtin_bit_cast(float, q2.x << 16), __builtin_bit_cast(float, q2.x & 0xffff0000u), __builtin_bit_cast(float, q2.y << 16), __builtin_bit_cast(float, q2.y & 0xffff0000u)};
;                     const float h3[4] = {__builtin_bit_cast(float, q3.x << 16), __builtin_bit_cast(float, q3.x & 0xffff0000u), __builtin_bit_cast(float, q3.y << 16), __builtin_bit_cast(float, q3.y & 0xffff0000u)};
;                     const f32x4 gv = acc[ai][bj][m][n];
;                     float o[4];
; #pragma unroll
;                     for (int j = 0; j < 4; ++j) { const float g = gv[j];
;                         float g1 = dpp_row_shr<1>(h1[j], g), g2 = dpp_row_shr<2>(h2[j], g), g3 = dpp_row_shr<3>(h3[j], g);
;                         g1 = p >= 1 ? g1 : 0.f; g2 = p >= 2 ? g2 : 0.f; g3 = p >= 3 ? g3 : 0.f;
;                         const float v = bs[j] + w3[j] * g + w2[j] * g1 + w1[j] * g2 + w0[j] * g3;
;                         o[j] = v * __builtin_amdgcn_rcpf(1.f + ex2(-1.4426950408889634f * v)); }
;                     if (ok) { u32x2 w; w.x = pk2e(o[0], o[1]); w.y = pk2e(o[2], o[3]); *(u32x2*)((char*)O + ooff + co * 2) = w; }
;                     asm volatile("" ::: "memory"); }
.LBB0_185:
	s_or_b64 exec, exec, s[22:23]
	ds_read_b64 v[124:125], v166 offset:1032
	ds_read_b64 v[126:127], v167 offset:520
	ds_read_b64 v[186:187], v168 offset:8
	ds_read_b128 v[208:211], v238 offset:4112
	ds_read_b128 v[212:215], v238 offset:3088
	ds_read_b128 v[216:219], v238 offset:2064
	ds_read_b128 v[220:223], v238 offset:1040
	ds_read_b128 v[224:227], v238 offset:16
	v_add_u32_e32 v184, 16, v136
	v_mov_b32_e32 v185, v137
	s_waitcnt lgkmcnt(0)
	v_lshlrev_b32_e32 v179, 16, v124
	v_and_b32_e32 v182, 0xffff0000, v124
	v_lshlrev_b32_e32 v173, 16, v125
	v_and_b32_e32 v174, 0xffff0000, v125
	v_lshlrev_b32_e32 v177, 16, v126
	v_and_b32_e32 v178, 0xffff0000, v126
	v_lshlrev_b32_e32 v171, 16, v127
	v_and_b32_e32 v172, 0xffff0000, v127
	v_lshlrev_b32_e32 v175, 16, v186
	v_and_b32_e32 v176, 0xffff0000, v186
	v_lshlrev_b32_e32 v169, 16, v187
	v_and_b32_e32 v170, 0xffff0000, v187
	v_mov_b32_dpp v179, v120 row_shr:1 row_mask:0xf bank_mask:0xf
	v_mov_b32_dpp v177, v120 row_shr:2 row_mask:0xf bank_mask:0xf
	v_mov_b32_dpp v175, v120 row_shr:3 row_mask:0xf bank_mask:0xf
	v_mov_b32_dpp v182, v121 row_shr:1 row_mask:0xf bank_mask:0xf
	v_mov_b32_dpp v178, v121 row_shr:2 row_mask:0xf bank_mask:0xf
	v_mov_b32_dpp v176, v121 row_shr:3 row_mask:0xf bank_mask:0xf
	v_mov_b32_dpp v173, v122 row_shr:1 row_mask:0xf bank_mask:0xf
	v_mov_b32_dpp v171, v122 row_shr:2 row_mask:0xf bank_mask:0xf
	v_mov_b32_dpp v169, v122 row_shr:3 row_mask:0xf bank_mask:0xf
	v_mov_b32_dpp v174, v123 row_shr:1 row_mask:0xf bank_mask:0xf
	v_mov_b32_dpp v172, v123 row_shr:2 row_mask:0xf bank_mask:0xf
	v_mov_b32_dpp v170, v123 row_shr:3 row_mask:0xf bank_mask:0xf
	s_and_saveexec_b64 s[22:23], s[2:3]
	s_cbranch_execz .LBB0_187
	v_cndmask_b32_e64 v183, v182, 0, s[8:9]
	s_nop 0
	v_cndmask_b32_e64 v182, v179, 0, s[8:9]
	v_cndmask_b32_e64 v179, 0, v178, s[6:7]
	v_cndmask_b32_e64 v178, 0, v177, s[6:7]
	v_cndmask_b32_e64 v177, 0, v176, s[4:5]
	v_cndmask_b32_e64 v176, 0, v175, s[4:5]
	v_pk_fma_f32 v[120:121], v[120:121], v[212:213], v[208:209]
	v_pk_fma_f32 v[122:123], v[122:123], v[214:215], v[210:211]
	v_pk_fma_f32 v[120:121], v[182:183], v[216:217], v[120:121]
	s_nop 0
	v_pk_fma_f32 v[120:121], v[178:179], v[220:221], v[120:121]
	s_nop 0
	v_pk_fma_f32 v[120:121], v[176:177], v[224:225], v[120:121]
	s_nop 0
	v_mul_f32_e32 v175, 0xbfb8aa3b, v121
	v_exp_f32_e32 v175, v175
	s_nop 0
	v_add_f32_e32 v175, 1.0, v175
	v_rcp_f32_e32 v177, v175
	v_mul_f32_e32 v175, 0xbfb8aa3b, v120
	v_exp_f32_e32 v175, v175
	s_nop 0
	v_add_f32_e32 v175, 1.0, v175
	v_rcp_f32_e32 v176, v175
	v_cndmask_b32_e64 v175, v174, 0, s[8:9]
	v_cndmask_b32_e64 v174, v173, 0, s[8:9]
	v_pk_fma_f32 v[122:123], v[174:175], v[218:219], v[122:123]
	v_cndmask_b32_e64 v173, 0, v172, s[6:7]
	v_cndmask_b32_e64 v172, 0, v171, s[6:7]
	v_pk_fma_f32 v[122:123], v[172:173], v[222:223], v[122:123]
	v_cndmask_b32_e64 v171, 0, v170, s[4:5]
	v_cndmask_b32_e64 v170, 0, v169, s[4:5]
	v_pk_mul_f32 v[120:121], v[120:121], v[176:177]
	v_pk_fma_f32 v[122:123], v[170:171], v[226:227], v[122:123]
	v_cvt_pk_bf16_f32 v120, v120, v121
	v_mul_f32_e32 v121, 0xbfb8aa3b, v123
	v_exp_f32_e32 v121, v121
	s_nop 0
	v_add_f32_e32 v121, 1.0, v121
	v_rcp_f32_e32 v171, v121
	v_mul_f32_e32 v121, 0xbfb8aa3b, v122
	v_exp_f32_e32 v121, v121
	s_nop 0
	v_add_f32_e32 v121, 1.0, v121
	v_rcp_f32_e32 v170, v121
	s_nop 0
	v_pk_mul_f32 v[122:123], v[122:123], v[170:171]
	s_nop 0
	v_cvt_pk_bf16_f32 v121, v122, v123
	global_store_dwordx2 v[150:151], v[120:121], off offset:8
.LBB0_187:
	s_or_b64 exec, exec, s[22:23]
	ds_read_b64 v[120:121], v166 offset:1280
	ds_read_b64 v[122:123], v167 offset:768
	ds_read_b64 v[186:187], v168 offset:256
	ds_read_b128 v[208:211], v238 offset:4608
	ds_read_b128 v[212:215], v238 offset:3584
	ds_read_b128 v[216:219], v238 offset:2560
	ds_read_b128 v[220:223], v238 offset:1536
	ds_read_b128 v[224:227], v238 offset:512
	v_add_u32_e32 v184, 0x200, v136
	v_mov_b32_e32 v185, v137
	s_waitcnt lgkmcnt(0)
	v_lshlrev_b32_e32 v179, 16, v120
	v_and_b32_e32 v182, 0xffff0000, v120
	v_lshlrev_b32_e32 v173, 16, v121
	v_and_b32_e32 v174, 0xffff0000, v121
	v_lshlrev_b32_e32 v177, 16, v122
	v_and_b32_e32 v178, 0xffff0000, v122
	v_lshlrev_b32_e32 v171, 16, v123
	v_and_b32_e32 v172, 0xffff0000, v123
	v_lshlrev_b32_e32 v175, 16, v186
	v_and_b32_e32 v176, 0xffff0000, v186
	v_lshlrev_b32_e32 v169, 16, v187
	v_and_b32_e32 v170, 0xffff0000, v187
	v_mov_b32_dpp v179, v116 row_shr:1 row_mask:0xf bank_mask:0xf
	v_mov_b32_dpp v177, v116 row_shr:2 row_mask:0xf bank_mask:0xf
	v_mov_b32_dpp v175, v116 row_shr:3 row_mask:0xf bank_mask:0xf
	v_mov_b32_dpp v182, v117 row_shr:1 row_mask:0xf bank_mask:0xf
	v_mov_b32_dpp v178, v117 row_shr:2 row_mask:0xf bank_mask:0xf
	v_mov_b32_dpp v176, v117 row_shr:3 row_mask:0xf bank_mask:0xf
	v_mov_b32_dpp v173, v118 row_shr:1 row_mask:0xf bank_mask:0xf
	v_mov_b32_dpp v171, v118 row_shr:2 row_mask:0xf bank_mask:0xf
	v_mov_b32_dpp v169, v118 row_shr:3 row_mask:0xf bank_mask:0xf
	v_mov_b32_dpp v174, v119 row_shr:1 row_mask:0xf bank_mask:0xf
	v_mov_b32_dpp v172, v119 row_shr:2 row_mask:0xf bank_mask:0xf
	v_mov_b32_dpp v170, v119 row_shr:3 row_mask:0xf bank_mask:0xf
	s_and_saveexec_b64 s[22:23], s[2:3]
	s_cbranch_execz .LBB0_189
	v_cndmask_b32_e64 v183, v182, 0, s[8:9]
	s_nop 0
	v_cndmask_b32_e64 v182, v179, 0, s[8:9]
	v_cndmask_b32_e64 v179, 0, v178, s[6:7]
	v_cndmask_b32_e64 v178, 0, v177, s[6:7]
	v_cndmask_b32_e64 v177, 0, v176, s[4:5]
	v_cndmask_b32_e64 v176, 0, v175, s[4:5]
	v_pk_fma_f32 v[116:117], v[116:117], v[212:213], v[208:209]
	v_pk_fma_f32 v[118:119], v[118:119], v[214:215], v[210:211]
	v_pk_fma_f32 v[116:117], v[182:183], v[216:217], v[116:117]
	s_nop 0
	v_pk_fma_f32 v[116:117], v[178:179], v[220:221], v[116:117]
	s_nop 0
	v_pk_fma_f32 v[116:117], v[176:177], v[224:225], v[116:117]
	s_nop 0
	v_mul_f32_e32 v175, 0xbfb8aa3b, v117
	v_exp_f32_e32 v175, v175
	s_nop 0
	v_add_f32_e32 v175, 1.0, v175
	v_rcp_f32_e32 v177, v175
	v_mul_f32_e32 v175, 0xbfb8aa3b, v116
	v_exp_f32_e32 v175, v175
	s_nop 0
	v_add_f32_e32 v175, 1.0, v175
	v_rcp_f32_e32 v176, v175
	v_cndmask_b32_e64 v175, v174, 0, s[8:9]
	v_cndmask_b32_e64 v174, v173, 0, s[8:9]
	v_pk_fma_f32 v[118:119], v[174:175], v[218:219], v[118:119]
	v_cndmask_b32_e64 v173, 0, v172, s[6:7]
	v_cndmask_b32_e64 v172, 0, v171, s[6:7]
	v_pk_fma_f32 v[118:119], v[172:173], v[222:223], v[118:119]
	v_cndmask_b32_e64 v171, 0, v170, s[4:5]
	v_cndmask_b32_e64 v170, 0, v169, s[4:5]
	v_pk_mul_f32 v[116:117], v[116:117], v[176:177]
	v_pk_fma_f32 v[118:119], v[170:171], v[226:227], v[118:119]
	v_cvt_pk_bf16_f32 v116, v116, v117
	v_mul_f32_e32 v117, 0xbfb8aa3b, v119
	v_exp_f32_e32 v117, v117
	s_nop 0
	v_add_f32_e32 v117, 1.0, v117
	v_rcp_f32_e32 v171, v117
	v_mul_f32_e32 v117, 0xbfb8aa3b, v118
	v_exp_f32_e32 v117, v117
	s_nop 0
	v_add_f32_e32 v117, 1.0, v117
	v_rcp_f32_e32 v170, v117
	s_nop 0
	v_pk_mul_f32 v[118:119], v[118:119], v[170:171]
	s_nop 0
	v_cvt_pk_bf16_f32 v117, v118, v119
	global_store_dwordx2 v[150:151], v[116:117], off offset:256
;     __device__ __forceinline__ void operator()(const f32x4 (&acc)[2][2][4][2], const Unit& u, int wr, int wc, int fr, int fq, LAS unsigned char* hb) const {
;     ...
;             for (int m = 0; m < 4; ++m) { asm volatile("" ::: "memory"); __builtin_amdgcn_sched_barrier(0);
;                 const int q = 8 * ai + 4 * wr + m, prev = q > 0 ? q - 1 : 0; const int lr = ai * HALF + wr * 64 + m * 16 + fr, R = R0 + lr;
;                 const int Rc = R < 0 ? 0 : R; const int b = Rc / LL, p = Rc - b * LL;
;                 const bool ok = (lr >= H && R < TT);
;                 const unsigned ooff = ((unsigned)Rc * (unsigned)LDP + (unsigned)(OFF_XBC + ch0)) * 2u;
; #pragma unroll
;                 for (int bn = 0; bn < 4; ++bn) { const int bj = bn >> 1, n = bn & 1; const int co = bj * HALF + 4 * n;
;                     const unsigned woff = (unsigned)(ch0 + co) * 4u;
;                     const f32x4 w0 = *(const f32x4*)((const char*)cw + woff), w1 = *(const f32x4*)((const char*)cw + woff + XBCW * 4), w2 = *(const f32x4*)((const char*)cw + woff + 2 * XBCW * 4), w3 = *(const f32x4*)((const char*)cw + woff + 3 * XBCW * 4), bs = *(const f32x4*)((const char*)cb + woff);
;                     const LAS unsigned char* hp = hb + (prev * H * NCH + chl + co) * 2;
;                     const u32x2 q1 = *(const LAS u32x2*)(hp + hr1 * NCH * 2), q2 = *(const LAS u32x2*)(hp + hr2 * NCH * 2), q3 = *(const LAS u32x2*)(hp + hr3 * NCH * 2);
;                     const float h1[4] = {__builtin_bit_cast(float, q1.x << 16), __builtin_bit_cast(float, q1.x & 0xffff0000u), __builtin_bit_cast(float, q1.y << 16), __builtin_bit_cast(float, q1.y & 0xffff0000u)};
;                     const float h2[4] = {__builtin_bit_cast(float, q2.x << 16), __builtin_bit_cast(float, q2.x & 0xffff0000u), __builtin_bit_cast(float, q2.y << 16), __builtin_bit_cast(float, q2.y & 0xffff0000u)};
;                     const float h3[4] = {__builtin_bit_cast(float, q3.x << 16), __builtin_bit_cast(float, q3.x & 0xffff0000u), __builtin_bit_cast(float, q3.y << 16), __builtin_bit_cast(float, q3.y & 0xffff0000u)};
;                     const f32x4 gv = acc[ai][bj][m][n];
;                     float o[4];
; #pragma unroll
;                     for (int j = 0; j < 4; ++j) { const float g = gv[j];
;                         float g1 = dpp_row_shr<1>(h1[j], g), g2 = dpp_row_shr<2>(h2[j], g), g3 = dpp_row_shr<3>(h3[j], g);
.LBB0_189:
	s_or_b64 exec, exec, s[22:23]
	ds_read_b64 v[116:117], v166 offset:1288
	ds_read_b64 v[118:119], v167 offset:776
	ds_read_b64 v[166:167], v168 offset:264
	ds_read_b128 v[208:211], v238 offset:4624
	ds_read_b128 v[212:215], v238 offset:3600
	ds_read_b128 v[216:219], v238 offset:2576
	ds_read_b128 v[220:223], v238 offset:1552
	ds_read_b128 v[224:227], v238 offset:528
	v_add_u32_e32 v136, 0x210, v136
	s_waitcnt lgkmcnt(0)
	v_lshlrev_b32_e32 v176, 16, v116
	v_and_b32_e32 v177, 0xffff0000, v116
	v_lshlrev_b32_e32 v170, 16, v117
	v_and_b32_e32 v171, 0xffff0000, v117
	v_lshlrev_b32_e32 v174, 16, v118
	v_and_b32_e32 v175, 0xffff0000, v118
	v_lshlrev_b32_e32 v168, 16, v119
	v_and_b32_e32 v169, 0xffff0000, v119
	v_lshlrev_b32_e32 v172, 16, v166
	v_and_b32_e32 v173, 0xffff0000, v166
	v_lshlrev_b32_e32 v166, 16, v167
	v_and_b32_e32 v167, 0xffff0000, v167
	v_mov_b32_dpp v176, v112 row_shr:1 row_mask:0xf bank_mask:0xf
	v_mov_b32_dpp v174, v112 row_shr:2 row_mask:0xf bank_mask:0xf
	v_mov_b32_dpp v172, v112 row_shr:3 row_mask:0xf bank_mask:0xf
	v_mov_b32_dpp v177, v113 row_shr:1 row_mask:0xf bank_mask:0xf
	v_mov_b32_dpp v175, v113 row_shr:2 row_mask:0xf bank_mask:0xf
	v_mov_b32_dpp v173, v113 row_shr:3 row_mask:0xf bank_mask:0xf
	v_mov_b32_dpp v170, v114 row_shr:1 row_mask:0xf bank_mask:0xf
	v_mov_b32_dpp v168, v114 row_shr:2 row_mask:0xf bank_mask:0xf
	v_mov_b32_dpp v166, v114 row_shr:3 row_mask:0xf bank_mask:0xf
	v_mov_b32_dpp v171, v115 row_shr:1 row_mask:0xf bank_mask:0xf
	v_mov_b32_dpp v169, v115 row_shr:2 row_mask:0xf bank_mask:0xf
	v_mov_b32_dpp v167, v115 row_shr:3 row_mask:0xf bank_mask:0xf
	s_and_saveexec_b64 s[22:23], s[2:3]
	s_cbranch_execz .LBB0_191
	v_cndmask_b32_e64 v177, v177, 0, s[8:9]
	v_cndmask_b32_e64 v176, v176, 0, s[8:9]
	v_cndmask_b32_e64 v175, 0, v175, s[6:7]
	v_cndmask_b32_e64 v174, 0, v174, s[6:7]
	v_cndmask_b32_e64 v173, 0, v173, s[4:5]
	v_cndmask_b32_e64 v172, 0, v172, s[4:5]
	v_cndmask_b32_e64 v171, v171, 0, s[8:9]
	v_cndmask_b32_e64 v170, v170, 0, s[8:9]
	v_cndmask_b32_e64 v169, 0, v169, s[6:7]
	v_cndmask_b32_e64 v168, 0, v168, s[6:7]
	v_cndmask_b32_e64 v167, 0, v167, s[4:5]
	v_cndmask_b32_e64 v166, 0, v166, s[4:5]
	v_pk_fma_f32 v[112:113], v[112:113], v[212:213], v[208:209]
	v_pk_fma_f32 v[114:115], v[114:115], v[214:215], v[210:211]
	v_pk_fma_f32 v[112:113], v[176:177], v[216:217], v[112:113]
	v_pk_fma_f32 v[114:115], v[170:171], v[218:219], v[114:115]
	v_pk_fma_f32 v[112:113], v[174:175], v[220:221], v[112:113]
	s_nop 0
	v_pk_fma_f32 v[112:113], v[172:173], v[224:225], v[112:113]
	v_pk_fma_f32 v[114:115], v[168:169], v[222:223], v[114:115]
	v_mul_f32_e32 v136, 0xbfb8aa3b, v113
	v_exp_f32_e32 v136, v136
	v_pk_fma_f32 v[114:115], v[166:167], v[226:227], v[114:115]
	v_add_f32_e32 v136, 1.0, v136
	v_rcp_f32_e32 v173, v136
	v_mul_f32_e32 v136, 0xbfb8aa3b, v112
	v_exp_f32_e32 v136, v136
	s_nop 0
	v_add_f32_e32 v136, 1.0, v136
	v_rcp_f32_e32 v172, v136
	s_nop 0
	v_pk_mul_f32 v[112:113], v[112:113], v[172:173]
	s_nop 0
	v_cvt_pk_bf16_f32 v112, v112, v113
	v_mul_f32_e32 v113, 0xbfb8aa3b, v115
	v_exp_f32_e32 v113, v113
	s_nop 0
	v_add_f32_e32 v113, 1.0, v113
	v_rcp_f32_e32 v167, v113
	v_mul_f32_e32 v113, 0xbfb8aa3b, v114
	v_exp_f32_e32 v113, v113
	s_nop 0
	v_add_f32_e32 v113, 1.0, v113
	v_rcp_f32_e32 v166, v113
	s_nop 0
	v_pk_mul_f32 v[114:115], v[114:115], v[166:167]
	s_nop 0
	v_cvt_pk_bf16_f32 v113, v114, v115
	global_store_dwordx2 v[150:151], v[112:113], off offset:264
.LBB0_191:
	s_or_b64 exec, exec, s[22:23]
	v_add_u32_e32 v112, 16, v161
	v_add_u32_e32 v113, s17, v112
	v_max_i32_e32 v114, 0, v113
	v_mul_hi_u32 v115, v114, s56
	v_lshrrev_b32_e32 v115, 11, v115
	v_cmp_lt_i32_e32 vcc, 2, v112
	v_mul_lo_u32 v112, v114, s51
	v_mul_u32_u24_e32 v115, 0x1010, v115
	v_add_lshl_u32 v136, v112, v164, 1
	v_add_u32_e32 v112, s38, v165
	v_sub_u32_e32 v115, v114, v115
	v_cmp_gt_i32_e64 s[4:5], s50, v113
	v_lshl_add_u32 v114, v112, 1, s53
	s_and_b64 s[2:3], vcc, s[4:5]
	v_cmp_eq_u32_e64 s[8:9], 0, v115
	v_cmp_lt_u32_e64 s[6:7], 1, v115
	v_cmp_lt_u32_e64 s[4:5], 2, v115
	v_add_u32_e32 v115, v114, v163
	ds_read_b64 v[112:113], v114 offset:1024
	v_add_u32_e32 v150, v114, v162
	ds_read_b64 v[178:179], v115 offset:512
	ds_read_b64 v[182:183], v150
	ds_read_b128 v[208:211], v238 offset:4096
	ds_read_b128 v[212:215], v238 offset:3072
	ds_read_b128 v[216:219], v238 offset:2048
	ds_read_b128 v[220:223], v238 offset:1024
	ds_read_b128 v[224:227], v238
	v_readlane_b32 s22, v237, 58
	v_readlane_b32 s23, v237, 59
	s_waitcnt lgkmcnt(0)
	v_lshlrev_b32_e32 v175, 16, v112
	v_and_b32_e32 v176, 0xffff0000, v112
	v_lshlrev_b32_e32 v169, 16, v113
	v_and_b32_e32 v170, 0xffff0000, v113
	v_lshlrev_b32_e32 v173, 16, v178
	v_and_b32_e32 v174, 0xffff0000, v178
	v_lshlrev_b32_e32 v167, 16, v179
	v_and_b32_e32 v168, 0xffff0000, v179
	v_lshlrev_b32_e32 v171, 16, v182
	v_and_b32_e32 v172, 0xffff0000, v182
	v_lshlrev_b32_e32 v151, 16, v183
	v_and_b32_e32 v166, 0xffff0000, v183
	v_mov_b32_dpp v175, v108 row_shr:1 row_mask:0xf bank_mask:0xf
	v_mov_b32_dpp v173, v108 row_shr:2 row_mask:0xf bank_mask:0xf
	v_mov_b32_dpp v171, v108 row_shr:3 row_mask:0xf bank_mask:0xf
	v_mov_b32_dpp v176, v109 row_shr:1 row_mask:0xf bank_mask:0xf
	v_mov_b32_dpp v174, v109 row_shr:2 row_mask:0xf bank_mask:0xf
	v_mov_b32_dpp v172, v109 row_shr:3 row_mask:0xf bank_mask:0xf
	v_mov_b32_dpp v169, v110 row_shr:1 row_mask:0xf bank_mask:0xf
	v_mov_b32_dpp v167, v110 row_shr:2 row_mask:0xf bank_mask:0xf
	v_mov_b32_dpp v151, v110 row_shr:3 row_mask:0xf bank_mask:0xf
	v_mov_b32_dpp v170, v111 row_shr:1 row_mask:0xf bank_mask:0xf
	v_mov_b32_dpp v168, v111 row_shr:2 row_mask:0xf bank_mask:0xf
	v_mov_b32_dpp v166, v111 row_shr:3 row_mask:0xf bank_mask:0xf
	v_lshl_add_u64 v[112:113], s[22:23], 0, v[136:137]
	s_and_saveexec_b64 s[22:23], s[2:3]
	s_cbranch_execz .LBB0_193
;     __device__ __forceinline__ void operator()(const f32x4 (&acc)[2][2][4][2], const Unit& u, int wr, int wc, int fr, int fq, LAS unsigned char* hb) const {
;     ...
;                 for (int bn = 0; bn < 4; ++bn) { const int bj = bn >> 1, n = bn & 1; const int co = bj * HALF + 4 * n;
;                     const unsigned woff = (unsigned)(ch0 + co) * 4u;
;                     const f32x4 w0 = *(const f32x4*)((const char*)cw + woff), w1 = *(const f32x4*)((const char*)cw + woff + XBCW * 4), w2 = *(const f32x4*)((const char*)cw + woff + 2 * XBCW * 4), w3 = *(const f32x4*)((const char*)cw + woff + 3 * XBCW * 4), bs = *(const f32x4*)((const char*)cb + woff);
;                     const LAS unsigned char* hp = hb + (prev * H * NCH + chl + co) * 2;
;                     const u32x2 q1 = *(const LAS u32x2*)(hp + hr1 * NCH * 2), q2 = *(const LAS u32x2*)(hp + hr2 * NCH * 2), q3 = *(const LAS u32x2*)(hp + hr3 * NCH * 2);
;                     const float h1[4] = {__builtin_bit_cast(float, q1.x << 16), __builtin_bit_cast(float, q1.x & 0xffff0000u), __builtin_bit_cast(float, q1.y << 16), __builtin_bit_cast(float, q1.y & 0xffff0000u)};
;                     const float h2[4] = {__builtin_bit_cast(float, q2.x << 16), __builtin_bit_cast(float, q2.x & 0xffff0000u), __builtin_bit_cast(float, q2.y << 16), __builtin_bit_cast(float, q2.y & 0xffff0000u)};
;                     const float h3[4] = {__builtin_bit_cast(float, q3.x << 16), __builtin_bit_cast(float, q3.x & 0xffff0000u), __builtin_bit_cast(float, q3.y << 16), __builtin_bit_cast(float, q3.y & 0xffff0000u)};
;                     const f32x4 gv = acc[ai][bj][m][n];
;                     float o[4];
; #pragma unroll
;                     for (int j = 0; j < 4; ++j) { const float g = gv[j];
;                         float g1 = dpp_row_shr<1>(h1[j], g), g2 = dpp_row_shr<2>(h2[j], g), g3 = dpp_row_shr<3>(h3[j], g);
;                         g1 = p >= 1 ? g1 : 0.f; g2 = p >= 2 ? g2 : 0.f; g3 = p >= 3 ? g3 : 0.f;
;                         const float v = bs[j] + w3[j] * g + w2[j] * g1 + w1[j] * g2 + w0[j] * g3;
;                         o[j] = v * __builtin_amdgcn_rcpf(1.f + ex2(-1.4426950408889634f * v)); }
;                     if (ok) { u32x2 w; w.x = pk2e(o[0], o[1]); w.y = pk2e(o[2], o[3]); *(u32x2*)((char*)O + ooff + co * 2) = w; }
;                     asm volatile("" ::: "memory"); }
	v_cndmask_b32_e64 v177, v176, 0, s[8:9]
	v_cndmask_b32_e64 v176, v175, 0, s[8:9]
	v_cndmask_b32_e64 v175, 0, v174, s[6:7]
	v_cndmask_b32_e64 v174, 0, v173, s[6:7]
	v_cndmask_b32_e64 v173, 0, v172, s[4:5]
	v_cndmask_b32_e64 v172, 0, v171, s[4:5]
	v_cndmask_b32_e64 v171, v170, 0, s[8:9]
	v_cndmask_b32_e64 v170, v169, 0, s[8:9]
	v_cndmask_b32_e64 v169, 0, v168, s[6:7]
	v_cndmask_b32_e64 v168, 0, v167, s[6:7]
	v_cndmask_b32_e64 v167, 0, v166, s[4:5]
	v_cndmask_b32_e64 v166, 0, v151, s[4:5]
	v_pk_fma_f32 v[108:109], v[108:109], v[212:213], v[208:209]
	v_pk_fma_f32 v[110:111], v[110:111], v[214:215], v[210:211]
	v_pk_fma_f32 v[108:109], v[176:177], v[216:217], v[108:109]
	v_pk_fma_f32 v[110:111], v[170:171], v[218:219], v[110:111]
	v_pk_fma_f32 v[108:109], v[174:175], v[220:221], v[108:109]
	s_nop 0
	v_pk_fma_f32 v[108:109], v[172:173], v[224:225], v[108:109]
	v_pk_fma_f32 v[110:111], v[168:169], v[222:223], v[110:111]
	v_mul_f32_e32 v136, 0xbfb8aa3b, v109
	v_exp_f32_e32 v136, v136
	v_pk_fma_f32 v[110:111], v[166:167], v[226:227], v[110:111]
	v_add_f32_e32 v136, 1.0, v136
	v_rcp_f32_e32 v173, v136
	v_mul_f32_e32 v136, 0xbfb8aa3b, v108
	v_exp_f32_e32 v136, v136
	s_nop 0
	v_add_f32_e32 v136, 1.0, v136
	v_rcp_f32_e32 v172, v136
	s_nop 0
	v_pk_mul_f32 v[108:109], v[108:109], v[172:173]
	s_nop 0
	v_cvt_pk_bf16_f32 v108, v108, v109
	v_mul_f32_e32 v109, 0xbfb8aa3b, v111
	v_exp_f32_e32 v109, v109
	s_nop 0
	v_add_f32_e32 v109, 1.0, v109
	v_rcp_f32_e32 v167, v109
	v_mul_f32_e32 v109, 0xbfb8aa3b, v110
	v_exp_f32_e32 v109, v109
	s_nop 0
	v_add_f32_e32 v109, 1.0, v109
	v_rcp_f32_e32 v166, v109
	s_nop 0
	v_pk_mul_f32 v[110:111], v[110:111], v[166:167]
	s_nop 0
	v_cvt_pk_bf16_f32 v109, v110, v111
	global_store_dwordx2 v[112:113], v[108:109], off
.LBB0_193:
	s_or_b64 exec, exec, s[22:23]
	ds_read_b64 v[108:109], v114 offset:1032
	ds_read_b64 v[110:111], v115 offset:520
	ds_read_b64 v[172:173], v150 offset:8
	ds_read_b128 v[208:211], v238 offset:4112
	ds_read_b128 v[212:215], v238 offset:3088
	ds_read_b128 v[216:219], v238 offset:2064
	ds_read_b128 v[220:223], v238 offset:1040
	ds_read_b128 v[224:227], v238 offset:16
	s_waitcnt lgkmcnt(0)
	v_lshlrev_b32_e32 v170, 16, v108
	v_and_b32_e32 v171, 0xffff0000, v108
	v_lshlrev_b32_e32 v136, 16, v109
	v_and_b32_e32 v151, 0xffff0000, v109
	v_lshlrev_b32_e32 v168, 16, v110
	v_and_b32_e32 v169, 0xffff0000, v110
	v_lshlrev_b32_e32 v110, 16, v111
	v_and_b32_e32 v111, 0xffff0000, v111
	v_lshlrev_b32_e32 v166, 16, v172
	v_and_b32_e32 v167, 0xffff0000, v172
	v_lshlrev_b32_e32 v108, 16, v173
	v_and_b32_e32 v109, 0xffff0000, v173
	v_mov_b32_dpp v170, v104 row_shr:1 row_mask:0xf bank_mask:0xf
	v_mov_b32_dpp v168, v104 row_shr:2 row_mask:0xf bank_mask:0xf
	v_mov_b32_dpp v166, v104 row_shr:3 row_mask:0xf bank_mask:0xf
	v_mov_b32_dpp v171, v105 row_shr:1 row_mask:0xf bank_mask:0xf
	v_mov_b32_dpp v169, v105 row_shr:2 row_mask:0xf bank_mask:0xf
	v_mov_b32_dpp v167, v105 row_shr:3 row_mask:0xf bank_mask:0xf
	v_mov_b32_dpp v136, v106 row_shr:1 row_mask:0xf bank_mask:0xf
	v_mov_b32_dpp v110, v106 row_shr:2 row_mask:0xf bank_mask:0xf
	v_mov_b32_dpp v108, v106 row_shr:3 row_mask:0xf bank_mask:0xf
	v_mov_b32_dpp v151, v107 row_shr:1 row_mask:0xf bank_mask:0xf
	v_mov_b32_dpp v111, v107 row_shr:2 row_mask:0xf bank_mask:0xf
	v_mov_b32_dpp v109, v107 row_shr:3 row_mask:0xf bank_mask:0xf
	s_and_saveexec_b64 s[22:23], s[2:3]
	s_cbranch_execz .LBB0_195
	v_cndmask_b32_e64 v171, v171, 0, s[8:9]
	s_nop 0
	v_cndmask_b32_e64 v170, v170, 0, s[8:9]
	v_cndmask_b32_e64 v169, 0, v169, s[6:7]
	v_cndmask_b32_e64 v168, 0, v168, s[6:7]
	v_cndmask_b32_e64 v167, 0, v167, s[4:5]
	v_cndmask_b32_e64 v166, 0, v166, s[4:5]
	v_cndmask_b32_e64 v111, 0, v111, s[6:7]
	v_cndmask_b32_e64 v110, 0, v110, s[6:7]
	v_cndmask_b32_e64 v109, 0, v109, s[4:5]
	v_cndmask_b32_e64 v108, 0, v108, s[4:5]
	v_pk_fma_f32 v[104:105], v[104:105], v[212:213], v[208:209]
	v_pk_fma_f32 v[106:107], v[106:107], v[214:215], v[210:211]
	v_pk_fma_f32 v[104:105], v[170:171], v[216:217], v[104:105]
	s_nop 0
	v_pk_fma_f32 v[104:105], v[168:169], v[220:221], v[104:105]
	s_nop 0
	v_pk_fma_f32 v[104:105], v[166:167], v[224:225], v[104:105]
	s_nop 0
	v_mul_f32_e32 v166, 0xbfb8aa3b, v105
	v_exp_f32_e32 v166, v166
	s_nop 0
	v_add_f32_e32 v166, 1.0, v166
	v_rcp_f32_e32 v167, v166
	v_mul_f32_e32 v166, 0xbfb8aa3b, v104
	v_exp_f32_e32 v166, v166
	s_nop 0
	v_add_f32_e32 v166, 1.0, v166
	v_rcp_f32_e32 v166, v166
	s_nop 0
	v_pk_mul_f32 v[104:105], v[104:105], v[166:167]
	v_cndmask_b32_e64 v167, v151, 0, s[8:9]
	v_cndmask_b32_e64 v166, v136, 0, s[8:9]
	v_pk_fma_f32 v[106:107], v[166:167], v[218:219], v[106:107]
	v_cvt_pk_bf16_f32 v104, v104, v105
	v_pk_fma_f32 v[106:107], v[110:111], v[222:223], v[106:107]
	s_nop 0
	v_pk_fma_f32 v[106:107], v[108:109], v[226:227], v[106:107]
	s_nop 0
	v_mul_f32_e32 v105, 0xbfb8aa3b, v107
	v_exp_f32_e32 v105, v105
	s_nop 0
	v_add_f32_e32 v105, 1.0, v105
	v_rcp_f32_e32 v109, v105
	v_mul_f32_e32 v105, 0xbfb8aa3b, v106
	v_exp_f32_e32 v105, v105
	s_nop 0
	v_add_f32_e32 v105, 1.0, v105
	v_rcp_f32_e32 v108, v105
	s_nop 0
	v_pk_mul_f32 v[106:107], v[106:107], v[108:109]
	s_nop 0
	v_cvt_pk_bf16_f32 v105, v106, v107
	global_store_dwordx2 v[112:113], v[104:105], off offset:8
;     __device__ __forceinline__ void operator()(const f32x4 (&acc)[2][2][4][2], const Unit& u, int wr, int wc, int fr, int fq, LAS unsigned char* hb) const {
;     ...
;                 for (int bn = 0; bn < 4; ++bn) { const int bj = bn >> 1, n = bn & 1; const int co = bj * HALF + 4 * n;
;                     const unsigned woff = (unsigned)(ch0 + co) * 4u;
;                     const f32x4 w0 = *(const f32x4*)((const char*)cw + woff), w1 = *(const f32x4*)((const char*)cw + woff + XBCW * 4), w2 = *(const f32x4*)((const char*)cw + woff + 2 * XBCW * 4), w3 = *(const f32x4*)((const char*)cw + woff + 3 * XBCW * 4), bs = *(const f32x4*)((const char*)cb + woff);
;                     const LAS unsigned char* hp = hb + (prev * H * NCH + chl + co) * 2;
;                     const u32x2 q1 = *(const LAS u32x2*)(hp + hr1 * NCH * 2), q2 = *(const LAS u32x2*)(hp + hr2 * NCH * 2), q3 = *(const LAS u32x2*)(hp + hr3 * NCH * 2);
;                     const float h1[4] = {__builtin_bit_cast(float, q1.x << 16), __builtin_bit_cast(float, q1.x & 0xffff0000u), __builtin_bit_cast(float, q1.y << 16), __builtin_bit_cast(float, q1.y & 0xffff0000u)};
;                     const float h2[4] = {__builtin_bit_cast(float, q2.x << 16), __builtin_bit_cast(float, q2.x & 0xffff0000u), __builtin_bit_cast(float, q2.y << 16), __builtin_bit_cast(float, q2.y & 0xffff0000u)};
;                     const float h3[4] = {__builtin_bit_cast(float, q3.x << 16), __builtin_bit_cast(float, q3.x & 0xffff0000u), __builtin_bit_cast(float, q3.y << 16), __builtin_bit_cast(float, q3.y & 0xffff0000u)};
;                     const f32x4 gv = acc[ai][bj][m][n];
;                     float o[4];
; #pragma unroll
;                     for (int j = 0; j < 4; ++j) { const float g = gv[j];
;                         float g1 = dpp_row_shr<1>(h1[j], g), g2 = dpp_row_shr<2>(h2[j], g), g3 = dpp_row_shr<3>(h3[j], g);
;                         g1 = p >= 1 ? g1 : 0.f; g2 = p >= 2 ? g2 : 0.f; g3 = p >= 3 ? g3 : 0.f;
;                         const float v = bs[j] + w3[j] * g + w2[j] * g1 + w1[j] * g2 + w0[j] * g3;
;                         o[j] = v * __builtin_amdgcn_rcpf(1.f + ex2(-1.4426950408889634f * v)); }
;                     if (ok) { u32x2 w; w.x = pk2e(o[0], o[1]); w.y = pk2e(o[2], o[3]); *(u32x2*)((char*)O + ooff + co * 2) = w; }
;                     asm volatile("" ::: "memory"); }
.LBB0_195:
	s_or_b64 exec, exec, s[22:23]
	ds_read_b64 v[104:105], v114 offset:1280
	ds_read_b64 v[106:107], v115 offset:768
	ds_read_b64 v[168:169], v150 offset:256
	ds_read_b128 v[208:211], v238 offset:4608
	ds_read_b128 v[212:215], v238 offset:3584
	ds_read_b128 v[216:219], v238 offset:2560
	ds_read_b128 v[220:223], v238 offset:1536
	ds_read_b128 v[224:227], v238 offset:512
	s_waitcnt lgkmcnt(0)
	v_lshlrev_b32_e32 v166, 16, v104
	v_and_b32_e32 v167, 0xffff0000, v104
	v_lshlrev_b32_e32 v108, 16, v105
	v_and_b32_e32 v109, 0xffff0000, v105
	v_lshlrev_b32_e32 v136, 16, v106
	v_and_b32_e32 v151, 0xffff0000, v106
	v_lshlrev_b32_e32 v106, 16, v107
	v_and_b32_e32 v107, 0xffff0000, v107
	v_lshlrev_b32_e32 v110, 16, v168
	v_and_b32_e32 v111, 0xffff0000, v168
	v_lshlrev_b32_e32 v104, 16, v169
	v_and_b32_e32 v105, 0xffff0000, v169
	v_mov_b32_dpp v166, v100 row_shr:1 row_mask:0xf bank_mask:0xf
	v_mov_b32_dpp v136, v100 row_shr:2 row_mask:0xf bank_mask:0xf
	v_mov_b32_dpp v110, v100 row_shr:3 row_mask:0xf bank_mask:0xf
	v_mov_b32_dpp v167, v101 row_shr:1 row_mask:0xf bank_mask:0xf
	v_mov_b32_dpp v151, v101 row_shr:2 row_mask:0xf bank_mask:0xf
	v_mov_b32_dpp v111, v101 row_shr:3 row_mask:0xf bank_mask:0xf
	v_mov_b32_dpp v108, v102 row_shr:1 row_mask:0xf bank_mask:0xf
	v_mov_b32_dpp v106, v102 row_shr:2 row_mask:0xf bank_mask:0xf
	v_mov_b32_dpp v104, v102 row_shr:3 row_mask:0xf bank_mask:0xf
	v_mov_b32_dpp v109, v103 row_shr:1 row_mask:0xf bank_mask:0xf
	v_mov_b32_dpp v107, v103 row_shr:2 row_mask:0xf bank_mask:0xf
	v_mov_b32_dpp v105, v103 row_shr:3 row_mask:0xf bank_mask:0xf
	s_and_saveexec_b64 s[22:23], s[2:3]
	s_cbranch_execz .LBB0_197
	v_cndmask_b32_e64 v167, v167, 0, s[8:9]
	s_nop 0
	v_cndmask_b32_e64 v166, v166, 0, s[8:9]
	v_cndmask_b32_e64 v111, 0, v111, s[4:5]
	v_cndmask_b32_e64 v110, 0, v110, s[4:5]
	v_cndmask_b32_e64 v109, v109, 0, s[8:9]
	v_cndmask_b32_e64 v108, v108, 0, s[8:9]
	v_cndmask_b32_e64 v107, 0, v107, s[6:7]
	v_cndmask_b32_e64 v106, 0, v106, s[6:7]
	v_cndmask_b32_e64 v105, 0, v105, s[4:5]
	v_cndmask_b32_e64 v104, 0, v104, s[4:5]
	v_pk_fma_f32 v[100:101], v[100:101], v[212:213], v[208:209]
	v_pk_fma_f32 v[102:103], v[102:103], v[214:215], v[210:211]
	v_pk_fma_f32 v[100:101], v[166:167], v[216:217], v[100:101]
	v_cndmask_b32_e64 v167, 0, v151, s[6:7]
	v_cndmask_b32_e64 v166, 0, v136, s[6:7]
	v_pk_fma_f32 v[102:103], v[108:109], v[218:219], v[102:103]
	v_pk_fma_f32 v[100:101], v[166:167], v[220:221], v[100:101]
	s_nop 0
	v_pk_fma_f32 v[100:101], v[110:111], v[224:225], v[100:101]
	v_pk_fma_f32 v[102:103], v[106:107], v[222:223], v[102:103]
	v_mul_f32_e32 v110, 0xbfb8aa3b, v101
	v_exp_f32_e32 v110, v110
	v_pk_fma_f32 v[102:103], v[104:105], v[226:227], v[102:103]
	v_add_f32_e32 v110, 1.0, v110
	v_rcp_f32_e32 v111, v110
	v_mul_f32_e32 v110, 0xbfb8aa3b, v100
	v_exp_f32_e32 v110, v110
	s_nop 0
	v_add_f32_e32 v110, 1.0, v110
	v_rcp_f32_e32 v110, v110
	s_nop 0
	v_pk_mul_f32 v[100:101], v[100:101], v[110:111]
	s_nop 0
	v_cvt_pk_bf16_f32 v100, v100, v101
	v_mul_f32_e32 v101, 0xbfb8aa3b, v103
	v_exp_f32_e32 v101, v101
	s_nop 0
	v_add_f32_e32 v101, 1.0, v101
	v_rcp_f32_e32 v105, v101
	v_mul_f32_e32 v101, 0xbfb8aa3b, v102
	v_exp_f32_e32 v101, v101
	s_nop 0
	v_add_f32_e32 v101, 1.0, v101
	v_rcp_f32_e32 v104, v101
	s_nop 0
	v_pk_mul_f32 v[102:103], v[102:103], v[104:105]
	s_nop 0
	v_cvt_pk_bf16_f32 v101, v102, v103
	global_store_dwordx2 v[112:113], v[100:101], off offset:256
.LBB0_197:
	s_or_b64 exec, exec, s[22:23]
	ds_read_b64 v[100:101], v114 offset:1288
	ds_read_b64 v[102:103], v115 offset:776
	ds_read_b64 v[114:115], v150 offset:264
	ds_read_b128 v[208:211], v238 offset:4624
	ds_read_b128 v[212:215], v238 offset:3600
	ds_read_b128 v[216:219], v238 offset:2576
	ds_read_b128 v[220:223], v238 offset:1552
	ds_read_b128 v[224:227], v238 offset:528
	s_waitcnt lgkmcnt(0)
	v_lshlrev_b32_e32 v110, 16, v100
	v_and_b32_e32 v111, 0xffff0000, v100
	v_lshlrev_b32_e32 v104, 16, v101
	v_and_b32_e32 v105, 0xffff0000, v101
	v_lshlrev_b32_e32 v108, 16, v102
	v_and_b32_e32 v109, 0xffff0000, v102
	v_lshlrev_b32_e32 v102, 16, v103
	v_and_b32_e32 v103, 0xffff0000, v103
	v_lshlrev_b32_e32 v106, 16, v114
	v_and_b32_e32 v107, 0xffff0000, v114
	v_lshlrev_b32_e32 v100, 16, v115
	v_and_b32_e32 v101, 0xffff0000, v115
	v_mov_b32_dpp v110, v96 row_shr:1 row_mask:0xf bank_mask:0xf
	v_mov_b32_dpp v108, v96 row_shr:2 row_mask:0xf bank_mask:0xf
	v_mov_b32_dpp v106, v96 row_shr:3 row_mask:0xf bank_mask:0xf
	v_mov_b32_dpp v111, v97 row_shr:1 row_mask:0xf bank_mask:0xf
	v_mov_b32_dpp v109, v97 row_shr:2 row_mask:0xf bank_mask:0xf
	v_mov_b32_dpp v107, v97 row_shr:3 row_mask:0xf bank_mask:0xf
	v_mov_b32_dpp v104, v98 row_shr:1 row_mask:0xf bank_mask:0xf
	v_mov_b32_dpp v102, v98 row_shr:2 row_mask:0xf bank_mask:0xf
	v_mov_b32_dpp v100, v98 row_shr:3 row_mask:0xf bank_mask:0xf
	v_mov_b32_dpp v105, v99 row_shr:1 row_mask:0xf bank_mask:0xf
	v_mov_b32_dpp v103, v99 row_shr:2 row_mask:0xf bank_mask:0xf
	v_mov_b32_dpp v101, v99 row_shr:3 row_mask:0xf bank_mask:0xf
	s_and_saveexec_b64 s[22:23], s[2:3]
	s_cbranch_execz .LBB0_199
	v_cndmask_b32_e64 v111, v111, 0, s[8:9]
	v_cndmask_b32_e64 v110, v110, 0, s[8:9]
	v_cndmask_b32_e64 v109, 0, v109, s[6:7]
	v_cndmask_b32_e64 v108, 0, v108, s[6:7]
	v_cndmask_b32_e64 v107, 0, v107, s[4:5]
	v_cndmask_b32_e64 v106, 0, v106, s[4:5]
	v_cndmask_b32_e64 v105, v105, 0, s[8:9]
	v_cndmask_b32_e64 v104, v104, 0, s[8:9]
	v_cndmask_b32_e64 v103, 0, v103, s[6:7]
	v_cndmask_b32_e64 v102, 0, v102, s[6:7]
	v_cndmask_b32_e64 v101, 0, v101, s[4:5]
	v_cndmask_b32_e64 v100, 0, v100, s[4:5]
	v_pk_fma_f32 v[96:97], v[96:97], v[212:213], v[208:209]
	v_pk_fma_f32 v[98:99], v[98:99], v[214:215], v[210:211]
	v_pk_fma_f32 v[96:97], v[110:111], v[216:217], v[96:97]
	v_pk_fma_f32 v[98:99], v[104:105], v[218:219], v[98:99]
	v_pk_fma_f32 v[96:97], v[108:109], v[220:221], v[96:97]
	s_nop 0
	v_pk_fma_f32 v[96:97], v[106:107], v[224:225], v[96:97]
	v_pk_fma_f32 v[98:99], v[102:103], v[222:223], v[98:99]
	v_mul_f32_e32 v106, 0xbfb8aa3b, v97
	v_exp_f32_e32 v106, v106
	v_pk_fma_f32 v[98:99], v[100:101], v[226:227], v[98:99]
	v_add_f32_e32 v106, 1.0, v106
	v_rcp_f32_e32 v107, v106
	v_mul_f32_e32 v106, 0xbfb8aa3b, v96
	v_exp_f32_e32 v106, v106
	s_nop 0
	v_add_f32_e32 v106, 1.0, v106
	v_rcp_f32_e32 v106, v106
	s_nop 0
	v_pk_mul_f32 v[96:97], v[96:97], v[106:107]
	s_nop 0
	v_cvt_pk_bf16_f32 v96, v96, v97
	v_mul_f32_e32 v97, 0xbfb8aa3b, v99
	v_exp_f32_e32 v97, v97
	s_nop 0
	v_add_f32_e32 v97, 1.0, v97
	v_rcp_f32_e32 v101, v97
	v_mul_f32_e32 v97, 0xbfb8aa3b, v98
	v_exp_f32_e32 v97, v97
	s_nop 0
	v_add_f32_e32 v97, 1.0, v97
	v_rcp_f32_e32 v100, v97
	s_nop 0
	v_pk_mul_f32 v[98:99], v[98:99], v[100:101]
	s_nop 0
	v_cvt_pk_bf16_f32 v97, v98, v99
	global_store_dwordx2 v[112:113], v[96:97], off offset:264
;     __device__ __forceinline__ void operator()(const f32x4 (&acc)[2][2][4][2], const Unit& u, int wr, int wc, int fr, int fq, LAS unsigned char* hb) const {
;     ...
;                 const int q = 8 * ai + 4 * wr + m, prev = q > 0 ? q - 1 : 0; const int lr = ai * HALF + wr * 64 + m * 16 + fr, R = R0 + lr;
;                 const int Rc = R < 0 ? 0 : R; const int b = Rc / LL, p = Rc - b * LL;
;                 const bool ok = (lr >= H && R < TT);
;                 const unsigned ooff = ((unsigned)Rc * (unsigned)LDP + (unsigned)(OFF_XBC + ch0)) * 2u;
; #pragma unroll
;                 for (int bn = 0; bn < 4; ++bn) { const int bj = bn >> 1, n = bn & 1; const int co = bj * HALF + 4 * n;
;                     const unsigned woff = (unsigned)(ch0 + co) * 4u;
;                     const f32x4 w0 = *(const f32x4*)((const char*)cw + woff), w1 = *(const f32x4*)((const char*)cw + woff + XBCW * 4), w2 = *(const f32x4*)((const char*)cw + woff + 2 * XBCW * 4), w3 = *(const f32x4*)((const char*)cw + woff + 3 * XBCW * 4), bs = *(const f32x4*)((const char*)cb + woff);
;                     const LAS unsigned char* hp = hb + (prev * H * NCH + chl + co) * 2;
;                     const u32x2 q1 = *(const LAS u32x2*)(hp + hr1 * NCH * 2), q2 = *(const LAS u32x2*)(hp + hr2 * NCH * 2), q3 = *(const LAS u32x2*)(hp + hr3 * NCH * 2);
;                     const float h1[4] = {__builtin_bit_cast(float, q1.x << 16), __builtin_bit_cast(float, q1.x & 0xffff0000u), __builtin_bit_cast(float, q1.y << 16), __builtin_bit_cast(float, q1.y & 0xffff0000u)};
;                     const float h2[4] = {__builtin_bit_cast(float, q2.x << 16), __builtin_bit_cast(float, q2.x & 0xffff0000u), __builtin_bit_cast(float, q2.y << 16), __builtin_bit_cast(float, q2.y & 0xffff0000u)};
;                     const float h3[4] = {__builtin_bit_cast(float, q3.x << 16), __builtin_bit_cast(float, q3.x & 0xffff0000u), __builtin_bit_cast(float, q3.y << 16), __builtin_bit_cast(float, q3.y & 0xffff0000u)};
;                     const f32x4 gv = acc[ai][bj][m][n];
;                     float o[4];
; #pragma unroll
;                     for (int j = 0; j < 4; ++j) { const float g = gv[j];
;                         float g1 = dpp_row_shr<1>(h1[j], g), g2 = dpp_row_shr<2>(h2[j], g), g3 = dpp_row_shr<3>(h3[j], g);
;                         g1 = p >= 1 ? g1 : 0.f; g2 = p >= 2 ? g2 : 0.f; g3 = p >= 3 ? g3 : 0.f;
.LBB0_199:
	s_or_b64 exec, exec, s[22:23]
	v_add_u32_e32 v96, 32, v161
	v_add_u32_e32 v97, s17, v96
	v_max_i32_e32 v98, 0, v97
	v_mul_hi_u32 v99, v98, s56
	v_lshrrev_b32_e32 v99, 11, v99
	v_cmp_lt_i32_e32 vcc, 2, v96
	v_mul_lo_u32 v96, v98, s51
	v_mul_u32_u24_e32 v99, 0x1010, v99
	v_add_lshl_u32 v136, v96, v164, 1
	v_add_u32_e32 v96, s39, v165
	v_sub_u32_e32 v99, v98, v99
	v_cmp_gt_i32_e64 s[4:5], s50, v97
	v_lshl_add_u32 v98, v96, 1, s53
	s_and_b64 s[2:3], vcc, s[4:5]
	v_cmp_eq_u32_e64 s[8:9], 0, v99
	v_cmp_lt_u32_e64 s[6:7], 1, v99
	v_cmp_lt_u32_e64 s[4:5], 2, v99
	v_add_u32_e32 v99, v98, v163
	ds_read_b64 v[96:97], v98 offset:1024
	v_add_u32_e32 v100, v98, v162
	ds_read_b64 v[114:115], v99 offset:512
	ds_read_b64 v[150:151], v100
	ds_read_b128 v[208:211], v238 offset:4096
	ds_read_b128 v[212:215], v238 offset:3072
	ds_read_b128 v[216:219], v238 offset:2048
	ds_read_b128 v[220:223], v238 offset:1024
	ds_read_b128 v[224:227], v238
	v_readlane_b32 s22, v237, 58
	v_readlane_b32 s23, v237, 59
	s_waitcnt lgkmcnt(0)
	v_lshlrev_b32_e32 v111, 16, v96
	v_and_b32_e32 v112, 0xffff0000, v96
	v_lshlrev_b32_e32 v105, 16, v97
	v_and_b32_e32 v106, 0xffff0000, v97
	v_lshlrev_b32_e32 v109, 16, v114
	v_and_b32_e32 v110, 0xffff0000, v114
	v_lshlrev_b32_e32 v103, 16, v115
	v_and_b32_e32 v104, 0xffff0000, v115
	v_lshlrev_b32_e32 v107, 16, v150
	v_and_b32_e32 v108, 0xffff0000, v150
	v_lshlrev_b32_e32 v101, 16, v151
	v_and_b32_e32 v102, 0xffff0000, v151
	v_mov_b32_dpp v111, v92 row_shr:1 row_mask:0xf bank_mask:0xf
	v_mov_b32_dpp v109, v92 row_shr:2 row_mask:0xf bank_mask:0xf
	v_mov_b32_dpp v107, v92 row_shr:3 row_mask:0xf bank_mask:0xf
	v_mov_b32_dpp v112, v93 row_shr:1 row_mask:0xf bank_mask:0xf
	v_mov_b32_dpp v110, v93 row_shr:2 row_mask:0xf bank_mask:0xf
	v_mov_b32_dpp v108, v93 row_shr:3 row_mask:0xf bank_mask:0xf
	v_mov_b32_dpp v105, v94 row_shr:1 row_mask:0xf bank_mask:0xf
	v_mov_b32_dpp v103, v94 row_shr:2 row_mask:0xf bank_mask:0xf
	v_mov_b32_dpp v101, v94 row_shr:3 row_mask:0xf bank_mask:0xf
	v_mov_b32_dpp v106, v95 row_shr:1 row_mask:0xf bank_mask:0xf
	v_mov_b32_dpp v104, v95 row_shr:2 row_mask:0xf bank_mask:0xf
	v_mov_b32_dpp v102, v95 row_shr:3 row_mask:0xf bank_mask:0xf
	v_lshl_add_u64 v[96:97], s[22:23], 0, v[136:137]
	s_and_saveexec_b64 s[22:23], s[2:3]
	s_cbranch_execz .LBB0_201
	v_cndmask_b32_e64 v113, v112, 0, s[8:9]
	v_cndmask_b32_e64 v112, v111, 0, s[8:9]
	v_cndmask_b32_e64 v111, 0, v110, s[6:7]
	v_cndmask_b32_e64 v110, 0, v109, s[6:7]
	v_cndmask_b32_e64 v109, 0, v108, s[4:5]
	v_cndmask_b32_e64 v108, 0, v107, s[4:5]
	v_pk_fma_f32 v[92:93], v[92:93], v[212:213], v[208:209]
	v_pk_fma_f32 v[94:95], v[94:95], v[214:215], v[210:211]
	v_pk_fma_f32 v[92:93], v[112:113], v[216:217], v[92:93]
	s_nop 0
	v_pk_fma_f32 v[92:93], v[110:111], v[220:221], v[92:93]
	s_nop 0
	v_pk_fma_f32 v[92:93], v[108:109], v[224:225], v[92:93]
	s_nop 0
	v_mul_f32_e32 v107, 0xbfb8aa3b, v93
	v_exp_f32_e32 v107, v107
	s_nop 0
	v_add_f32_e32 v107, 1.0, v107
	v_rcp_f32_e32 v109, v107
	v_mul_f32_e32 v107, 0xbfb8aa3b, v92
	v_exp_f32_e32 v107, v107
	s_nop 0
	v_add_f32_e32 v107, 1.0, v107
	v_rcp_f32_e32 v108, v107
	v_cndmask_b32_e64 v107, v106, 0, s[8:9]
	v_cndmask_b32_e64 v106, v105, 0, s[8:9]
	v_pk_fma_f32 v[94:95], v[106:107], v[218:219], v[94:95]
	v_cndmask_b32_e64 v105, 0, v104, s[6:7]
	v_cndmask_b32_e64 v104, 0, v103, s[6:7]
	v_pk_fma_f32 v[94:95], v[104:105], v[222:223], v[94:95]
	v_cndmask_b32_e64 v103, 0, v102, s[4:5]
	v_cndmask_b32_e64 v102, 0, v101, s[4:5]
	v_pk_mul_f32 v[92:93], v[92:93], v[108:109]
	v_pk_fma_f32 v[94:95], v[102:103], v[226:227], v[94:95]
	v_cvt_pk_bf16_f32 v92, v92, v93
	v_mul_f32_e32 v93, 0xbfb8aa3b, v95
	v_exp_f32_e32 v93, v93
	s_nop 0
	v_add_f32_e32 v93, 1.0, v93
	v_rcp_f32_e32 v103, v93
	v_mul_f32_e32 v93, 0xbfb8aa3b, v94
	v_exp_f32_e32 v93, v93
	s_nop 0
	v_add_f32_e32 v93, 1.0, v93
	v_rcp_f32_e32 v102, v93
	s_nop 0
	v_pk_mul_f32 v[94:95], v[94:95], v[102:103]
	s_nop 0
	v_cvt_pk_bf16_f32 v93, v94, v95
	global_store_dwordx2 v[96:97], v[92:93], off
.LBB0_201:
	s_or_b64 exec, exec, s[22:23]
	ds_read_b64 v[92:93], v98 offset:1032
	ds_read_b64 v[94:95], v99 offset:520
	ds_read_b64 v[110:111], v100 offset:8
	ds_read_b128 v[208:211], v238 offset:4112
	ds_read_b128 v[212:215], v238 offset:3088
	ds_read_b128 v[216:219], v238 offset:2064
	ds_read_b128 v[220:223], v238 offset:1040
	ds_read_b128 v[224:227], v238 offset:16
	s_waitcnt lgkmcnt(0)
	v_lshlrev_b32_e32 v107, 16, v92
	v_and_b32_e32 v108, 0xffff0000, v92
	v_lshlrev_b32_e32 v101, 16, v93
	v_and_b32_e32 v102, 0xffff0000, v93
	v_lshlrev_b32_e32 v105, 16, v94
	v_and_b32_e32 v106, 0xffff0000, v94
	v_lshlrev_b32_e32 v94, 16, v95
	v_and_b32_e32 v95, 0xffff0000, v95
	v_lshlrev_b32_e32 v103, 16, v110
	v_and_b32_e32 v104, 0xffff0000, v110
	v_lshlrev_b32_e32 v92, 16, v111
	v_and_b32_e32 v93, 0xffff0000, v111
	v_mov_b32_dpp v107, v88 row_shr:1 row_mask:0xf bank_mask:0xf
	v_mov_b32_dpp v105, v88 row_shr:2 row_mask:0xf bank_mask:0xf
	v_mov_b32_dpp v103, v88 row_shr:3 row_mask:0xf bank_mask:0xf
	v_mov_b32_dpp v108, v89 row_shr:1 row_mask:0xf bank_mask:0xf
	v_mov_b32_dpp v106, v89 row_shr:2 row_mask:0xf bank_mask:0xf
	v_mov_b32_dpp v104, v89 row_shr:3 row_mask:0xf bank_mask:0xf
	v_mov_b32_dpp v101, v90 row_shr:1 row_mask:0xf bank_mask:0xf
	v_mov_b32_dpp v94, v90 row_shr:2 row_mask:0xf bank_mask:0xf
	v_mov_b32_dpp v92, v90 row_shr:3 row_mask:0xf bank_mask:0xf
	v_mov_b32_dpp v102, v91 row_shr:1 row_mask:0xf bank_mask:0xf
	v_mov_b32_dpp v95, v91 row_shr:2 row_mask:0xf bank_mask:0xf
	v_mov_b32_dpp v93, v91 row_shr:3 row_mask:0xf bank_mask:0xf
	s_and_saveexec_b64 s[22:23], s[2:3]
	s_cbranch_execz .LBB0_203
;     __device__ __forceinline__ void operator()(const f32x4 (&acc)[2][2][4][2], const Unit& u, int wr, int wc, int fr, int fq, LAS unsigned char* hb) const {
;     ...
;                 for (int bn = 0; bn < 4; ++bn) { const int bj = bn >> 1, n = bn & 1; const int co = bj * HALF + 4 * n;
;                     const unsigned woff = (unsigned)(ch0 + co) * 4u;
;                     const f32x4 w0 = *(const f32x4*)((const char*)cw + woff), w1 = *(const f32x4*)((const char*)cw + woff + XBCW * 4), w2 = *(const f32x4*)((const char*)cw + woff + 2 * XBCW * 4), w3 = *(const f32x4*)((const char*)cw + woff + 3 * XBCW * 4), bs = *(const f32x4*)((const char*)cb + woff);
;                     const LAS unsigned char* hp = hb + (prev * H * NCH + chl + co) * 2;
;                     const u32x2 q1 = *(const LAS u32x2*)(hp + hr1 * NCH * 2), q2 = *(const LAS u32x2*)(hp + hr2 * NCH * 2), q3 = *(const LAS u32x2*)(hp + hr3 * NCH * 2);
;                     const float h1[4] = {__builtin_bit_cast(float, q1.x << 16), __builtin_bit_cast(float, q1.x & 0xffff0000u), __builtin_bit_cast(float, q1.y << 16), __builtin_bit_cast(float, q1.y & 0xffff0000u)};
;                     const float h2[4] = {__builtin_bit_cast(float, q2.x << 16), __builtin_bit_cast(float, q2.x & 0xffff0000u), __builtin_bit_cast(float, q2.y << 16), __builtin_bit_cast(float, q2.y & 0xffff0000u)};
;                     const float h3[4] = {__builtin_bit_cast(float, q3.x << 16), __builtin_bit_cast(float, q3.x & 0xffff0000u), __builtin_bit_cast(float, q3.y << 16), __builtin_bit_cast(float, q3.y & 0xffff0000u)};
;                     const f32x4 gv = acc[ai][bj][m][n];
;                     float o[4];
; #pragma unroll
;                     for (int j = 0; j < 4; ++j) { const float g = gv[j];
;                         float g1 = dpp_row_shr<1>(h1[j], g), g2 = dpp_row_shr<2>(h2[j], g), g3 = dpp_row_shr<3>(h3[j], g);
;                         g1 = p >= 1 ? g1 : 0.f; g2 = p >= 2 ? g2 : 0.f; g3 = p >= 3 ? g3 : 0.f;
;                         const float v = bs[j] + w3[j] * g + w2[j] * g1 + w1[j] * g2 + w0[j] * g3;
;                         o[j] = v * __builtin_amdgcn_rcpf(1.f + ex2(-1.4426950408889634f * v)); }
;                     if (ok) { u32x2 w; w.x = pk2e(o[0], o[1]); w.y = pk2e(o[2], o[3]); *(u32x2*)((char*)O + ooff + co * 2) = w; }
;                     asm volatile("" ::: "memory"); }
	v_cndmask_b32_e64 v109, v108, 0, s[8:9]
	v_cndmask_b32_e64 v108, v107, 0, s[8:9]
	v_cndmask_b32_e64 v107, 0, v106, s[6:7]
	v_cndmask_b32_e64 v106, 0, v105, s[6:7]
	v_cndmask_b32_e64 v105, 0, v104, s[4:5]
	v_cndmask_b32_e64 v104, 0, v103, s[4:5]
	v_cndmask_b32_e64 v95, 0, v95, s[6:7]
	v_cndmask_b32_e64 v94, 0, v94, s[6:7]
	v_cndmask_b32_e64 v93, 0, v93, s[4:5]
	v_cndmask_b32_e64 v92, 0, v92, s[4:5]
	v_pk_fma_f32 v[88:89], v[88:89], v[212:213], v[208:209]
	v_pk_fma_f32 v[90:91], v[90:91], v[214:215], v[210:211]
	v_pk_fma_f32 v[88:89], v[108:109], v[216:217], v[88:89]
	s_nop 0
	v_pk_fma_f32 v[88:89], v[106:107], v[220:221], v[88:89]
	s_nop 0
	v_pk_fma_f32 v[88:89], v[104:105], v[224:225], v[88:89]
	s_nop 0
	v_mul_f32_e32 v103, 0xbfb8aa3b, v89
	v_exp_f32_e32 v103, v103
	s_nop 0
	v_add_f32_e32 v103, 1.0, v103
	v_rcp_f32_e32 v105, v103
	v_mul_f32_e32 v103, 0xbfb8aa3b, v88
	v_exp_f32_e32 v103, v103
	s_nop 0
	v_add_f32_e32 v103, 1.0, v103
	v_rcp_f32_e32 v104, v103
	v_cndmask_b32_e64 v103, v102, 0, s[8:9]
	v_cndmask_b32_e64 v102, v101, 0, s[8:9]
	v_pk_fma_f32 v[90:91], v[102:103], v[218:219], v[90:91]
	v_pk_mul_f32 v[88:89], v[88:89], v[104:105]
	v_pk_fma_f32 v[90:91], v[94:95], v[222:223], v[90:91]
	v_cvt_pk_bf16_f32 v88, v88, v89
	v_pk_fma_f32 v[90:91], v[92:93], v[226:227], v[90:91]
	s_nop 0
	v_mul_f32_e32 v89, 0xbfb8aa3b, v91
	v_exp_f32_e32 v89, v89
	s_nop 0
	v_add_f32_e32 v89, 1.0, v89
	v_rcp_f32_e32 v93, v89
	v_mul_f32_e32 v89, 0xbfb8aa3b, v90
	v_exp_f32_e32 v89, v89
	s_nop 0
	v_add_f32_e32 v89, 1.0, v89
	v_rcp_f32_e32 v92, v89
	s_nop 0
	v_pk_mul_f32 v[90:91], v[90:91], v[92:93]
	s_nop 0
	v_cvt_pk_bf16_f32 v89, v90, v91
	global_store_dwordx2 v[96:97], v[88:89], off offset:8
.LBB0_203:
	s_or_b64 exec, exec, s[22:23]
	ds_read_b64 v[88:89], v98 offset:1280
	ds_read_b64 v[90:91], v99 offset:768
	ds_read_b64 v[106:107], v100 offset:256
	ds_read_b128 v[208:211], v238 offset:4608
	ds_read_b128 v[212:215], v238 offset:3584
	ds_read_b128 v[216:219], v238 offset:2560
	ds_read_b128 v[220:223], v238 offset:1536
	ds_read_b128 v[224:227], v238 offset:512
	s_waitcnt lgkmcnt(0)
	v_lshlrev_b32_e32 v103, 16, v88
	v_and_b32_e32 v104, 0xffff0000, v88
	v_lshlrev_b32_e32 v92, 16, v89
	v_and_b32_e32 v93, 0xffff0000, v89
	v_lshlrev_b32_e32 v101, 16, v90
	v_and_b32_e32 v102, 0xffff0000, v90
	v_lshlrev_b32_e32 v90, 16, v91
	v_and_b32_e32 v91, 0xffff0000, v91
	v_lshlrev_b32_e32 v94, 16, v106
	v_and_b32_e32 v95, 0xffff0000, v106
	v_lshlrev_b32_e32 v88, 16, v107
	v_and_b32_e32 v89, 0xffff0000, v107
	v_mov_b32_dpp v103, v84 row_shr:1 row_mask:0xf bank_mask:0xf
	v_mov_b32_dpp v101, v84 row_shr:2 row_mask:0xf bank_mask:0xf
	v_mov_b32_dpp v94, v84 row_shr:3 row_mask:0xf bank_mask:0xf
	v_mov_b32_dpp v104, v85 row_shr:1 row_mask:0xf bank_mask:0xf
	v_mov_b32_dpp v102, v85 row_shr:2 row_mask:0xf bank_mask:0xf
	v_mov_b32_dpp v95, v85 row_shr:3 row_mask:0xf bank_mask:0xf
	v_mov_b32_dpp v92, v86 row_shr:1 row_mask:0xf bank_mask:0xf
	v_mov_b32_dpp v90, v86 row_shr:2 row_mask:0xf bank_mask:0xf
	v_mov_b32_dpp v88, v86 row_shr:3 row_mask:0xf bank_mask:0xf
	v_mov_b32_dpp v93, v87 row_shr:1 row_mask:0xf bank_mask:0xf
	v_mov_b32_dpp v91, v87 row_shr:2 row_mask:0xf bank_mask:0xf
	v_mov_b32_dpp v89, v87 row_shr:3 row_mask:0xf bank_mask:0xf
	s_and_saveexec_b64 s[22:23], s[2:3]
	s_cbranch_execz .LBB0_205
	v_cndmask_b32_e64 v105, v104, 0, s[8:9]
	v_cndmask_b32_e64 v104, v103, 0, s[8:9]
	v_cndmask_b32_e64 v103, 0, v102, s[6:7]
	v_cndmask_b32_e64 v102, 0, v101, s[6:7]
	v_cndmask_b32_e64 v95, 0, v95, s[4:5]
	v_cndmask_b32_e64 v94, 0, v94, s[4:5]
	v_cndmask_b32_e64 v93, v93, 0, s[8:9]
	v_cndmask_b32_e64 v92, v92, 0, s[8:9]
	v_cndmask_b32_e64 v91, 0, v91, s[6:7]
	v_cndmask_b32_e64 v90, 0, v90, s[6:7]
	v_cndmask_b32_e64 v89, 0, v89, s[4:5]
	v_cndmask_b32_e64 v88, 0, v88, s[4:5]
	v_pk_fma_f32 v[84:85], v[84:85], v[212:213], v[208:209]
	v_pk_fma_f32 v[86:87], v[86:87], v[214:215], v[210:211]
	v_pk_fma_f32 v[84:85], v[104:105], v[216:217], v[84:85]
	v_pk_fma_f32 v[86:87], v[92:93], v[218:219], v[86:87]
	v_pk_fma_f32 v[84:85], v[102:103], v[220:221], v[84:85]
	s_nop 0
	v_pk_fma_f32 v[84:85], v[94:95], v[224:225], v[84:85]
	v_pk_fma_f32 v[86:87], v[90:91], v[222:223], v[86:87]
	v_mul_f32_e32 v94, 0xbfb8aa3b, v85
	v_exp_f32_e32 v94, v94
	v_pk_fma_f32 v[86:87], v[88:89], v[226:227], v[86:87]
	v_add_f32_e32 v94, 1.0, v94
	v_rcp_f32_e32 v95, v94
	v_mul_f32_e32 v94, 0xbfb8aa3b, v84
	v_exp_f32_e32 v94, v94
	s_nop 0
	v_add_f32_e32 v94, 1.0, v94
	v_rcp_f32_e32 v94, v94
	s_nop 0
	v_pk_mul_f32 v[84:85], v[84:85], v[94:95]
	s_nop 0
	v_cvt_pk_bf16_f32 v84, v84, v85
	v_mul_f32_e32 v85, 0xbfb8aa3b, v87
	v_exp_f32_e32 v85, v85
	s_nop 0
	v_add_f32_e32 v85, 1.0, v85
	v_rcp_f32_e32 v89, v85
	v_mul_f32_e32 v85, 0xbfb8aa3b, v86
	v_exp_f32_e32 v85, v85
	s_nop 0
	v_add_f32_e32 v85, 1.0, v85
	v_rcp_f32_e32 v88, v85
	s_nop 0
	v_pk_mul_f32 v[86:87], v[86:87], v[88:89]
	s_nop 0
	v_cvt_pk_bf16_f32 v85, v86, v87
	global_store_dwordx2 v[96:97], v[84:85], off offset:256
;     __device__ __forceinline__ void operator()(const f32x4 (&acc)[2][2][4][2], const Unit& u, int wr, int wc, int fr, int fq, LAS unsigned char* hb) const {
;     ...
;                 const int q = 8 * ai + 4 * wr + m, prev = q > 0 ? q - 1 : 0; const int lr = ai * HALF + wr * 64 + m * 16 + fr, R = R0 + lr;
;                 const int Rc = R < 0 ? 0 : R; const int b = Rc / LL, p = Rc - b * LL;
;                 const bool ok = (lr >= H && R < TT);
;                 const unsigned ooff = ((unsigned)Rc * (unsigned)LDP + (unsigned)(OFF_XBC + ch0)) * 2u;
; #pragma unroll
;                 for (int bn = 0; bn < 4; ++bn) { const int bj = bn >> 1, n = bn & 1; const int co = bj * HALF + 4 * n;
;                     const unsigned woff = (unsigned)(ch0 + co) * 4u;
;                     const f32x4 w0 = *(const f32x4*)((const char*)cw + woff), w1 = *(const f32x4*)((const char*)cw + woff + XBCW * 4), w2 = *(const f32x4*)((const char*)cw + woff + 2 * XBCW * 4), w3 = *(const f32x4*)((const char*)cw + woff + 3 * XBCW * 4), bs = *(const f32x4*)((const char*)cb + woff);
;                     const LAS unsigned char* hp = hb + (prev * H * NCH + chl + co) * 2;
;                     const u32x2 q1 = *(const LAS u32x2*)(hp + hr1 * NCH * 2), q2 = *(const LAS u32x2*)(hp + hr2 * NCH * 2), q3 = *(const LAS u32x2*)(hp + hr3 * NCH * 2);
;                     const float h1[4] = {__builtin_bit_cast(float, q1.x << 16), __builtin_bit_cast(float, q1.x & 0xffff0000u), __builtin_bit_cast(float, q1.y << 16), __builtin_bit_cast(float, q1.y & 0xffff0000u)};
;                     const float h2[4] = {__builtin_bit_cast(float, q2.x << 16), __builtin_bit_cast(float, q2.x & 0xffff0000u), __builtin_bit_cast(float, q2.y << 16), __builtin_bit_cast(float, q2.y & 0xffff0000u)};
;                     const float h3[4] = {__builtin_bit_cast(float, q3.x << 16), __builtin_bit_cast(float, q3.x & 0xffff0000u), __builtin_bit_cast(float, q3.y << 16), __builtin_bit_cast(float, q3.y & 0xffff0000u)};
;                     const f32x4 gv = acc[ai][bj][m][n];
;                     float o[4];
; #pragma unroll
;                     for (int j = 0; j < 4; ++j) { const float g = gv[j];
;                         float g1 = dpp_row_shr<1>(h1[j], g), g2 = dpp_row_shr<2>(h2[j], g), g3 = dpp_row_shr<3>(h3[j], g);
;                         g1 = p >= 1 ? g1 : 0.f; g2 = p >= 2 ? g2 : 0.f; g3 = p >= 3 ? g3 : 0.f;
.LBB0_205:
	s_or_b64 exec, exec, s[22:23]
	ds_read_b64 v[84:85], v98 offset:1288
	ds_read_b64 v[86:87], v99 offset:776
	ds_read_b64 v[98:99], v100 offset:264
	ds_read_b128 v[208:211], v238 offset:4624
	ds_read_b128 v[212:215], v238 offset:3600
	ds_read_b128 v[216:219], v238 offset:2576
	ds_read_b128 v[220:223], v238 offset:1552
	ds_read_b128 v[224:227], v238 offset:528
	s_waitcnt lgkmcnt(0)
	v_lshlrev_b32_e32 v94, 16, v84
	v_and_b32_e32 v95, 0xffff0000, v84
	v_lshlrev_b32_e32 v88, 16, v85
	v_and_b32_e32 v89, 0xffff0000, v85
	v_lshlrev_b32_e32 v92, 16, v86
	v_and_b32_e32 v93, 0xffff0000, v86
	v_lshlrev_b32_e32 v86, 16, v87
	v_and_b32_e32 v87, 0xffff0000, v87
	v_lshlrev_b32_e32 v90, 16, v98
	v_and_b32_e32 v91, 0xffff0000, v98
	v_lshlrev_b32_e32 v84, 16, v99
	v_and_b32_e32 v85, 0xffff0000, v99
	v_mov_b32_dpp v94, v80 row_shr:1 row_mask:0xf bank_mask:0xf
	v_mov_b32_dpp v92, v80 row_shr:2 row_mask:0xf bank_mask:0xf
	v_mov_b32_dpp v90, v80 row_shr:3 row_mask:0xf bank_mask:0xf
	v_mov_b32_dpp v95, v81 row_shr:1 row_mask:0xf bank_mask:0xf
	v_mov_b32_dpp v93, v81 row_shr:2 row_mask:0xf bank_mask:0xf
	v_mov_b32_dpp v91, v81 row_shr:3 row_mask:0xf bank_mask:0xf
	v_mov_b32_dpp v88, v82 row_shr:1 row_mask:0xf bank_mask:0xf
	v_mov_b32_dpp v86, v82 row_shr:2 row_mask:0xf bank_mask:0xf
	v_mov_b32_dpp v84, v82 row_shr:3 row_mask:0xf bank_mask:0xf
	v_mov_b32_dpp v89, v83 row_shr:1 row_mask:0xf bank_mask:0xf
	v_mov_b32_dpp v87, v83 row_shr:2 row_mask:0xf bank_mask:0xf
	v_mov_b32_dpp v85, v83 row_shr:3 row_mask:0xf bank_mask:0xf
	s_and_saveexec_b64 s[22:23], s[2:3]
	s_cbranch_execz .LBB0_207
	v_cndmask_b32_e64 v95, v95, 0, s[8:9]
	s_nop 0
	v_cndmask_b32_e64 v94, v94, 0, s[8:9]
	v_cndmask_b32_e64 v93, 0, v93, s[6:7]
	v_cndmask_b32_e64 v92, 0, v92, s[6:7]
	v_cndmask_b32_e64 v91, 0, v91, s[4:5]
	v_cndmask_b32_e64 v90, 0, v90, s[4:5]
	v_cndmask_b32_e64 v89, v89, 0, s[8:9]
	v_cndmask_b32_e64 v88, v88, 0, s[8:9]
	v_cndmask_b32_e64 v87, 0, v87, s[6:7]
	v_cndmask_b32_e64 v86, 0, v86, s[6:7]
	v_cndmask_b32_e64 v85, 0, v85, s[4:5]
	v_cndmask_b32_e64 v84, 0, v84, s[4:5]
	v_pk_fma_f32 v[80:81], v[80:81], v[212:213], v[208:209]
	v_pk_fma_f32 v[82:83], v[82:83], v[214:215], v[210:211]
	v_pk_fma_f32 v[80:81], v[94:95], v[216:217], v[80:81]
	v_pk_fma_f32 v[82:83], v[88:89], v[218:219], v[82:83]
	v_pk_fma_f32 v[80:81], v[92:93], v[220:221], v[80:81]
	s_nop 0
	v_pk_fma_f32 v[80:81], v[90:91], v[224:225], v[80:81]
	v_pk_fma_f32 v[82:83], v[86:87], v[222:223], v[82:83]
	v_mul_f32_e32 v90, 0xbfb8aa3b, v81
	v_exp_f32_e32 v90, v90
	v_pk_fma_f32 v[82:83], v[84:85], v[226:227], v[82:83]
	v_add_f32_e32 v90, 1.0, v90
	v_rcp_f32_e32 v91, v90
	v_mul_f32_e32 v90, 0xbfb8aa3b, v80
	v_exp_f32_e32 v90, v90
	s_nop 0
	v_add_f32_e32 v90, 1.0, v90
	v_rcp_f32_e32 v90, v90
	s_nop 0
	v_pk_mul_f32 v[80:81], v[80:81], v[90:91]
	s_nop 0
	v_cvt_pk_bf16_f32 v80, v80, v81
	v_mul_f32_e32 v81, 0xbfb8aa3b, v83
	v_exp_f32_e32 v81, v81
	s_nop 0
	v_add_f32_e32 v81, 1.0, v81
	v_rcp_f32_e32 v85, v81
	v_mul_f32_e32 v81, 0xbfb8aa3b, v82
	v_exp_f32_e32 v81, v81
	s_nop 0
	v_add_f32_e32 v81, 1.0, v81
	v_rcp_f32_e32 v84, v81
	s_nop 0
	v_pk_mul_f32 v[82:83], v[82:83], v[84:85]
	s_nop 0
	v_cvt_pk_bf16_f32 v81, v82, v83
	global_store_dwordx2 v[96:97], v[80:81], off offset:264
.LBB0_207:
	s_or_b64 exec, exec, s[22:23]
	v_add_u32_e32 v80, 48, v161
	v_add_u32_e32 v81, s17, v80
	v_max_i32_e32 v82, 0, v81
	v_mul_hi_u32 v83, v82, s56
	v_lshrrev_b32_e32 v83, 11, v83
	v_cmp_lt_i32_e32 vcc, 2, v80
	v_mul_lo_u32 v80, v82, s51
	v_mul_u32_u24_e32 v83, 0x1010, v83
	v_add_lshl_u32 v136, v80, v164, 1
	v_add_u32_e32 v80, s40, v165
	v_sub_u32_e32 v83, v82, v83
	v_cmp_gt_i32_e64 s[4:5], s50, v81
	v_lshl_add_u32 v82, v80, 1, s53
	s_and_b64 s[2:3], vcc, s[4:5]
	v_cmp_eq_u32_e64 s[8:9], 0, v83
	v_cmp_lt_u32_e64 s[6:7], 1, v83
	v_cmp_lt_u32_e64 s[4:5], 2, v83
	v_add_u32_e32 v83, v82, v163
	ds_read_b64 v[80:81], v82 offset:1024
	v_add_u32_e32 v84, v82, v162
	ds_read_b64 v[98:99], v83 offset:512
	ds_read_b64 v[100:101], v84
	ds_read_b128 v[208:211], v238 offset:4096
	ds_read_b128 v[212:215], v238 offset:3072
	ds_read_b128 v[216:219], v238 offset:2048
	ds_read_b128 v[220:223], v238 offset:1024
	ds_read_b128 v[224:227], v238
	v_readlane_b32 s22, v237, 58
	v_readlane_b32 s23, v237, 59
	s_waitcnt lgkmcnt(0)
	v_lshlrev_b32_e32 v95, 16, v80
	v_and_b32_e32 v96, 0xffff0000, v80
	v_lshlrev_b32_e32 v89, 16, v81
	v_and_b32_e32 v90, 0xffff0000, v81
	v_lshlrev_b32_e32 v93, 16, v98
	v_and_b32_e32 v94, 0xffff0000, v98
	v_lshlrev_b32_e32 v87, 16, v99
	v_and_b32_e32 v88, 0xffff0000, v99
	v_lshlrev_b32_e32 v91, 16, v100
	v_and_b32_e32 v92, 0xffff0000, v100
	v_lshlrev_b32_e32 v85, 16, v101
	v_and_b32_e32 v86, 0xffff0000, v101
	v_mov_b32_dpp v95, v76 row_shr:1 row_mask:0xf bank_mask:0xf
	v_mov_b32_dpp v93, v76 row_shr:2 row_mask:0xf bank_mask:0xf
	v_mov_b32_dpp v91, v76 row_shr:3 row_mask:0xf bank_mask:0xf
	v_mov_b32_dpp v96, v77 row_shr:1 row_mask:0xf bank_mask:0xf
	v_mov_b32_dpp v94, v77 row_shr:2 row_mask:0xf bank_mask:0xf
	v_mov_b32_dpp v92, v77 row_shr:3 row_mask:0xf bank_mask:0xf
	v_mov_b32_dpp v89, v78 row_shr:1 row_mask:0xf bank_mask:0xf
	v_mov_b32_dpp v87, v78 row_shr:2 row_mask:0xf bank_mask:0xf
	v_mov_b32_dpp v85, v78 row_shr:3 row_mask:0xf bank_mask:0xf
	v_mov_b32_dpp v90, v79 row_shr:1 row_mask:0xf bank_mask:0xf
	v_mov_b32_dpp v88, v79 row_shr:2 row_mask:0xf bank_mask:0xf
	v_mov_b32_dpp v86, v79 row_shr:3 row_mask:0xf bank_mask:0xf
	v_lshl_add_u64 v[80:81], s[22:23], 0, v[136:137]
	s_and_saveexec_b64 s[22:23], s[2:3]
	s_cbranch_execz .LBB0_209
;     __device__ __forceinline__ void operator()(const f32x4 (&acc)[2][2][4][2], const Unit& u, int wr, int wc, int fr, int fq, LAS unsigned char* hb) const {
;     ...
;                 for (int bn = 0; bn < 4; ++bn) { const int bj = bn >> 1, n = bn & 1; const int co = bj * HALF + 4 * n;
;                     const unsigned woff = (unsigned)(ch0 + co) * 4u;
;                     const f32x4 w0 = *(const f32x4*)((const char*)cw + woff), w1 = *(const f32x4*)((const char*)cw + woff + XBCW * 4), w2 = *(const f32x4*)((const char*)cw + woff + 2 * XBCW * 4), w3 = *(const f32x4*)((const char*)cw + woff + 3 * XBCW * 4), bs = *(const f32x4*)((const char*)cb + woff);
;                     const LAS unsigned char* hp = hb + (prev * H * NCH + chl + co) * 2;
;                     const u32x2 q1 = *(const LAS u32x2*)(hp + hr1 * NCH * 2), q2 = *(const LAS u32x2*)(hp + hr2 * NCH * 2), q3 = *(const LAS u32x2*)(hp + hr3 * NCH * 2);
;                     const float h1[4] = {__builtin_bit_cast(float, q1.x << 16), __builtin_bit_cast(float, q1.x & 0xffff0000u), __builtin_bit_cast(float, q1.y << 16), __builtin_bit_cast(float, q1.y & 0xffff0000u)};
;                     const float h2[4] = {__builtin_bit_cast(float, q2.x << 16), __builtin_bit_cast(float, q2.x & 0xffff0000u), __builtin_bit_cast(float, q2.y << 16), __builtin_bit_cast(float, q2.y & 0xffff0000u)};
;                     const float h3[4] = {__builtin_bit_cast(float, q3.x << 16), __builtin_bit_cast(float, q3.x & 0xffff0000u), __builtin_bit_cast(float, q3.y << 16), __builtin_bit_cast(float, q3.y & 0xffff0000u)};
;                     const f32x4 gv = acc[ai][bj][m][n];
;                     float o[4];
; #pragma unroll
;                     for (int j = 0; j < 4; ++j) { const float g = gv[j];
;                         float g1 = dpp_row_shr<1>(h1[j], g), g2 = dpp_row_shr<2>(h2[j], g), g3 = dpp_row_shr<3>(h3[j], g);
;                         g1 = p >= 1 ? g1 : 0.f; g2 = p >= 2 ? g2 : 0.f; g3 = p >= 3 ? g3 : 0.f;
;                         const float v = bs[j] + w3[j] * g + w2[j] * g1 + w1[j] * g2 + w0[j] * g3;
;                         o[j] = v * __builtin_amdgcn_rcpf(1.f + ex2(-1.4426950408889634f * v)); }
;                     if (ok) { u32x2 w; w.x = pk2e(o[0], o[1]); w.y = pk2e(o[2], o[3]); *(u32x2*)((char*)O + ooff + co * 2) = w; }
;                     asm volatile("" ::: "memory"); }
	v_cndmask_b32_e64 v97, v96, 0, s[8:9]
	s_nop 0
	v_cndmask_b32_e64 v96, v95, 0, s[8:9]
	v_cndmask_b32_e64 v95, 0, v94, s[6:7]
	v_cndmask_b32_e64 v94, 0, v93, s[6:7]
	v_cndmask_b32_e64 v93, 0, v92, s[4:5]
	v_cndmask_b32_e64 v92, 0, v91, s[4:5]
	v_pk_fma_f32 v[76:77], v[76:77], v[212:213], v[208:209]
	v_pk_fma_f32 v[78:79], v[78:79], v[214:215], v[210:211]
	v_pk_fma_f32 v[76:77], v[96:97], v[216:217], v[76:77]
	s_nop 0
	v_pk_fma_f32 v[76:77], v[94:95], v[220:221], v[76:77]
	s_nop 0
	v_pk_fma_f32 v[76:77], v[92:93], v[224:225], v[76:77]
	s_nop 0
	v_mul_f32_e32 v91, 0xbfb8aa3b, v77
	v_exp_f32_e32 v91, v91
	s_nop 0
	v_add_f32_e32 v91, 1.0, v91
	v_rcp_f32_e32 v93, v91
	v_mul_f32_e32 v91, 0xbfb8aa3b, v76
	v_exp_f32_e32 v91, v91
	s_nop 0
	v_add_f32_e32 v91, 1.0, v91
	v_rcp_f32_e32 v92, v91
	v_cndmask_b32_e64 v91, v90, 0, s[8:9]
	v_cndmask_b32_e64 v90, v89, 0, s[8:9]
	v_pk_fma_f32 v[78:79], v[90:91], v[218:219], v[78:79]
	v_cndmask_b32_e64 v89, 0, v88, s[6:7]
	v_cndmask_b32_e64 v88, 0, v87, s[6:7]
	v_pk_fma_f32 v[78:79], v[88:89], v[222:223], v[78:79]
	v_cndmask_b32_e64 v87, 0, v86, s[4:5]
	v_cndmask_b32_e64 v86, 0, v85, s[4:5]
	v_pk_mul_f32 v[76:77], v[76:77], v[92:93]
	v_pk_fma_f32 v[78:79], v[86:87], v[226:227], v[78:79]
	v_cvt_pk_bf16_f32 v76, v76, v77
	v_mul_f32_e32 v77, 0xbfb8aa3b, v79
	v_exp_f32_e32 v77, v77
	s_nop 0
	v_add_f32_e32 v77, 1.0, v77
	v_rcp_f32_e32 v87, v77
	v_mul_f32_e32 v77, 0xbfb8aa3b, v78
	v_exp_f32_e32 v77, v77
	s_nop 0
	v_add_f32_e32 v77, 1.0, v77
	v_rcp_f32_e32 v86, v77
	s_nop 0
	v_pk_mul_f32 v[78:79], v[78:79], v[86:87]
	s_nop 0
	v_cvt_pk_bf16_f32 v77, v78, v79
	global_store_dwordx2 v[80:81], v[76:77], off
.LBB0_209:
	s_or_b64 exec, exec, s[22:23]
	ds_read_b64 v[76:77], v82 offset:1032
	ds_read_b64 v[78:79], v83 offset:520
	ds_read_b64 v[94:95], v84 offset:8
	ds_read_b128 v[208:211], v238 offset:4112
	ds_read_b128 v[212:215], v238 offset:3088
	ds_read_b128 v[216:219], v238 offset:2064
	ds_read_b128 v[220:223], v238 offset:1040
	ds_read_b128 v[224:227], v238 offset:16
	s_waitcnt lgkmcnt(0)
	v_lshlrev_b32_e32 v91, 16, v76
	v_and_b32_e32 v92, 0xffff0000, v76
	v_lshlrev_b32_e32 v85, 16, v77
	v_and_b32_e32 v86, 0xffff0000, v77
	v_lshlrev_b32_e32 v89, 16, v78
	v_and_b32_e32 v90, 0xffff0000, v78
	v_lshlrev_b32_e32 v78, 16, v79
	v_and_b32_e32 v79, 0xffff0000, v79
	v_lshlrev_b32_e32 v87, 16, v94
	v_and_b32_e32 v88, 0xffff0000, v94
	v_lshlrev_b32_e32 v76, 16, v95
	v_and_b32_e32 v77, 0xffff0000, v95
	v_mov_b32_dpp v91, v72 row_shr:1 row_mask:0xf bank_mask:0xf
	v_mov_b32_dpp v89, v72 row_shr:2 row_mask:0xf bank_mask:0xf
	v_mov_b32_dpp v87, v72 row_shr:3 row_mask:0xf bank_mask:0xf
	v_mov_b32_dpp v92, v73 row_shr:1 row_mask:0xf bank_mask:0xf
	v_mov_b32_dpp v90, v73 row_shr:2 row_mask:0xf bank_mask:0xf
	v_mov_b32_dpp v88, v73 row_shr:3 row_mask:0xf bank_mask:0xf
	v_mov_b32_dpp v85, v74 row_shr:1 row_mask:0xf bank_mask:0xf
	v_mov_b32_dpp v78, v74 row_shr:2 row_mask:0xf bank_mask:0xf
	v_mov_b32_dpp v76, v74 row_shr:3 row_mask:0xf bank_mask:0xf
	v_mov_b32_dpp v86, v75 row_shr:1 row_mask:0xf bank_mask:0xf
	v_mov_b32_dpp v79, v75 row_shr:2 row_mask:0xf bank_mask:0xf
	v_mov_b32_dpp v77, v75 row_shr:3 row_mask:0xf bank_mask:0xf
	s_and_saveexec_b64 s[22:23], s[2:3]
	s_cbranch_execz .LBB0_211
	v_cndmask_b32_e64 v93, v92, 0, s[8:9]
	s_nop 0
	v_cndmask_b32_e64 v92, v91, 0, s[8:9]
	v_cndmask_b32_e64 v91, 0, v90, s[6:7]
	v_cndmask_b32_e64 v90, 0, v89, s[6:7]
	v_cndmask_b32_e64 v89, 0, v88, s[4:5]
	v_cndmask_b32_e64 v88, 0, v87, s[4:5]
	v_cndmask_b32_e64 v79, 0, v79, s[6:7]
	v_cndmask_b32_e64 v78, 0, v78, s[6:7]
	v_cndmask_b32_e64 v77, 0, v77, s[4:5]
	v_cndmask_b32_e64 v76, 0, v76, s[4:5]
	v_pk_fma_f32 v[72:73], v[72:73], v[212:213], v[208:209]
	v_pk_fma_f32 v[74:75], v[74:75], v[214:215], v[210:211]
	v_pk_fma_f32 v[72:73], v[92:93], v[216:217], v[72:73]
	s_nop 0
	v_pk_fma_f32 v[72:73], v[90:91], v[220:221], v[72:73]
	s_nop 0
	v_pk_fma_f32 v[72:73], v[88:89], v[224:225], v[72:73]
	s_nop 0
	v_mul_f32_e32 v87, 0xbfb8aa3b, v73
	v_exp_f32_e32 v87, v87
	s_nop 0
	v_add_f32_e32 v87, 1.0, v87
	v_rcp_f32_e32 v89, v87
	v_mul_f32_e32 v87, 0xbfb8aa3b, v72
	v_exp_f32_e32 v87, v87
	s_nop 0
	v_add_f32_e32 v87, 1.0, v87
	v_rcp_f32_e32 v88, v87
	v_cndmask_b32_e64 v87, v86, 0, s[8:9]
	v_cndmask_b32_e64 v86, v85, 0, s[8:9]
	v_pk_fma_f32 v[74:75], v[86:87], v[218:219], v[74:75]
	v_pk_mul_f32 v[72:73], v[72:73], v[88:89]
	v_pk_fma_f32 v[74:75], v[78:79], v[222:223], v[74:75]
	v_cvt_pk_bf16_f32 v72, v72, v73
	v_pk_fma_f32 v[74:75], v[76:77], v[226:227], v[74:75]
	s_nop 0
	v_mul_f32_e32 v73, 0xbfb8aa3b, v75
	v_exp_f32_e32 v73, v73
	s_nop 0
	v_add_f32_e32 v73, 1.0, v73
	v_rcp_f32_e32 v77, v73
	v_mul_f32_e32 v73, 0xbfb8aa3b, v74
	v_exp_f32_e32 v73, v73
	s_nop 0
	v_add_f32_e32 v73, 1.0, v73
	v_rcp_f32_e32 v76, v73
	s_nop 0
	v_pk_mul_f32 v[74:75], v[74:75], v[76:77]
	s_nop 0
	v_cvt_pk_bf16_f32 v73, v74, v75
	global_store_dwordx2 v[80:81], v[72:73], off offset:8
;     __device__ __forceinline__ void operator()(const f32x4 (&acc)[2][2][4][2], const Unit& u, int wr, int wc, int fr, int fq, LAS unsigned char* hb) const {
;     ...
;                 for (int bn = 0; bn < 4; ++bn) { const int bj = bn >> 1, n = bn & 1; const int co = bj * HALF + 4 * n;
;                     const unsigned woff = (unsigned)(ch0 + co) * 4u;
;                     const f32x4 w0 = *(const f32x4*)((const char*)cw + woff), w1 = *(const f32x4*)((const char*)cw + woff + XBCW * 4), w2 = *(const f32x4*)((const char*)cw + woff + 2 * XBCW * 4), w3 = *(const f32x4*)((const char*)cw + woff + 3 * XBCW * 4), bs = *(const f32x4*)((const char*)cb + woff);
;                     const LAS unsigned char* hp = hb + (prev * H * NCH + chl + co) * 2;
;                     const u32x2 q1 = *(const LAS u32x2*)(hp + hr1 * NCH * 2), q2 = *(const LAS u32x2*)(hp + hr2 * NCH * 2), q3 = *(const LAS u32x2*)(hp + hr3 * NCH * 2);
;                     const float h1[4] = {__builtin_bit_cast(float, q1.x << 16), __builtin_bit_cast(float, q1.x & 0xffff0000u), __builtin_bit_cast(float, q1.y << 16), __builtin_bit_cast(float, q1.y & 0xffff0000u)};
;                     const float h2[4] = {__builtin_bit_cast(float, q2.x << 16), __builtin_bit_cast(float, q2.x & 0xffff0000u), __builtin_bit_cast(float, q2.y << 16), __builtin_bit_cast(float, q2.y & 0xffff0000u)};
;                     const float h3[4] = {__builtin_bit_cast(float, q3.x << 16), __builtin_bit_cast(float, q3.x & 0xffff0000u), __builtin_bit_cast(float, q3.y << 16), __builtin_bit_cast(float, q3.y & 0xffff0000u)};
;                     const f32x4 gv = acc[ai][bj][m][n];
;                     float o[4];
; #pragma unroll
;                     for (int j = 0; j < 4; ++j) { const float g = gv[j];
;                         float g1 = dpp_row_shr<1>(h1[j], g), g2 = dpp_row_shr<2>(h2[j], g), g3 = dpp_row_shr<3>(h3[j], g);
;                         g1 = p >= 1 ? g1 : 0.f; g2 = p >= 2 ? g2 : 0.f; g3 = p >= 3 ? g3 : 0.f;
;                         const float v = bs[j] + w3[j] * g + w2[j] * g1 + w1[j] * g2 + w0[j] * g3;
;                         o[j] = v * __builtin_amdgcn_rcpf(1.f + ex2(-1.4426950408889634f * v)); }
;                     if (ok) { u32x2 w; w.x = pk2e(o[0], o[1]); w.y = pk2e(o[2], o[3]); *(u32x2*)((char*)O + ooff + co * 2) = w; }
;                     asm volatile("" ::: "memory"); }
.LBB0_211:
	s_or_b64 exec, exec, s[22:23]
	ds_read_b64 v[72:73], v82 offset:1280
	ds_read_b64 v[74:75], v83 offset:768
	ds_read_b64 v[90:91], v84 offset:256
	ds_read_b128 v[208:211], v238 offset:4608
	ds_read_b128 v[212:215], v238 offset:3584
	ds_read_b128 v[216:219], v238 offset:2560
	ds_read_b128 v[220:223], v238 offset:1536
	ds_read_b128 v[224:227], v238 offset:512
	s_waitcnt lgkmcnt(0)
	v_lshlrev_b32_e32 v87, 16, v72
	v_and_b32_e32 v88, 0xffff0000, v72
	v_lshlrev_b32_e32 v76, 16, v73
	v_and_b32_e32 v77, 0xffff0000, v73
	v_lshlrev_b32_e32 v85, 16, v74
	v_and_b32_e32 v86, 0xffff0000, v74
	v_lshlrev_b32_e32 v74, 16, v75
	v_and_b32_e32 v75, 0xffff0000, v75
	v_lshlrev_b32_e32 v78, 16, v90
	v_and_b32_e32 v79, 0xffff0000, v90
	v_lshlrev_b32_e32 v72, 16, v91
	v_and_b32_e32 v73, 0xffff0000, v91
	v_mov_b32_dpp v87, v68 row_shr:1 row_mask:0xf bank_mask:0xf
	v_mov_b32_dpp v85, v68 row_shr:2 row_mask:0xf bank_mask:0xf
	v_mov_b32_dpp v78, v68 row_shr:3 row_mask:0xf bank_mask:0xf
	v_mov_b32_dpp v88, v69 row_shr:1 row_mask:0xf bank_mask:0xf
	v_mov_b32_dpp v86, v69 row_shr:2 row_mask:0xf bank_mask:0xf
	v_mov_b32_dpp v79, v69 row_shr:3 row_mask:0xf bank_mask:0xf
	v_mov_b32_dpp v76, v70 row_shr:1 row_mask:0xf bank_mask:0xf
	v_mov_b32_dpp v74, v70 row_shr:2 row_mask:0xf bank_mask:0xf
	v_mov_b32_dpp v72, v70 row_shr:3 row_mask:0xf bank_mask:0xf
	v_mov_b32_dpp v77, v71 row_shr:1 row_mask:0xf bank_mask:0xf
	v_mov_b32_dpp v75, v71 row_shr:2 row_mask:0xf bank_mask:0xf
	v_mov_b32_dpp v73, v71 row_shr:3 row_mask:0xf bank_mask:0xf
	s_and_saveexec_b64 s[22:23], s[2:3]
	s_cbranch_execz .LBB0_213
	v_cndmask_b32_e64 v89, v88, 0, s[8:9]
	s_nop 0
	v_cndmask_b32_e64 v88, v87, 0, s[8:9]
	v_cndmask_b32_e64 v87, 0, v86, s[6:7]
	v_cndmask_b32_e64 v86, 0, v85, s[6:7]
	v_cndmask_b32_e64 v79, 0, v79, s[4:5]
	v_cndmask_b32_e64 v78, 0, v78, s[4:5]
	v_cndmask_b32_e64 v77, v77, 0, s[8:9]
	v_cndmask_b32_e64 v76, v76, 0, s[8:9]
	v_cndmask_b32_e64 v75, 0, v75, s[6:7]
	v_cndmask_b32_e64 v74, 0, v74, s[6:7]
	v_cndmask_b32_e64 v73, 0, v73, s[4:5]
	v_cndmask_b32_e64 v72, 0, v72, s[4:5]
	v_pk_fma_f32 v[68:69], v[68:69], v[212:213], v[208:209]
	v_pk_fma_f32 v[70:71], v[70:71], v[214:215], v[210:211]
	v_pk_fma_f32 v[68:69], v[88:89], v[216:217], v[68:69]
	v_pk_fma_f32 v[70:71], v[76:77], v[218:219], v[70:71]
	v_pk_fma_f32 v[68:69], v[86:87], v[220:221], v[68:69]
	s_nop 0
	v_pk_fma_f32 v[68:69], v[78:79], v[224:225], v[68:69]
	v_pk_fma_f32 v[70:71], v[74:75], v[222:223], v[70:71]
	v_mul_f32_e32 v78, 0xbfb8aa3b, v69
	v_exp_f32_e32 v78, v78
	v_pk_fma_f32 v[70:71], v[72:73], v[226:227], v[70:71]
	v_add_f32_e32 v78, 1.0, v78
	v_rcp_f32_e32 v79, v78
	v_mul_f32_e32 v78, 0xbfb8aa3b, v68
	v_exp_f32_e32 v78, v78
	s_nop 0
	v_add_f32_e32 v78, 1.0, v78
	v_rcp_f32_e32 v78, v78
	s_nop 0
	v_pk_mul_f32 v[68:69], v[68:69], v[78:79]
	s_nop 0
	v_cvt_pk_bf16_f32 v68, v68, v69
	v_mul_f32_e32 v69, 0xbfb8aa3b, v71
	v_exp_f32_e32 v69, v69
	s_nop 0
	v_add_f32_e32 v69, 1.0, v69
	v_rcp_f32_e32 v73, v69
	v_mul_f32_e32 v69, 0xbfb8aa3b, v70
	v_exp_f32_e32 v69, v69
	s_nop 0
	v_add_f32_e32 v69, 1.0, v69
	v_rcp_f32_e32 v72, v69
	s_nop 0
	v_pk_mul_f32 v[70:71], v[70:71], v[72:73]
	s_nop 0
	v_cvt_pk_bf16_f32 v69, v70, v71
	global_store_dwordx2 v[80:81], v[68:69], off offset:256
.LBB0_213:
	s_or_b64 exec, exec, s[22:23]
	ds_read_b64 v[68:69], v82 offset:1288
	ds_read_b64 v[70:71], v83 offset:776
	ds_read_b64 v[82:83], v84 offset:264
	ds_read_b128 v[208:211], v238 offset:4624
	ds_read_b128 v[212:215], v238 offset:3600
	ds_read_b128 v[216:219], v238 offset:2576
	ds_read_b128 v[220:223], v238 offset:1552
	ds_read_b128 v[224:227], v238 offset:528
	s_waitcnt lgkmcnt(0)
	v_lshlrev_b32_e32 v78, 16, v68
	v_and_b32_e32 v79, 0xffff0000, v68
	v_lshlrev_b32_e32 v72, 16, v69
	v_and_b32_e32 v73, 0xffff0000, v69
	v_lshlrev_b32_e32 v76, 16, v70
	v_and_b32_e32 v77, 0xffff0000, v70
	v_lshlrev_b32_e32 v70, 16, v71
	v_and_b32_e32 v71, 0xffff0000, v71
	v_lshlrev_b32_e32 v74, 16, v82
	v_and_b32_e32 v75, 0xffff0000, v82
	v_lshlrev_b32_e32 v68, 16, v83
	v_and_b32_e32 v69, 0xffff0000, v83
	v_mov_b32_dpp v78, v64 row_shr:1 row_mask:0xf bank_mask:0xf
	v_mov_b32_dpp v76, v64 row_shr:2 row_mask:0xf bank_mask:0xf
	v_mov_b32_dpp v74, v64 row_shr:3 row_mask:0xf bank_mask:0xf
	v_mov_b32_dpp v79, v65 row_shr:1 row_mask:0xf bank_mask:0xf
	v_mov_b32_dpp v77, v65 row_shr:2 row_mask:0xf bank_mask:0xf
	v_mov_b32_dpp v75, v65 row_shr:3 row_mask:0xf bank_mask:0xf
	v_mov_b32_dpp v72, v66 row_shr:1 row_mask:0xf bank_mask:0xf
	v_mov_b32_dpp v70, v66 row_shr:2 row_mask:0xf bank_mask:0xf
	v_mov_b32_dpp v68, v66 row_shr:3 row_mask:0xf bank_mask:0xf
	v_mov_b32_dpp v73, v67 row_shr:1 row_mask:0xf bank_mask:0xf
	v_mov_b32_dpp v71, v67 row_shr:2 row_mask:0xf bank_mask:0xf
	v_mov_b32_dpp v69, v67 row_shr:3 row_mask:0xf bank_mask:0xf
	s_and_saveexec_b64 s[22:23], s[2:3]
	s_cbranch_execz .LBB0_215
	v_cndmask_b32_e64 v79, v79, 0, s[8:9]
	s_nop 0
	v_cndmask_b32_e64 v78, v78, 0, s[8:9]
	v_cndmask_b32_e64 v77, 0, v77, s[6:7]
	v_cndmask_b32_e64 v76, 0, v76, s[6:7]
	v_cndmask_b32_e64 v75, 0, v75, s[4:5]
	v_cndmask_b32_e64 v74, 0, v74, s[4:5]
	v_cndmask_b32_e64 v73, v73, 0, s[8:9]
	v_cndmask_b32_e64 v72, v72, 0, s[8:9]
	v_cndmask_b32_e64 v71, 0, v71, s[6:7]
	v_cndmask_b32_e64 v70, 0, v70, s[6:7]
	v_cndmask_b32_e64 v69, 0, v69, s[4:5]
	v_cndmask_b32_e64 v68, 0, v68, s[4:5]
	v_pk_fma_f32 v[64:65], v[64:65], v[212:213], v[208:209]
	v_pk_fma_f32 v[66:67], v[66:67], v[214:215], v[210:211]
	v_pk_fma_f32 v[64:65], v[78:79], v[216:217], v[64:65]
	v_pk_fma_f32 v[66:67], v[72:73], v[218:219], v[66:67]
	v_pk_fma_f32 v[64:65], v[76:77], v[220:221], v[64:65]
	s_nop 0
	v_pk_fma_f32 v[64:65], v[74:75], v[224:225], v[64:65]
	v_pk_fma_f32 v[66:67], v[70:71], v[222:223], v[66:67]
	v_mul_f32_e32 v74, 0xbfb8aa3b, v65
	v_exp_f32_e32 v74, v74
	v_pk_fma_f32 v[66:67], v[68:69], v[226:227], v[66:67]
	v_add_f32_e32 v74, 1.0, v74
	v_rcp_f32_e32 v75, v74
	v_mul_f32_e32 v74, 0xbfb8aa3b, v64
	v_exp_f32_e32 v74, v74
	s_nop 0
	v_add_f32_e32 v74, 1.0, v74
	v_rcp_f32_e32 v74, v74
	s_nop 0
	v_pk_mul_f32 v[64:65], v[64:65], v[74:75]
	s_nop 0
	v_cvt_pk_bf16_f32 v64, v64, v65
	v_mul_f32_e32 v65, 0xbfb8aa3b, v67
	v_exp_f32_e32 v65, v65
	s_nop 0
	v_add_f32_e32 v65, 1.0, v65
	v_rcp_f32_e32 v69, v65
	v_mul_f32_e32 v65, 0xbfb8aa3b, v66
	v_exp_f32_e32 v65, v65
	s_nop 0
	v_add_f32_e32 v65, 1.0, v65
	v_rcp_f32_e32 v68, v65
	s_nop 0
	v_pk_mul_f32 v[66:67], v[66:67], v[68:69]
	s_nop 0
	v_cvt_pk_bf16_f32 v65, v66, v67
	global_store_dwordx2 v[80:81], v[64:65], off offset:264
;     __device__ __forceinline__ void operator()(const f32x4 (&acc)[2][2][4][2], const Unit& u, int wr, int wc, int fr, int fq, LAS unsigned char* hb) const {
;     ...
;                 const int q = 8 * ai + 4 * wr + m, prev = q > 0 ? q - 1 : 0; const int lr = ai * HALF + wr * 64 + m * 16 + fr, R = R0 + lr;
;                 const int Rc = R < 0 ? 0 : R; const int b = Rc / LL, p = Rc - b * LL;
;                 const bool ok = (lr >= H && R < TT);
;                 const unsigned ooff = ((unsigned)Rc * (unsigned)LDP + (unsigned)(OFF_XBC + ch0)) * 2u;
; #pragma unroll
;                 for (int bn = 0; bn < 4; ++bn) { const int bj = bn >> 1, n = bn & 1; const int co = bj * HALF + 4 * n;
;                     const unsigned woff = (unsigned)(ch0 + co) * 4u;
;                     const f32x4 w0 = *(const f32x4*)((const char*)cw + woff), w1 = *(const f32x4*)((const char*)cw + woff + XBCW * 4), w2 = *(const f32x4*)((const char*)cw + woff + 2 * XBCW * 4), w3 = *(const f32x4*)((const char*)cw + woff + 3 * XBCW * 4), bs = *(const f32x4*)((const char*)cb + woff);
;                     const LAS unsigned char* hp = hb + (prev * H * NCH + chl + co) * 2;
;                     const u32x2 q1 = *(const LAS u32x2*)(hp + hr1 * NCH * 2), q2 = *(const LAS u32x2*)(hp + hr2 * NCH * 2), q3 = *(const LAS u32x2*)(hp + hr3 * NCH * 2);
;                     const float h1[4] = {__builtin_bit_cast(float, q1.x << 16), __builtin_bit_cast(float, q1.x & 0xffff0000u), __builtin_bit_cast(float, q1.y << 16), __builtin_bit_cast(float, q1.y & 0xffff0000u)};
;                     const float h2[4] = {__builtin_bit_cast(float, q2.x << 16), __builtin_bit_cast(float, q2.x & 0xffff0000u), __builtin_bit_cast(float, q2.y << 16), __builtin_bit_cast(float, q2.y & 0xffff0000u)};
;                     const float h3[4] = {__builtin_bit_cast(float, q3.x << 16), __builtin_bit_cast(float, q3.x & 0xffff0000u), __builtin_bit_cast(float, q3.y << 16), __builtin_bit_cast(float, q3.y & 0xffff0000u)};
;                     const f32x4 gv = acc[ai][bj][m][n];
;                     float o[4];
; #pragma unroll
;                     for (int j = 0; j < 4; ++j) { const float g = gv[j];
;                         float g1 = dpp_row_shr<1>(h1[j], g), g2 = dpp_row_shr<2>(h2[j], g), g3 = dpp_row_shr<3>(h3[j], g);
;                         g1 = p >= 1 ? g1 : 0.f; g2 = p >= 2 ? g2 : 0.f; g3 = p >= 3 ? g3 : 0.f;
.LBB0_215:
	s_or_b64 exec, exec, s[22:23]
	v_add_u32_e32 v64, 0x80, v161
	v_add_u32_e32 v65, s17, v64
	v_max_i32_e32 v66, 0, v65
	v_mul_hi_u32 v67, v66, s56
	v_lshrrev_b32_e32 v67, 11, v67
	v_cmp_lt_i32_e32 vcc, 2, v64
	v_mul_lo_u32 v64, v66, s51
	v_mul_u32_u24_e32 v67, 0x1010, v67
	v_add_lshl_u32 v136, v64, v164, 1
	v_add_u32_e32 v64, s41, v165
	v_sub_u32_e32 v67, v66, v67
	v_cmp_gt_i32_e64 s[4:5], s50, v65
	v_lshl_add_u32 v66, v64, 1, s53
	s_and_b64 s[2:3], vcc, s[4:5]
	v_cmp_eq_u32_e64 s[8:9], 0, v67
	v_cmp_lt_u32_e64 s[6:7], 1, v67
	v_cmp_lt_u32_e64 s[4:5], 2, v67
	v_add_u32_e32 v67, v66, v163
	ds_read_b64 v[64:65], v66 offset:1024
	v_add_u32_e32 v68, v66, v162
	ds_read_b64 v[82:83], v67 offset:512
	ds_read_b64 v[84:85], v68
	ds_read_b128 v[208:211], v238 offset:4096
	ds_read_b128 v[212:215], v238 offset:3072
	ds_read_b128 v[216:219], v238 offset:2048
	ds_read_b128 v[220:223], v238 offset:1024
	ds_read_b128 v[224:227], v238
	v_readlane_b32 s22, v237, 58
	v_readlane_b32 s23, v237, 59
	s_waitcnt lgkmcnt(0)
	v_lshlrev_b32_e32 v79, 16, v64
	v_and_b32_e32 v80, 0xffff0000, v64
	v_lshlrev_b32_e32 v73, 16, v65
	v_and_b32_e32 v74, 0xffff0000, v65
	v_lshlrev_b32_e32 v77, 16, v82
	v_and_b32_e32 v78, 0xffff0000, v82
	v_lshlrev_b32_e32 v71, 16, v83
	v_and_b32_e32 v72, 0xffff0000, v83
	v_lshlrev_b32_e32 v75, 16, v84
	v_and_b32_e32 v76, 0xffff0000, v84
	v_lshlrev_b32_e32 v69, 16, v85
	v_and_b32_e32 v70, 0xffff0000, v85
	v_mov_b32_dpp v79, v60 row_shr:1 row_mask:0xf bank_mask:0xf
	v_mov_b32_dpp v77, v60 row_shr:2 row_mask:0xf bank_mask:0xf
	v_mov_b32_dpp v75, v60 row_shr:3 row_mask:0xf bank_mask:0xf
	v_mov_b32_dpp v80, v61 row_shr:1 row_mask:0xf bank_mask:0xf
	v_mov_b32_dpp v78, v61 row_shr:2 row_mask:0xf bank_mask:0xf
	v_mov_b32_dpp v76, v61 row_shr:3 row_mask:0xf bank_mask:0xf
	v_mov_b32_dpp v73, v62 row_shr:1 row_mask:0xf bank_mask:0xf
	v_mov_b32_dpp v71, v62 row_shr:2 row_mask:0xf bank_mask:0xf
	v_mov_b32_dpp v69, v62 row_shr:3 row_mask:0xf bank_mask:0xf
	v_mov_b32_dpp v74, v63 row_shr:1 row_mask:0xf bank_mask:0xf
	v_mov_b32_dpp v72, v63 row_shr:2 row_mask:0xf bank_mask:0xf
	v_mov_b32_dpp v70, v63 row_shr:3 row_mask:0xf bank_mask:0xf
	v_lshl_add_u64 v[64:65], s[22:23], 0, v[136:137]
	s_and_saveexec_b64 s[22:23], s[2:3]
	s_cbranch_execz .LBB0_217
	v_cndmask_b32_e64 v81, v80, 0, s[8:9]
	s_nop 0
	v_cndmask_b32_e64 v80, v79, 0, s[8:9]
	v_cndmask_b32_e64 v79, 0, v78, s[6:7]
	v_cndmask_b32_e64 v78, 0, v77, s[6:7]
	v_cndmask_b32_e64 v77, 0, v76, s[4:5]
	v_cndmask_b32_e64 v76, 0, v75, s[4:5]
	v_pk_fma_f32 v[60:61], v[60:61], v[212:213], v[208:209]
	v_pk_fma_f32 v[62:63], v[62:63], v[214:215], v[210:211]
	v_pk_fma_f32 v[60:61], v[80:81], v[216:217], v[60:61]
	s_nop 0
	v_pk_fma_f32 v[60:61], v[78:79], v[220:221], v[60:61]
	s_nop 0
	v_pk_fma_f32 v[60:61], v[76:77], v[224:225], v[60:61]
	s_nop 0
	v_mul_f32_e32 v75, 0xbfb8aa3b, v61
	v_exp_f32_e32 v75, v75
	s_nop 0
	v_add_f32_e32 v75, 1.0, v75
	v_rcp_f32_e32 v77, v75
	v_mul_f32_e32 v75, 0xbfb8aa3b, v60
	v_exp_f32_e32 v75, v75
	s_nop 0
	v_add_f32_e32 v75, 1.0, v75
	v_rcp_f32_e32 v76, v75
	v_cndmask_b32_e64 v75, v74, 0, s[8:9]
	v_cndmask_b32_e64 v74, v73, 0, s[8:9]
	v_pk_fma_f32 v[62:63], v[74:75], v[218:219], v[62:63]
	v_cndmask_b32_e64 v73, 0, v72, s[6:7]
	v_cndmask_b32_e64 v72, 0, v71, s[6:7]
	v_pk_fma_f32 v[62:63], v[72:73], v[222:223], v[62:63]
	v_cndmask_b32_e64 v71, 0, v70, s[4:5]
	v_cndmask_b32_e64 v70, 0, v69, s[4:5]
	v_pk_mul_f32 v[60:61], v[60:61], v[76:77]
	v_pk_fma_f32 v[62:63], v[70:71], v[226:227], v[62:63]
	v_cvt_pk_bf16_f32 v60, v60, v61
	v_mul_f32_e32 v61, 0xbfb8aa3b, v63
	v_exp_f32_e32 v61, v61
	s_nop 0
	v_add_f32_e32 v61, 1.0, v61
	v_rcp_f32_e32 v71, v61
	v_mul_f32_e32 v61, 0xbfb8aa3b, v62
	v_exp_f32_e32 v61, v61
	s_nop 0
	v_add_f32_e32 v61, 1.0, v61
	v_rcp_f32_e32 v70, v61
	s_nop 0
	v_pk_mul_f32 v[62:63], v[62:63], v[70:71]
	s_nop 0
	v_cvt_pk_bf16_f32 v61, v62, v63
	global_store_dwordx2 v[64:65], v[60:61], off
.LBB0_217:
	s_or_b64 exec, exec, s[22:23]
	ds_read_b64 v[60:61], v66 offset:1032
	ds_read_b64 v[62:63], v67 offset:520
	ds_read_b64 v[78:79], v68 offset:8
	ds_read_b128 v[208:211], v238 offset:4112
	ds_read_b128 v[212:215], v238 offset:3088
	ds_read_b128 v[216:219], v238 offset:2064
	ds_read_b128 v[220:223], v238 offset:1040
	ds_read_b128 v[224:227], v238 offset:16
	s_waitcnt lgkmcnt(0)
	v_lshlrev_b32_e32 v75, 16, v60
	v_and_b32_e32 v76, 0xffff0000, v60
	v_lshlrev_b32_e32 v69, 16, v61
	v_and_b32_e32 v70, 0xffff0000, v61
	v_lshlrev_b32_e32 v73, 16, v62
	v_and_b32_e32 v74, 0xffff0000, v62
	v_lshlrev_b32_e32 v62, 16, v63
	v_and_b32_e32 v63, 0xffff0000, v63
	v_lshlrev_b32_e32 v71, 16, v78
	v_and_b32_e32 v72, 0xffff0000, v78
	v_lshlrev_b32_e32 v60, 16, v79
	v_and_b32_e32 v61, 0xffff0000, v79
	v_mov_b32_dpp v75, v56 row_shr:1 row_mask:0xf bank_mask:0xf
	v_mov_b32_dpp v73, v56 row_shr:2 row_mask:0xf bank_mask:0xf
	v_mov_b32_dpp v71, v56 row_shr:3 row_mask:0xf bank_mask:0xf
	v_mov_b32_dpp v76, v57 row_shr:1 row_mask:0xf bank_mask:0xf
	v_mov_b32_dpp v74, v57 row_shr:2 row_mask:0xf bank_mask:0xf
	v_mov_b32_dpp v72, v57 row_shr:3 row_mask:0xf bank_mask:0xf
	v_mov_b32_dpp v69, v58 row_shr:1 row_mask:0xf bank_mask:0xf
	v_mov_b32_dpp v62, v58 row_shr:2 row_mask:0xf bank_mask:0xf
	v_mov_b32_dpp v60, v58 row_shr:3 row_mask:0xf bank_mask:0xf
	v_mov_b32_dpp v70, v59 row_shr:1 row_mask:0xf bank_mask:0xf
	v_mov_b32_dpp v63, v59 row_shr:2 row_mask:0xf bank_mask:0xf
	v_mov_b32_dpp v61, v59 row_shr:3 row_mask:0xf bank_mask:0xf
	s_and_saveexec_b64 s[22:23], s[2:3]
	s_cbranch_execz .LBB0_219
;     __device__ __forceinline__ void operator()(const f32x4 (&acc)[2][2][4][2], const Unit& u, int wr, int wc, int fr, int fq, LAS unsigned char* hb) const {
;     ...
;                 for (int bn = 0; bn < 4; ++bn) { const int bj = bn >> 1, n = bn & 1; const int co = bj * HALF + 4 * n;
;                     const unsigned woff = (unsigned)(ch0 + co) * 4u;
;                     const f32x4 w0 = *(const f32x4*)((const char*)cw + woff), w1 = *(const f32x4*)((const char*)cw + woff + XBCW * 4), w2 = *(const f32x4*)((const char*)cw + woff + 2 * XBCW * 4), w3 = *(const f32x4*)((const char*)cw + woff + 3 * XBCW * 4), bs = *(const f32x4*)((const char*)cb + woff);
;                     const LAS unsigned char* hp = hb + (prev * H * NCH + chl + co) * 2;
;                     const u32x2 q1 = *(const LAS u32x2*)(hp + hr1 * NCH * 2), q2 = *(const LAS u32x2*)(hp + hr2 * NCH * 2), q3 = *(const LAS u32x2*)(hp + hr3 * NCH * 2);
;                     const float h1[4] = {__builtin_bit_cast(float, q1.x << 16), __builtin_bit_cast(float, q1.x & 0xffff0000u), __builtin_bit_cast(float, q1.y << 16), __builtin_bit_cast(float, q1.y & 0xffff0000u)};
;                     const float h2[4] = {__builtin_bit_cast(float, q2.x << 16), __builtin_bit_cast(float, q2.x & 0xffff0000u), __builtin_bit_cast(float, q2.y << 16), __builtin_bit_cast(float, q2.y & 0xffff0000u)};
;                     const float h3[4] = {__builtin_bit_cast(float, q3.x << 16), __builtin_bit_cast(float, q3.x & 0xffff0000u), __builtin_bit_cast(float, q3.y << 16), __builtin_bit_cast(float, q3.y & 0xffff0000u)};
;                     const f32x4 gv = acc[ai][bj][m][n];
;                     float o[4];
; #pragma unroll
;                     for (int j = 0; j < 4; ++j) { const float g = gv[j];
;                         float g1 = dpp_row_shr<1>(h1[j], g), g2 = dpp_row_shr<2>(h2[j], g), g3 = dpp_row_shr<3>(h3[j], g);
;                         g1 = p >= 1 ? g1 : 0.f; g2 = p >= 2 ? g2 : 0.f; g3 = p >= 3 ? g3 : 0.f;
;                         const float v = bs[j] + w3[j] * g + w2[j] * g1 + w1[j] * g2 + w0[j] * g3;
;                         o[j] = v * __builtin_amdgcn_rcpf(1.f + ex2(-1.4426950408889634f * v)); }
;                     if (ok) { u32x2 w; w.x = pk2e(o[0], o[1]); w.y = pk2e(o[2], o[3]); *(u32x2*)((char*)O + ooff + co * 2) = w; }
;                     asm volatile("" ::: "memory"); }
	v_cndmask_b32_e64 v77, v76, 0, s[8:9]
	s_nop 0
	v_cndmask_b32_e64 v76, v75, 0, s[8:9]
	v_cndmask_b32_e64 v75, 0, v74, s[6:7]
	v_cndmask_b32_e64 v74, 0, v73, s[6:7]
	v_cndmask_b32_e64 v73, 0, v72, s[4:5]
	v_cndmask_b32_e64 v72, 0, v71, s[4:5]
	v_cndmask_b32_e64 v63, 0, v63, s[6:7]
	v_cndmask_b32_e64 v62, 0, v62, s[6:7]
	v_cndmask_b32_e64 v61, 0, v61, s[4:5]
	v_cndmask_b32_e64 v60, 0, v60, s[4:5]
	v_pk_fma_f32 v[56:57], v[56:57], v[212:213], v[208:209]
	v_pk_fma_f32 v[58:59], v[58:59], v[214:215], v[210:211]
	v_pk_fma_f32 v[56:57], v[76:77], v[216:217], v[56:57]
	s_nop 0
	v_pk_fma_f32 v[56:57], v[74:75], v[220:221], v[56:57]
	s_nop 0
	v_pk_fma_f32 v[56:57], v[72:73], v[224:225], v[56:57]
	s_nop 0
	v_mul_f32_e32 v71, 0xbfb8aa3b, v57
	v_exp_f32_e32 v71, v71
	s_nop 0
	v_add_f32_e32 v71, 1.0, v71
	v_rcp_f32_e32 v73, v71
	v_mul_f32_e32 v71, 0xbfb8aa3b, v56
	v_exp_f32_e32 v71, v71
	s_nop 0
	v_add_f32_e32 v71, 1.0, v71
	v_rcp_f32_e32 v72, v71
	v_cndmask_b32_e64 v71, v70, 0, s[8:9]
	v_cndmask_b32_e64 v70, v69, 0, s[8:9]
	v_pk_fma_f32 v[58:59], v[70:71], v[218:219], v[58:59]
	v_pk_mul_f32 v[56:57], v[56:57], v[72:73]
	v_pk_fma_f32 v[58:59], v[62:63], v[222:223], v[58:59]
	v_cvt_pk_bf16_f32 v56, v56, v57
	v_pk_fma_f32 v[58:59], v[60:61], v[226:227], v[58:59]
	s_nop 0
	v_mul_f32_e32 v57, 0xbfb8aa3b, v59
	v_exp_f32_e32 v57, v57
	s_nop 0
	v_add_f32_e32 v57, 1.0, v57
	v_rcp_f32_e32 v61, v57
	v_mul_f32_e32 v57, 0xbfb8aa3b, v58
	v_exp_f32_e32 v57, v57
	s_nop 0
	v_add_f32_e32 v57, 1.0, v57
	v_rcp_f32_e32 v60, v57
	s_nop 0
	v_pk_mul_f32 v[58:59], v[58:59], v[60:61]
	s_nop 0
	v_cvt_pk_bf16_f32 v57, v58, v59
	global_store_dwordx2 v[64:65], v[56:57], off offset:8
.LBB0_219:
	s_or_b64 exec, exec, s[22:23]
	ds_read_b64 v[56:57], v66 offset:1280
	ds_read_b64 v[58:59], v67 offset:768
	ds_read_b64 v[74:75], v68 offset:256
	ds_read_b128 v[208:211], v238 offset:4608
	ds_read_b128 v[212:215], v238 offset:3584
	ds_read_b128 v[216:219], v238 offset:2560
	ds_read_b128 v[220:223], v238 offset:1536
	ds_read_b128 v[224:227], v238 offset:512
	s_waitcnt lgkmcnt(0)
	v_lshlrev_b32_e32 v71, 16, v56
	v_and_b32_e32 v72, 0xffff0000, v56
	v_lshlrev_b32_e32 v60, 16, v57
	v_and_b32_e32 v61, 0xffff0000, v57
	v_lshlrev_b32_e32 v69, 16, v58
	v_and_b32_e32 v70, 0xffff0000, v58
	v_lshlrev_b32_e32 v58, 16, v59
	v_and_b32_e32 v59, 0xffff0000, v59
	v_lshlrev_b32_e32 v62, 16, v74
	v_and_b32_e32 v63, 0xffff0000, v74
	v_lshlrev_b32_e32 v56, 16, v75
	v_and_b32_e32 v57, 0xffff0000, v75
	v_mov_b32_dpp v71, v52 row_shr:1 row_mask:0xf bank_mask:0xf
	v_mov_b32_dpp v69, v52 row_shr:2 row_mask:0xf bank_mask:0xf
	v_mov_b32_dpp v62, v52 row_shr:3 row_mask:0xf bank_mask:0xf
	v_mov_b32_dpp v72, v53 row_shr:1 row_mask:0xf bank_mask:0xf
	v_mov_b32_dpp v70, v53 row_shr:2 row_mask:0xf bank_mask:0xf
	v_mov_b32_dpp v63, v53 row_shr:3 row_mask:0xf bank_mask:0xf
	v_mov_b32_dpp v60, v54 row_shr:1 row_mask:0xf bank_mask:0xf
	v_mov_b32_dpp v58, v54 row_shr:2 row_mask:0xf bank_mask:0xf
	v_mov_b32_dpp v56, v54 row_shr:3 row_mask:0xf bank_mask:0xf
	v_mov_b32_dpp v61, v55 row_shr:1 row_mask:0xf bank_mask:0xf
	v_mov_b32_dpp v59, v55 row_shr:2 row_mask:0xf bank_mask:0xf
	v_mov_b32_dpp v57, v55 row_shr:3 row_mask:0xf bank_mask:0xf
	s_and_saveexec_b64 s[22:23], s[2:3]
	s_cbranch_execz .LBB0_221
	v_cndmask_b32_e64 v73, v72, 0, s[8:9]
	s_nop 0
	v_cndmask_b32_e64 v72, v71, 0, s[8:9]
	v_cndmask_b32_e64 v71, 0, v70, s[6:7]
	v_cndmask_b32_e64 v70, 0, v69, s[6:7]
	v_cndmask_b32_e64 v63, 0, v63, s[4:5]
	v_cndmask_b32_e64 v62, 0, v62, s[4:5]
	v_cndmask_b32_e64 v61, v61, 0, s[8:9]
	v_cndmask_b32_e64 v60, v60, 0, s[8:9]
	v_cndmask_b32_e64 v59, 0, v59, s[6:7]
	v_cndmask_b32_e64 v58, 0, v58, s[6:7]
	v_cndmask_b32_e64 v57, 0, v57, s[4:5]
	v_cndmask_b32_e64 v56, 0, v56, s[4:5]
	v_pk_fma_f32 v[52:53], v[52:53], v[212:213], v[208:209]
	v_pk_fma_f32 v[54:55], v[54:55], v[214:215], v[210:211]
	v_pk_fma_f32 v[52:53], v[72:73], v[216:217], v[52:53]
	v_pk_fma_f32 v[54:55], v[60:61], v[218:219], v[54:55]
	v_pk_fma_f32 v[52:53], v[70:71], v[220:221], v[52:53]
	s_nop 0
	v_pk_fma_f32 v[52:53], v[62:63], v[224:225], v[52:53]
	v_pk_fma_f32 v[54:55], v[58:59], v[222:223], v[54:55]
	v_mul_f32_e32 v62, 0xbfb8aa3b, v53
	v_exp_f32_e32 v62, v62
	v_pk_fma_f32 v[54:55], v[56:57], v[226:227], v[54:55]
	v_add_f32_e32 v62, 1.0, v62
	v_rcp_f32_e32 v63, v62
	v_mul_f32_e32 v62, 0xbfb8aa3b, v52
	v_exp_f32_e32 v62, v62
	s_nop 0
	v_add_f32_e32 v62, 1.0, v62
	v_rcp_f32_e32 v62, v62
	s_nop 0
	v_pk_mul_f32 v[52:53], v[52:53], v[62:63]
	s_nop 0
	v_cvt_pk_bf16_f32 v52, v52, v53
	v_mul_f32_e32 v53, 0xbfb8aa3b, v55
	v_exp_f32_e32 v53, v53
	s_nop 0
	v_add_f32_e32 v53, 1.0, v53
	v_rcp_f32_e32 v57, v53
	v_mul_f32_e32 v53, 0xbfb8aa3b, v54
	v_exp_f32_e32 v53, v53
	s_nop 0
	v_add_f32_e32 v53, 1.0, v53
	v_rcp_f32_e32 v56, v53
	s_nop 0
	v_pk_mul_f32 v[54:55], v[54:55], v[56:57]
	s_nop 0
	v_cvt_pk_bf16_f32 v53, v54, v55
	global_store_dwordx2 v[64:65], v[52:53], off offset:256
;     __device__ __forceinline__ void operator()(const f32x4 (&acc)[2][2][4][2], const Unit& u, int wr, int wc, int fr, int fq, LAS unsigned char* hb) const {
;     ...
;                 const int q = 8 * ai + 4 * wr + m, prev = q > 0 ? q - 1 : 0; const int lr = ai * HALF + wr * 64 + m * 16 + fr, R = R0 + lr;
;                 const int Rc = R < 0 ? 0 : R; const int b = Rc / LL, p = Rc - b * LL;
;                 const bool ok = (lr >= H && R < TT);
;                 const unsigned ooff = ((unsigned)Rc * (unsigned)LDP + (unsigned)(OFF_XBC + ch0)) * 2u;
; #pragma unroll
;                 for (int bn = 0; bn < 4; ++bn) { const int bj = bn >> 1, n = bn & 1; const int co = bj * HALF + 4 * n;
;                     const unsigned woff = (unsigned)(ch0 + co) * 4u;
;                     const f32x4 w0 = *(const f32x4*)((const char*)cw + woff), w1 = *(const f32x4*)((const char*)cw + woff + XBCW * 4), w2 = *(const f32x4*)((const char*)cw + woff + 2 * XBCW * 4), w3 = *(const f32x4*)((const char*)cw + woff + 3 * XBCW * 4), bs = *(const f32x4*)((const char*)cb + woff);
;                     const LAS unsigned char* hp = hb + (prev * H * NCH + chl + co) * 2;
;                     const u32x2 q1 = *(const LAS u32x2*)(hp + hr1 * NCH * 2), q2 = *(const LAS u32x2*)(hp + hr2 * NCH * 2), q3 = *(const LAS u32x2*)(hp + hr3 * NCH * 2);
;                     const float h1[4] = {__builtin_bit_cast(float, q1.x << 16), __builtin_bit_cast(float, q1.x & 0xffff0000u), __builtin_bit_cast(float, q1.y << 16), __builtin_bit_cast(float, q1.y & 0xffff0000u)};
;                     const float h2[4] = {__builtin_bit_cast(float, q2.x << 16), __builtin_bit_cast(float, q2.x & 0xffff0000u), __builtin_bit_cast(float, q2.y << 16), __builtin_bit_cast(float, q2.y & 0xffff0000u)};
;                     const float h3[4] = {__builtin_bit_cast(float, q3.x << 16), __builtin_bit_cast(float, q3.x & 0xffff0000u), __builtin_bit_cast(float, q3.y << 16), __builtin_bit_cast(float, q3.y & 0xffff0000u)};
;                     const f32x4 gv = acc[ai][bj][m][n];
;                     float o[4];
; #pragma unroll
;                     for (int j = 0; j < 4; ++j) { const float g = gv[j];
;                         float g1 = dpp_row_shr<1>(h1[j], g), g2 = dpp_row_shr<2>(h2[j], g), g3 = dpp_row_shr<3>(h3[j], g);
;                         g1 = p >= 1 ? g1 : 0.f; g2 = p >= 2 ? g2 : 0.f; g3 = p >= 3 ? g3 : 0.f;
.LBB0_221:
	s_or_b64 exec, exec, s[22:23]
	ds_read_b64 v[52:53], v66 offset:1288
	ds_read_b64 v[54:55], v67 offset:776
	ds_read_b64 v[66:67], v68 offset:264
	ds_read_b128 v[208:211], v238 offset:4624
	ds_read_b128 v[212:215], v238 offset:3600
	ds_read_b128 v[216:219], v238 offset:2576
	ds_read_b128 v[220:223], v238 offset:1552
	ds_read_b128 v[224:227], v238 offset:528
	s_waitcnt lgkmcnt(0)
	v_lshlrev_b32_e32 v62, 16, v52
	v_and_b32_e32 v63, 0xffff0000, v52
	v_lshlrev_b32_e32 v56, 16, v53
	v_and_b32_e32 v57, 0xffff0000, v53
	v_lshlrev_b32_e32 v60, 16, v54
	v_and_b32_e32 v61, 0xffff0000, v54
	v_lshlrev_b32_e32 v54, 16, v55
	v_and_b32_e32 v55, 0xffff0000, v55
	v_lshlrev_b32_e32 v58, 16, v66
	v_and_b32_e32 v59, 0xffff0000, v66
	v_lshlrev_b32_e32 v52, 16, v67
	v_and_b32_e32 v53, 0xffff0000, v67
	v_mov_b32_dpp v62, v48 row_shr:1 row_mask:0xf bank_mask:0xf
	v_mov_b32_dpp v60, v48 row_shr:2 row_mask:0xf bank_mask:0xf
	v_mov_b32_dpp v58, v48 row_shr:3 row_mask:0xf bank_mask:0xf
	v_mov_b32_dpp v63, v49 row_shr:1 row_mask:0xf bank_mask:0xf
	v_mov_b32_dpp v61, v49 row_shr:2 row_mask:0xf bank_mask:0xf
	v_mov_b32_dpp v59, v49 row_shr:3 row_mask:0xf bank_mask:0xf
	v_mov_b32_dpp v56, v50 row_shr:1 row_mask:0xf bank_mask:0xf
	v_mov_b32_dpp v54, v50 row_shr:2 row_mask:0xf bank_mask:0xf
	v_mov_b32_dpp v52, v50 row_shr:3 row_mask:0xf bank_mask:0xf
	v_mov_b32_dpp v57, v51 row_shr:1 row_mask:0xf bank_mask:0xf
	v_mov_b32_dpp v55, v51 row_shr:2 row_mask:0xf bank_mask:0xf
	v_mov_b32_dpp v53, v51 row_shr:3 row_mask:0xf bank_mask:0xf
	s_and_saveexec_b64 s[22:23], s[2:3]
	s_cbranch_execz .LBB0_223
	v_cndmask_b32_e64 v63, v63, 0, s[8:9]
	s_nop 0
	v_cndmask_b32_e64 v62, v62, 0, s[8:9]
	v_cndmask_b32_e64 v61, 0, v61, s[6:7]
	v_cndmask_b32_e64 v60, 0, v60, s[6:7]
	v_cndmask_b32_e64 v59, 0, v59, s[4:5]
	v_cndmask_b32_e64 v58, 0, v58, s[4:5]
	v_cndmask_b32_e64 v57, v57, 0, s[8:9]
	v_cndmask_b32_e64 v56, v56, 0, s[8:9]
	v_cndmask_b32_e64 v55, 0, v55, s[6:7]
	v_cndmask_b32_e64 v54, 0, v54, s[6:7]
	v_cndmask_b32_e64 v53, 0, v53, s[4:5]
	v_cndmask_b32_e64 v52, 0, v52, s[4:5]
	v_pk_fma_f32 v[48:49], v[48:49], v[212:213], v[208:209]
	v_pk_fma_f32 v[50:51], v[50:51], v[214:215], v[210:211]
	v_pk_fma_f32 v[48:49], v[62:63], v[216:217], v[48:49]
	v_pk_fma_f32 v[50:51], v[56:57], v[218:219], v[50:51]
	v_pk_fma_f32 v[48:49], v[60:61], v[220:221], v[48:49]
	s_nop 0
	v_pk_fma_f32 v[48:49], v[58:59], v[224:225], v[48:49]
	v_pk_fma_f32 v[50:51], v[54:55], v[222:223], v[50:51]
	v_mul_f32_e32 v58, 0xbfb8aa3b, v49
	v_exp_f32_e32 v58, v58
	v_pk_fma_f32 v[50:51], v[52:53], v[226:227], v[50:51]
	v_add_f32_e32 v58, 1.0, v58
	v_rcp_f32_e32 v59, v58
	v_mul_f32_e32 v58, 0xbfb8aa3b, v48
	v_exp_f32_e32 v58, v58
	s_nop 0
	v_add_f32_e32 v58, 1.0, v58
	v_rcp_f32_e32 v58, v58
	s_nop 0
	v_pk_mul_f32 v[48:49], v[48:49], v[58:59]
	s_nop 0
	v_cvt_pk_bf16_f32 v48, v48, v49
	v_mul_f32_e32 v49, 0xbfb8aa3b, v51
	v_exp_f32_e32 v49, v49
	s_nop 0
	v_add_f32_e32 v49, 1.0, v49
	v_rcp_f32_e32 v53, v49
	v_mul_f32_e32 v49, 0xbfb8aa3b, v50
	v_exp_f32_e32 v49, v49
	s_nop 0
	v_add_f32_e32 v49, 1.0, v49
	v_rcp_f32_e32 v52, v49
	s_nop 0
	v_pk_mul_f32 v[50:51], v[50:51], v[52:53]
	s_nop 0
	v_cvt_pk_bf16_f32 v49, v50, v51
	global_store_dwordx2 v[64:65], v[48:49], off offset:264
.LBB0_223:
	s_or_b64 exec, exec, s[22:23]
	v_add_u32_e32 v48, 0x90, v161
	v_add_u32_e32 v49, s17, v48
	v_max_i32_e32 v50, 0, v49
	v_mul_hi_u32 v51, v50, s56
	v_lshrrev_b32_e32 v51, 11, v51
	v_cmp_lt_i32_e32 vcc, 2, v48
	v_mul_lo_u32 v48, v50, s51
	v_mul_u32_u24_e32 v51, 0x1010, v51
	v_add_lshl_u32 v136, v48, v164, 1
	v_add_u32_e32 v48, s42, v165
	v_sub_u32_e32 v51, v50, v51
	v_cmp_gt_i32_e64 s[4:5], s50, v49
	v_lshl_add_u32 v50, v48, 1, s53
	s_and_b64 s[2:3], vcc, s[4:5]
	v_cmp_eq_u32_e64 s[8:9], 0, v51
	v_cmp_lt_u32_e64 s[6:7], 1, v51
	v_cmp_lt_u32_e64 s[4:5], 2, v51
	v_add_u32_e32 v51, v50, v163
	ds_read_b64 v[48:49], v50 offset:1024
	v_add_u32_e32 v52, v50, v162
	ds_read_b64 v[66:67], v51 offset:512
	ds_read_b64 v[68:69], v52
	ds_read_b128 v[208:211], v238 offset:4096
	ds_read_b128 v[212:215], v238 offset:3072
	ds_read_b128 v[216:219], v238 offset:2048
	ds_read_b128 v[220:223], v238 offset:1024
	ds_read_b128 v[224:227], v238
	v_readlane_b32 s22, v237, 58
	v_readlane_b32 s23, v237, 59
	s_waitcnt lgkmcnt(0)
	v_lshlrev_b32_e32 v63, 16, v48
	v_and_b32_e32 v64, 0xffff0000, v48
	v_lshlrev_b32_e32 v57, 16, v49
	v_and_b32_e32 v58, 0xffff0000, v49
	v_lshlrev_b32_e32 v61, 16, v66
	v_and_b32_e32 v62, 0xffff0000, v66
	v_lshlrev_b32_e32 v55, 16, v67
	v_and_b32_e32 v56, 0xffff0000, v67
	v_lshlrev_b32_e32 v59, 16, v68
	v_and_b32_e32 v60, 0xffff0000, v68
	v_lshlrev_b32_e32 v53, 16, v69
	v_and_b32_e32 v54, 0xffff0000, v69
	v_mov_b32_dpp v63, v44 row_shr:1 row_mask:0xf bank_mask:0xf
	v_mov_b32_dpp v61, v44 row_shr:2 row_mask:0xf bank_mask:0xf
	v_mov_b32_dpp v59, v44 row_shr:3 row_mask:0xf bank_mask:0xf
	v_mov_b32_dpp v64, v45 row_shr:1 row_mask:0xf bank_mask:0xf
	v_mov_b32_dpp v62, v45 row_shr:2 row_mask:0xf bank_mask:0xf
	v_mov_b32_dpp v60, v45 row_shr:3 row_mask:0xf bank_mask:0xf
	v_mov_b32_dpp v57, v46 row_shr:1 row_mask:0xf bank_mask:0xf
	v_mov_b32_dpp v55, v46 row_shr:2 row_mask:0xf bank_mask:0xf
	v_mov_b32_dpp v53, v46 row_shr:3 row_mask:0xf bank_mask:0xf
	v_mov_b32_dpp v58, v47 row_shr:1 row_mask:0xf bank_mask:0xf
	v_mov_b32_dpp v56, v47 row_shr:2 row_mask:0xf bank_mask:0xf
	v_mov_b32_dpp v54, v47 row_shr:3 row_mask:0xf bank_mask:0xf
	v_lshl_add_u64 v[48:49], s[22:23], 0, v[136:137]
	s_and_saveexec_b64 s[22:23], s[2:3]
	s_cbranch_execz .LBB0_225
;     __device__ __forceinline__ void operator()(const f32x4 (&acc)[2][2][4][2], const Unit& u, int wr, int wc, int fr, int fq, LAS unsigned char* hb) const {
;     ...
;                 for (int bn = 0; bn < 4; ++bn) { const int bj = bn >> 1, n = bn & 1; const int co = bj * HALF + 4 * n;
;                     const unsigned woff = (unsigned)(ch0 + co) * 4u;
;                     const f32x4 w0 = *(const f32x4*)((const char*)cw + woff), w1 = *(const f32x4*)((const char*)cw + woff + XBCW * 4), w2 = *(const f32x4*)((const char*)cw + woff + 2 * XBCW * 4), w3 = *(const f32x4*)((const char*)cw + woff + 3 * XBCW * 4), bs = *(const f32x4*)((const char*)cb + woff);
;                     const LAS unsigned char* hp = hb + (prev * H * NCH + chl + co) * 2;
;                     const u32x2 q1 = *(const LAS u32x2*)(hp + hr1 * NCH * 2), q2 = *(const LAS u32x2*)(hp + hr2 * NCH * 2), q3 = *(const LAS u32x2*)(hp + hr3 * NCH * 2);
;                     const float h1[4] = {__builtin_bit_cast(float, q1.x << 16), __builtin_bit_cast(float, q1.x & 0xffff0000u), __builtin_bit_cast(float, q1.y << 16), __builtin_bit_cast(float, q1.y & 0xffff0000u)};
;                     const float h2[4] = {__builtin_bit_cast(float, q2.x << 16), __builtin_bit_cast(float, q2.x & 0xffff0000u), __builtin_bit_cast(float, q2.y << 16), __builtin_bit_cast(float, q2.y & 0xffff0000u)};
;                     const float h3[4] = {__builtin_bit_cast(float, q3.x << 16), __builtin_bit_cast(float, q3.x & 0xffff0000u), __builtin_bit_cast(float, q3.y << 16), __builtin_bit_cast(float, q3.y & 0xffff0000u)};
;                     const f32x4 gv = acc[ai][bj][m][n];
;                     float o[4];
; #pragma unroll
;                     for (int j = 0; j < 4; ++j) { const float g = gv[j];
;                         float g1 = dpp_row_shr<1>(h1[j], g), g2 = dpp_row_shr<2>(h2[j], g), g3 = dpp_row_shr<3>(h3[j], g);
;                         g1 = p >= 1 ? g1 : 0.f; g2 = p >= 2 ? g2 : 0.f; g3 = p >= 3 ? g3 : 0.f;
;                         const float v = bs[j] + w3[j] * g + w2[j] * g1 + w1[j] * g2 + w0[j] * g3;
;                         o[j] = v * __builtin_amdgcn_rcpf(1.f + ex2(-1.4426950408889634f * v)); }
;                     if (ok) { u32x2 w; w.x = pk2e(o[0], o[1]); w.y = pk2e(o[2], o[3]); *(u32x2*)((char*)O + ooff + co * 2) = w; }
;                     asm volatile("" ::: "memory"); }
	v_cndmask_b32_e64 v65, v64, 0, s[8:9]
	s_nop 0
	v_cndmask_b32_e64 v64, v63, 0, s[8:9]
	v_cndmask_b32_e64 v63, 0, v62, s[6:7]
	v_cndmask_b32_e64 v62, 0, v61, s[6:7]
	v_cndmask_b32_e64 v61, 0, v60, s[4:5]
	v_cndmask_b32_e64 v60, 0, v59, s[4:5]
	v_pk_fma_f32 v[44:45], v[44:45], v[212:213], v[208:209]
	v_pk_fma_f32 v[46:47], v[46:47], v[214:215], v[210:211]
	v_pk_fma_f32 v[44:45], v[64:65], v[216:217], v[44:45]
	s_nop 0
	v_pk_fma_f32 v[44:45], v[62:63], v[220:221], v[44:45]
	s_nop 0
	v_pk_fma_f32 v[44:45], v[60:61], v[224:225], v[44:45]
	s_nop 0
	v_mul_f32_e32 v59, 0xbfb8aa3b, v45
	v_exp_f32_e32 v59, v59
	s_nop 0
	v_add_f32_e32 v59, 1.0, v59
	v_rcp_f32_e32 v61, v59
	v_mul_f32_e32 v59, 0xbfb8aa3b, v44
	v_exp_f32_e32 v59, v59
	s_nop 0
	v_add_f32_e32 v59, 1.0, v59
	v_rcp_f32_e32 v60, v59
	v_cndmask_b32_e64 v59, v58, 0, s[8:9]
	v_cndmask_b32_e64 v58, v57, 0, s[8:9]
	v_pk_fma_f32 v[46:47], v[58:59], v[218:219], v[46:47]
	v_cndmask_b32_e64 v57, 0, v56, s[6:7]
	v_cndmask_b32_e64 v56, 0, v55, s[6:7]
	v_pk_fma_f32 v[46:47], v[56:57], v[222:223], v[46:47]
	v_cndmask_b32_e64 v55, 0, v54, s[4:5]
	v_cndmask_b32_e64 v54, 0, v53, s[4:5]
	v_pk_mul_f32 v[44:45], v[44:45], v[60:61]
	v_pk_fma_f32 v[46:47], v[54:55], v[226:227], v[46:47]
	v_cvt_pk_bf16_f32 v44, v44, v45
	v_mul_f32_e32 v45, 0xbfb8aa3b, v47
	v_exp_f32_e32 v45, v45
	s_nop 0
	v_add_f32_e32 v45, 1.0, v45
	v_rcp_f32_e32 v55, v45
	v_mul_f32_e32 v45, 0xbfb8aa3b, v46
	v_exp_f32_e32 v45, v45
	s_nop 0
	v_add_f32_e32 v45, 1.0, v45
	v_rcp_f32_e32 v54, v45
	s_nop 0
	v_pk_mul_f32 v[46:47], v[46:47], v[54:55]
	s_nop 0
	v_cvt_pk_bf16_f32 v45, v46, v47
	global_store_dwordx2 v[48:49], v[44:45], off
.LBB0_225:
	s_or_b64 exec, exec, s[22:23]
	ds_read_b64 v[44:45], v50 offset:1032
	ds_read_b64 v[46:47], v51 offset:520
	ds_read_b64 v[62:63], v52 offset:8
	ds_read_b128 v[208:211], v238 offset:4112
	ds_read_b128 v[212:215], v238 offset:3088
	ds_read_b128 v[216:219], v238 offset:2064
	ds_read_b128 v[220:223], v238 offset:1040
	ds_read_b128 v[224:227], v238 offset:16
	s_waitcnt lgkmcnt(0)
	v_lshlrev_b32_e32 v59, 16, v44
	v_and_b32_e32 v60, 0xffff0000, v44
	v_lshlrev_b32_e32 v53, 16, v45
	v_and_b32_e32 v54, 0xffff0000, v45
	v_lshlrev_b32_e32 v57, 16, v46
	v_and_b32_e32 v58, 0xffff0000, v46
	v_lshlrev_b32_e32 v46, 16, v47
	v_and_b32_e32 v47, 0xffff0000, v47
	v_lshlrev_b32_e32 v55, 16, v62
	v_and_b32_e32 v56, 0xffff0000, v62
	v_lshlrev_b32_e32 v44, 16, v63
	v_and_b32_e32 v45, 0xffff0000, v63
	v_mov_b32_dpp v59, v40 row_shr:1 row_mask:0xf bank_mask:0xf
	v_mov_b32_dpp v57, v40 row_shr:2 row_mask:0xf bank_mask:0xf
	v_mov_b32_dpp v55, v40 row_shr:3 row_mask:0xf bank_mask:0xf
	v_mov_b32_dpp v60, v41 row_shr:1 row_mask:0xf bank_mask:0xf
	v_mov_b32_dpp v58, v41 row_shr:2 row_mask:0xf bank_mask:0xf
	v_mov_b32_dpp v56, v41 row_shr:3 row_mask:0xf bank_mask:0xf
	v_mov_b32_dpp v53, v42 row_shr:1 row_mask:0xf bank_mask:0xf
	v_mov_b32_dpp v46, v42 row_shr:2 row_mask:0xf bank_mask:0xf
	v_mov_b32_dpp v44, v42 row_shr:3 row_mask:0xf bank_mask:0xf
	v_mov_b32_dpp v54, v43 row_shr:1 row_mask:0xf bank_mask:0xf
	v_mov_b32_dpp v47, v43 row_shr:2 row_mask:0xf bank_mask:0xf
	v_mov_b32_dpp v45, v43 row_shr:3 row_mask:0xf bank_mask:0xf
	s_and_saveexec_b64 s[22:23], s[2:3]
	s_cbranch_execz .LBB0_227
	v_cndmask_b32_e64 v61, v60, 0, s[8:9]
	s_nop 0
	v_cndmask_b32_e64 v60, v59, 0, s[8:9]
	v_cndmask_b32_e64 v59, 0, v58, s[6:7]
	v_cndmask_b32_e64 v58, 0, v57, s[6:7]
	v_cndmask_b32_e64 v57, 0, v56, s[4:5]
	v_cndmask_b32_e64 v56, 0, v55, s[4:5]
	v_cndmask_b32_e64 v47, 0, v47, s[6:7]
	v_cndmask_b32_e64 v46, 0, v46, s[6:7]
	v_cndmask_b32_e64 v45, 0, v45, s[4:5]
	v_cndmask_b32_e64 v44, 0, v44, s[4:5]
	v_pk_fma_f32 v[40:41], v[40:41], v[212:213], v[208:209]
	v_pk_fma_f32 v[42:43], v[42:43], v[214:215], v[210:211]
	v_pk_fma_f32 v[40:41], v[60:61], v[216:217], v[40:41]
	s_nop 0
	v_pk_fma_f32 v[40:41], v[58:59], v[220:221], v[40:41]
	s_nop 0
	v_pk_fma_f32 v[40:41], v[56:57], v[224:225], v[40:41]
	s_nop 0
	v_mul_f32_e32 v55, 0xbfb8aa3b, v41
	v_exp_f32_e32 v55, v55
	s_nop 0
	v_add_f32_e32 v55, 1.0, v55
	v_rcp_f32_e32 v57, v55
	v_mul_f32_e32 v55, 0xbfb8aa3b, v40
	v_exp_f32_e32 v55, v55
	s_nop 0
	v_add_f32_e32 v55, 1.0, v55
	v_rcp_f32_e32 v56, v55
	v_cndmask_b32_e64 v55, v54, 0, s[8:9]
	v_cndmask_b32_e64 v54, v53, 0, s[8:9]
	v_pk_fma_f32 v[42:43], v[54:55], v[218:219], v[42:43]
	v_pk_mul_f32 v[40:41], v[40:41], v[56:57]
	v_pk_fma_f32 v[42:43], v[46:47], v[222:223], v[42:43]
	v_cvt_pk_bf16_f32 v40, v40, v41
	v_pk_fma_f32 v[42:43], v[44:45], v[226:227], v[42:43]
	s_nop 0
	v_mul_f32_e32 v41, 0xbfb8aa3b, v43
	v_exp_f32_e32 v41, v41
	s_nop 0
	v_add_f32_e32 v41, 1.0, v41
	v_rcp_f32_e32 v45, v41
	v_mul_f32_e32 v41, 0xbfb8aa3b, v42
	v_exp_f32_e32 v41, v41
	s_nop 0
	v_add_f32_e32 v41, 1.0, v41
	v_rcp_f32_e32 v44, v41
	s_nop 0
	v_pk_mul_f32 v[42:43], v[42:43], v[44:45]
	s_nop 0
	v_cvt_pk_bf16_f32 v41, v42, v43
	global_store_dwordx2 v[48:49], v[40:41], off offset:8
;     __device__ __forceinline__ void operator()(const f32x4 (&acc)[2][2][4][2], const Unit& u, int wr, int wc, int fr, int fq, LAS unsigned char* hb) const {
;     ...
;                 for (int bn = 0; bn < 4; ++bn) { const int bj = bn >> 1, n = bn & 1; const int co = bj * HALF + 4 * n;
;                     const unsigned woff = (unsigned)(ch0 + co) * 4u;
;                     const f32x4 w0 = *(const f32x4*)((const char*)cw + woff), w1 = *(const f32x4*)((const char*)cw + woff + XBCW * 4), w2 = *(const f32x4*)((const char*)cw + woff + 2 * XBCW * 4), w3 = *(const f32x4*)((const char*)cw + woff + 3 * XBCW * 4), bs = *(const f32x4*)((const char*)cb + woff);
;                     const LAS unsigned char* hp = hb + (prev * H * NCH + chl + co) * 2;
;                     const u32x2 q1 = *(const LAS u32x2*)(hp + hr1 * NCH * 2), q2 = *(const LAS u32x2*)(hp + hr2 * NCH * 2), q3 = *(const LAS u32x2*)(hp + hr3 * NCH * 2);
;                     const float h1[4] = {__builtin_bit_cast(float, q1.x << 16), __builtin_bit_cast(float, q1.x & 0xffff0000u), __builtin_bit_cast(float, q1.y << 16), __builtin_bit_cast(float, q1.y & 0xffff0000u)};
;                     const float h2[4] = {__builtin_bit_cast(float, q2.x << 16), __builtin_bit_cast(float, q2.x & 0xffff0000u), __builtin_bit_cast(float, q2.y << 16), __builtin_bit_cast(float, q2.y & 0xffff0000u)};
;                     const float h3[4] = {__builtin_bit_cast(float, q3.x << 16), __builtin_bit_cast(float, q3.x & 0xffff0000u), __builtin_bit_cast(float, q3.y << 16), __builtin_bit_cast(float, q3.y & 0xffff0000u)};
;                     const f32x4 gv = acc[ai][bj][m][n];
;                     float o[4];
; #pragma unroll
;                     for (int j = 0; j < 4; ++j) { const float g = gv[j];
;                         float g1 = dpp_row_shr<1>(h1[j], g), g2 = dpp_row_shr<2>(h2[j], g), g3 = dpp_row_shr<3>(h3[j], g);
;                         g1 = p >= 1 ? g1 : 0.f; g2 = p >= 2 ? g2 : 0.f; g3 = p >= 3 ? g3 : 0.f;
;                         const float v = bs[j] + w3[j] * g + w2[j] * g1 + w1[j] * g2 + w0[j] * g3;
;                         o[j] = v * __builtin_amdgcn_rcpf(1.f + ex2(-1.4426950408889634f * v)); }
;                     if (ok) { u32x2 w; w.x = pk2e(o[0], o[1]); w.y = pk2e(o[2], o[3]); *(u32x2*)((char*)O + ooff + co * 2) = w; }
;                     asm volatile("" ::: "memory"); }
.LBB0_227:
	s_or_b64 exec, exec, s[22:23]
	ds_read_b64 v[40:41], v50 offset:1280
	ds_read_b64 v[42:43], v51 offset:768
	ds_read_b64 v[58:59], v52 offset:256
	ds_read_b128 v[208:211], v238 offset:4608
	ds_read_b128 v[212:215], v238 offset:3584
	ds_read_b128 v[216:219], v238 offset:2560
	ds_read_b128 v[220:223], v238 offset:1536
	ds_read_b128 v[224:227], v238 offset:512
	s_waitcnt lgkmcnt(0)
	v_lshlrev_b32_e32 v55, 16, v40
	v_and_b32_e32 v56, 0xffff0000, v40
	v_lshlrev_b32_e32 v44, 16, v41
	v_and_b32_e32 v45, 0xffff0000, v41
	v_lshlrev_b32_e32 v53, 16, v42
	v_and_b32_e32 v54, 0xffff0000, v42
	v_lshlrev_b32_e32 v42, 16, v43
	v_and_b32_e32 v43, 0xffff0000, v43
	v_lshlrev_b32_e32 v46, 16, v58
	v_and_b32_e32 v47, 0xffff0000, v58
	v_lshlrev_b32_e32 v40, 16, v59
	v_and_b32_e32 v41, 0xffff0000, v59
	v_mov_b32_dpp v55, v36 row_shr:1 row_mask:0xf bank_mask:0xf
	v_mov_b32_dpp v53, v36 row_shr:2 row_mask:0xf bank_mask:0xf
	v_mov_b32_dpp v46, v36 row_shr:3 row_mask:0xf bank_mask:0xf
	v_mov_b32_dpp v56, v37 row_shr:1 row_mask:0xf bank_mask:0xf
	v_mov_b32_dpp v54, v37 row_shr:2 row_mask:0xf bank_mask:0xf
	v_mov_b32_dpp v47, v37 row_shr:3 row_mask:0xf bank_mask:0xf
	v_mov_b32_dpp v44, v38 row_shr:1 row_mask:0xf bank_mask:0xf
	v_mov_b32_dpp v42, v38 row_shr:2 row_mask:0xf bank_mask:0xf
	v_mov_b32_dpp v40, v38 row_shr:3 row_mask:0xf bank_mask:0xf
	v_mov_b32_dpp v45, v39 row_shr:1 row_mask:0xf bank_mask:0xf
	v_mov_b32_dpp v43, v39 row_shr:2 row_mask:0xf bank_mask:0xf
	v_mov_b32_dpp v41, v39 row_shr:3 row_mask:0xf bank_mask:0xf
	s_and_saveexec_b64 s[22:23], s[2:3]
	s_cbranch_execz .LBB0_229
	v_cndmask_b32_e64 v57, v56, 0, s[8:9]
	s_nop 0
	v_cndmask_b32_e64 v56, v55, 0, s[8:9]
	v_cndmask_b32_e64 v55, 0, v54, s[6:7]
	v_cndmask_b32_e64 v54, 0, v53, s[6:7]
	v_cndmask_b32_e64 v47, 0, v47, s[4:5]
	v_cndmask_b32_e64 v46, 0, v46, s[4:5]
	v_cndmask_b32_e64 v45, v45, 0, s[8:9]
	v_cndmask_b32_e64 v44, v44, 0, s[8:9]
	v_cndmask_b32_e64 v43, 0, v43, s[6:7]
	v_cndmask_b32_e64 v42, 0, v42, s[6:7]
	v_cndmask_b32_e64 v41, 0, v41, s[4:5]
	v_cndmask_b32_e64 v40, 0, v40, s[4:5]
	v_pk_fma_f32 v[36:37], v[36:37], v[212:213], v[208:209]
	v_pk_fma_f32 v[38:39], v[38:39], v[214:215], v[210:211]
	v_pk_fma_f32 v[36:37], v[56:57], v[216:217], v[36:37]
	v_pk_fma_f32 v[38:39], v[44:45], v[218:219], v[38:39]
	v_pk_fma_f32 v[36:37], v[54:55], v[220:221], v[36:37]
	s_nop 0
	v_pk_fma_f32 v[36:37], v[46:47], v[224:225], v[36:37]
	v_pk_fma_f32 v[38:39], v[42:43], v[222:223], v[38:39]
	v_mul_f32_e32 v46, 0xbfb8aa3b, v37
	v_exp_f32_e32 v46, v46
	v_pk_fma_f32 v[38:39], v[40:41], v[226:227], v[38:39]
	v_add_f32_e32 v46, 1.0, v46
	v_rcp_f32_e32 v47, v46
	v_mul_f32_e32 v46, 0xbfb8aa3b, v36
	v_exp_f32_e32 v46, v46
	s_nop 0
	v_add_f32_e32 v46, 1.0, v46
	v_rcp_f32_e32 v46, v46
	s_nop 0
	v_pk_mul_f32 v[36:37], v[36:37], v[46:47]
	s_nop 0
	v_cvt_pk_bf16_f32 v36, v36, v37
	v_mul_f32_e32 v37, 0xbfb8aa3b, v39
	v_exp_f32_e32 v37, v37
	s_nop 0
	v_add_f32_e32 v37, 1.0, v37
	v_rcp_f32_e32 v41, v37
	v_mul_f32_e32 v37, 0xbfb8aa3b, v38
	v_exp_f32_e32 v37, v37
	s_nop 0
	v_add_f32_e32 v37, 1.0, v37
	v_rcp_f32_e32 v40, v37
	s_nop 0
	v_pk_mul_f32 v[38:39], v[38:39], v[40:41]
	s_nop 0
	v_cvt_pk_bf16_f32 v37, v38, v39
	global_store_dwordx2 v[48:49], v[36:37], off offset:256
.LBB0_229:
	s_or_b64 exec, exec, s[22:23]
	ds_read_b64 v[36:37], v50 offset:1288
	ds_read_b64 v[38:39], v51 offset:776
	ds_read_b64 v[50:51], v52 offset:264
	ds_read_b128 v[208:211], v238 offset:4624
	ds_read_b128 v[212:215], v238 offset:3600
	ds_read_b128 v[216:219], v238 offset:2576
	ds_read_b128 v[220:223], v238 offset:1552
	ds_read_b128 v[224:227], v238 offset:528
	s_waitcnt lgkmcnt(0)
	v_lshlrev_b32_e32 v46, 16, v36
	v_and_b32_e32 v47, 0xffff0000, v36
	v_lshlrev_b32_e32 v40, 16, v37
	v_and_b32_e32 v41, 0xffff0000, v37
	v_lshlrev_b32_e32 v44, 16, v38
	v_and_b32_e32 v45, 0xffff0000, v38
	v_lshlrev_b32_e32 v38, 16, v39
	v_and_b32_e32 v39, 0xffff0000, v39
	v_lshlrev_b32_e32 v42, 16, v50
	v_and_b32_e32 v43, 0xffff0000, v50
	v_lshlrev_b32_e32 v36, 16, v51
	v_and_b32_e32 v37, 0xffff0000, v51
	v_mov_b32_dpp v46, v32 row_shr:1 row_mask:0xf bank_mask:0xf
	v_mov_b32_dpp v44, v32 row_shr:2 row_mask:0xf bank_mask:0xf
	v_mov_b32_dpp v42, v32 row_shr:3 row_mask:0xf bank_mask:0xf
	v_mov_b32_dpp v47, v33 row_shr:1 row_mask:0xf bank_mask:0xf
	v_mov_b32_dpp v45, v33 row_shr:2 row_mask:0xf bank_mask:0xf
	v_mov_b32_dpp v43, v33 row_shr:3 row_mask:0xf bank_mask:0xf
	v_mov_b32_dpp v40, v34 row_shr:1 row_mask:0xf bank_mask:0xf
	v_mov_b32_dpp v38, v34 row_shr:2 row_mask:0xf bank_mask:0xf
	v_mov_b32_dpp v36, v34 row_shr:3 row_mask:0xf bank_mask:0xf
	v_mov_b32_dpp v41, v35 row_shr:1 row_mask:0xf bank_mask:0xf
	v_mov_b32_dpp v39, v35 row_shr:2 row_mask:0xf bank_mask:0xf
	v_mov_b32_dpp v37, v35 row_shr:3 row_mask:0xf bank_mask:0xf
	s_and_saveexec_b64 s[22:23], s[2:3]
	s_cbranch_execz .LBB0_231
	v_cndmask_b32_e64 v47, v47, 0, s[8:9]
	s_nop 0
	v_cndmask_b32_e64 v46, v46, 0, s[8:9]
	v_cndmask_b32_e64 v45, 0, v45, s[6:7]
	v_cndmask_b32_e64 v44, 0, v44, s[6:7]
	v_cndmask_b32_e64 v43, 0, v43, s[4:5]
	v_cndmask_b32_e64 v42, 0, v42, s[4:5]
	v_cndmask_b32_e64 v41, v41, 0, s[8:9]
	v_cndmask_b32_e64 v40, v40, 0, s[8:9]
	v_cndmask_b32_e64 v39, 0, v39, s[6:7]
	v_cndmask_b32_e64 v38, 0, v38, s[6:7]
	v_cndmask_b32_e64 v37, 0, v37, s[4:5]
	v_cndmask_b32_e64 v36, 0, v36, s[4:5]
	v_pk_fma_f32 v[32:33], v[32:33], v[212:213], v[208:209]
	v_pk_fma_f32 v[34:35], v[34:35], v[214:215], v[210:211]
	v_pk_fma_f32 v[32:33], v[46:47], v[216:217], v[32:33]
	v_pk_fma_f32 v[34:35], v[40:41], v[218:219], v[34:35]
	v_pk_fma_f32 v[32:33], v[44:45], v[220:221], v[32:33]
	s_nop 0
	v_pk_fma_f32 v[32:33], v[42:43], v[224:225], v[32:33]
	v_pk_fma_f32 v[34:35], v[38:39], v[222:223], v[34:35]
	v_mul_f32_e32 v42, 0xbfb8aa3b, v33
	v_exp_f32_e32 v42, v42
	v_pk_fma_f32 v[34:35], v[36:37], v[226:227], v[34:35]
	v_add_f32_e32 v42, 1.0, v42
	v_rcp_f32_e32 v43, v42
	v_mul_f32_e32 v42, 0xbfb8aa3b, v32
	v_exp_f32_e32 v42, v42
	s_nop 0
	v_add_f32_e32 v42, 1.0, v42
	v_rcp_f32_e32 v42, v42
	s_nop 0
	v_pk_mul_f32 v[32:33], v[32:33], v[42:43]
	s_nop 0
	v_cvt_pk_bf16_f32 v32, v32, v33
	v_mul_f32_e32 v33, 0xbfb8aa3b, v35
	v_exp_f32_e32 v33, v33
	s_nop 0
	v_add_f32_e32 v33, 1.0, v33
	v_rcp_f32_e32 v37, v33
	v_mul_f32_e32 v33, 0xbfb8aa3b, v34
	v_exp_f32_e32 v33, v33
	s_nop 0
	v_add_f32_e32 v33, 1.0, v33
	v_rcp_f32_e32 v36, v33
	s_nop 0
	v_pk_mul_f32 v[34:35], v[34:35], v[36:37]
	s_nop 0
	v_cvt_pk_bf16_f32 v33, v34, v35
	global_store_dwordx2 v[48:49], v[32:33], off offset:264
;     __device__ __forceinline__ void operator()(const f32x4 (&acc)[2][2][4][2], const Unit& u, int wr, int wc, int fr, int fq, LAS unsigned char* hb) const {
;     ...
;                 const int q = 8 * ai + 4 * wr + m, prev = q > 0 ? q - 1 : 0; const int lr = ai * HALF + wr * 64 + m * 16 + fr, R = R0 + lr;
;                 const int Rc = R < 0 ? 0 : R; const int b = Rc / LL, p = Rc - b * LL;
;                 const bool ok = (lr >= H && R < TT);
;                 const unsigned ooff = ((unsigned)Rc * (unsigned)LDP + (unsigned)(OFF_XBC + ch0)) * 2u;
; #pragma unroll
;                 for (int bn = 0; bn < 4; ++bn) { const int bj = bn >> 1, n = bn & 1; const int co = bj * HALF + 4 * n;
;                     const unsigned woff = (unsigned)(ch0 + co) * 4u;
;                     const f32x4 w0 = *(const f32x4*)((const char*)cw + woff), w1 = *(const f32x4*)((const char*)cw + woff + XBCW * 4), w2 = *(const f32x4*)((const char*)cw + woff + 2 * XBCW * 4), w3 = *(const f32x4*)((const char*)cw + woff + 3 * XBCW * 4), bs = *(const f32x4*)((const char*)cb + woff);
;                     const LAS unsigned char* hp = hb + (prev * H * NCH + chl + co) * 2;
;                     const u32x2 q1 = *(const LAS u32x2*)(hp + hr1 * NCH * 2), q2 = *(const LAS u32x2*)(hp + hr2 * NCH * 2), q3 = *(const LAS u32x2*)(hp + hr3 * NCH * 2);
;                     const float h1[4] = {__builtin_bit_cast(float, q1.x << 16), __builtin_bit_cast(float, q1.x & 0xffff0000u), __builtin_bit_cast(float, q1.y << 16), __builtin_bit_cast(float, q1.y & 0xffff0000u)};
;                     const float h2[4] = {__builtin_bit_cast(float, q2.x << 16), __builtin_bit_cast(float, q2.x & 0xffff0000u), __builtin_bit_cast(float, q2.y << 16), __builtin_bit_cast(float, q2.y & 0xffff0000u)};
;                     const float h3[4] = {__builtin_bit_cast(float, q3.x << 16), __builtin_bit_cast(float, q3.x & 0xffff0000u), __builtin_bit_cast(float, q3.y << 16), __builtin_bit_cast(float, q3.y & 0xffff0000u)};
;                     const f32x4 gv = acc[ai][bj][m][n];
;                     float o[4];
; #pragma unroll
;                     for (int j = 0; j < 4; ++j) { const float g = gv[j];
;                         float g1 = dpp_row_shr<1>(h1[j], g), g2 = dpp_row_shr<2>(h2[j], g), g3 = dpp_row_shr<3>(h3[j], g);
;                         g1 = p >= 1 ? g1 : 0.f; g2 = p >= 2 ? g2 : 0.f; g3 = p >= 3 ? g3 : 0.f;
.LBB0_231:
	s_or_b64 exec, exec, s[22:23]
	v_add_u32_e32 v32, 0xa0, v161
	v_add_u32_e32 v33, s17, v32
	v_max_i32_e32 v34, 0, v33
	v_mul_hi_u32 v35, v34, s56
	v_lshrrev_b32_e32 v35, 11, v35
	v_cmp_lt_i32_e32 vcc, 2, v32
	v_mul_lo_u32 v32, v34, s51
	v_mul_u32_u24_e32 v35, 0x1010, v35
	v_add_lshl_u32 v136, v32, v164, 1
	v_add_u32_e32 v32, s43, v165
	v_sub_u32_e32 v35, v34, v35
	v_cmp_gt_i32_e64 s[4:5], s50, v33
	v_lshl_add_u32 v34, v32, 1, s53
	s_and_b64 s[2:3], vcc, s[4:5]
	v_cmp_eq_u32_e64 s[8:9], 0, v35
	v_cmp_lt_u32_e64 s[6:7], 1, v35
	v_cmp_lt_u32_e64 s[4:5], 2, v35
	v_add_u32_e32 v35, v34, v163
	ds_read_b64 v[32:33], v34 offset:1024
	v_add_u32_e32 v36, v34, v162
	ds_read_b64 v[50:51], v35 offset:512
	ds_read_b64 v[52:53], v36
	ds_read_b128 v[208:211], v238 offset:4096
	ds_read_b128 v[212:215], v238 offset:3072
	ds_read_b128 v[216:219], v238 offset:2048
	ds_read_b128 v[220:223], v238 offset:1024
	ds_read_b128 v[224:227], v238
	v_readlane_b32 s22, v237, 58
	v_readlane_b32 s23, v237, 59
	s_waitcnt lgkmcnt(0)
	v_lshlrev_b32_e32 v47, 16, v32
	v_and_b32_e32 v48, 0xffff0000, v32
	v_lshlrev_b32_e32 v41, 16, v33
	v_and_b32_e32 v42, 0xffff0000, v33
	v_lshlrev_b32_e32 v45, 16, v50
	v_and_b32_e32 v46, 0xffff0000, v50
	v_lshlrev_b32_e32 v39, 16, v51
	v_and_b32_e32 v40, 0xffff0000, v51
	v_lshlrev_b32_e32 v43, 16, v52
	v_and_b32_e32 v44, 0xffff0000, v52
	v_lshlrev_b32_e32 v37, 16, v53
	v_and_b32_e32 v38, 0xffff0000, v53
	v_mov_b32_dpp v47, v28 row_shr:1 row_mask:0xf bank_mask:0xf
	v_mov_b32_dpp v45, v28 row_shr:2 row_mask:0xf bank_mask:0xf
	v_mov_b32_dpp v43, v28 row_shr:3 row_mask:0xf bank_mask:0xf
	v_mov_b32_dpp v48, v29 row_shr:1 row_mask:0xf bank_mask:0xf
	v_mov_b32_dpp v46, v29 row_shr:2 row_mask:0xf bank_mask:0xf
	v_mov_b32_dpp v44, v29 row_shr:3 row_mask:0xf bank_mask:0xf
	v_mov_b32_dpp v41, v30 row_shr:1 row_mask:0xf bank_mask:0xf
	v_mov_b32_dpp v39, v30 row_shr:2 row_mask:0xf bank_mask:0xf
	v_mov_b32_dpp v37, v30 row_shr:3 row_mask:0xf bank_mask:0xf
	v_mov_b32_dpp v42, v31 row_shr:1 row_mask:0xf bank_mask:0xf
	v_mov_b32_dpp v40, v31 row_shr:2 row_mask:0xf bank_mask:0xf
	v_mov_b32_dpp v38, v31 row_shr:3 row_mask:0xf bank_mask:0xf
	v_lshl_add_u64 v[32:33], s[22:23], 0, v[136:137]
	s_and_saveexec_b64 s[22:23], s[2:3]
	s_cbranch_execz .LBB0_233
	v_cndmask_b32_e64 v49, v48, 0, s[8:9]
	s_nop 0
	v_cndmask_b32_e64 v48, v47, 0, s[8:9]
	v_cndmask_b32_e64 v47, 0, v46, s[6:7]
	v_cndmask_b32_e64 v46, 0, v45, s[6:7]
	v_cndmask_b32_e64 v45, 0, v44, s[4:5]
	v_cndmask_b32_e64 v44, 0, v43, s[4:5]
	v_pk_fma_f32 v[28:29], v[28:29], v[212:213], v[208:209]
	v_pk_fma_f32 v[30:31], v[30:31], v[214:215], v[210:211]
	v_pk_fma_f32 v[28:29], v[48:49], v[216:217], v[28:29]
	s_nop 0
	v_pk_fma_f32 v[28:29], v[46:47], v[220:221], v[28:29]
	s_nop 0
	v_pk_fma_f32 v[28:29], v[44:45], v[224:225], v[28:29]
	s_nop 0
	v_mul_f32_e32 v43, 0xbfb8aa3b, v29
	v_exp_f32_e32 v43, v43
	s_nop 0
	v_add_f32_e32 v43, 1.0, v43
	v_rcp_f32_e32 v45, v43
	v_mul_f32_e32 v43, 0xbfb8aa3b, v28
	v_exp_f32_e32 v43, v43
	s_nop 0
	v_add_f32_e32 v43, 1.0, v43
	v_rcp_f32_e32 v44, v43
	v_cndmask_b32_e64 v43, v42, 0, s[8:9]
	v_cndmask_b32_e64 v42, v41, 0, s[8:9]
	v_pk_fma_f32 v[30:31], v[42:43], v[218:219], v[30:31]
	v_cndmask_b32_e64 v41, 0, v40, s[6:7]
	v_cndmask_b32_e64 v40, 0, v39, s[6:7]
	v_pk_fma_f32 v[30:31], v[40:41], v[222:223], v[30:31]
	v_cndmask_b32_e64 v39, 0, v38, s[4:5]
	v_cndmask_b32_e64 v38, 0, v37, s[4:5]
	v_pk_mul_f32 v[28:29], v[28:29], v[44:45]
	v_pk_fma_f32 v[30:31], v[38:39], v[226:227], v[30:31]
	v_cvt_pk_bf16_f32 v28, v28, v29
	v_mul_f32_e32 v29, 0xbfb8aa3b, v31
	v_exp_f32_e32 v29, v29
	s_nop 0
	v_add_f32_e32 v29, 1.0, v29
	v_rcp_f32_e32 v39, v29
	v_mul_f32_e32 v29, 0xbfb8aa3b, v30
	v_exp_f32_e32 v29, v29
	s_nop 0
	v_add_f32_e32 v29, 1.0, v29
	v_rcp_f32_e32 v38, v29
	s_nop 0
	v_pk_mul_f32 v[30:31], v[30:31], v[38:39]
	s_nop 0
	v_cvt_pk_bf16_f32 v29, v30, v31
	global_store_dwordx2 v[32:33], v[28:29], off
.LBB0_233:
	s_or_b64 exec, exec, s[22:23]
	ds_read_b64 v[28:29], v34 offset:1032
	ds_read_b64 v[30:31], v35 offset:520
	ds_read_b64 v[46:47], v36 offset:8
	ds_read_b128 v[208:211], v238 offset:4112
	ds_read_b128 v[212:215], v238 offset:3088
	ds_read_b128 v[216:219], v238 offset:2064
	ds_read_b128 v[220:223], v238 offset:1040
	ds_read_b128 v[224:227], v238 offset:16
	s_waitcnt lgkmcnt(0)
	v_lshlrev_b32_e32 v43, 16, v28
	v_and_b32_e32 v44, 0xffff0000, v28
	v_lshlrev_b32_e32 v37, 16, v29
	v_and_b32_e32 v38, 0xffff0000, v29
	v_lshlrev_b32_e32 v41, 16, v30
	v_and_b32_e32 v42, 0xffff0000, v30
	v_lshlrev_b32_e32 v30, 16, v31
	v_and_b32_e32 v31, 0xffff0000, v31
	v_lshlrev_b32_e32 v39, 16, v46
	v_and_b32_e32 v40, 0xffff0000, v46
	v_lshlrev_b32_e32 v28, 16, v47
	v_and_b32_e32 v29, 0xffff0000, v47
	v_mov_b32_dpp v43, v24 row_shr:1 row_mask:0xf bank_mask:0xf
	v_mov_b32_dpp v41, v24 row_shr:2 row_mask:0xf bank_mask:0xf
	v_mov_b32_dpp v39, v24 row_shr:3 row_mask:0xf bank_mask:0xf
	v_mov_b32_dpp v44, v25 row_shr:1 row_mask:0xf bank_mask:0xf
	v_mov_b32_dpp v42, v25 row_shr:2 row_mask:0xf bank_mask:0xf
	v_mov_b32_dpp v40, v25 row_shr:3 row_mask:0xf bank_mask:0xf
	v_mov_b32_dpp v37, v26 row_shr:1 row_mask:0xf bank_mask:0xf
	v_mov_b32_dpp v30, v26 row_shr:2 row_mask:0xf bank_mask:0xf
	v_mov_b32_dpp v28, v26 row_shr:3 row_mask:0xf bank_mask:0xf
	v_mov_b32_dpp v38, v27 row_shr:1 row_mask:0xf bank_mask:0xf
	v_mov_b32_dpp v31, v27 row_shr:2 row_mask:0xf bank_mask:0xf
	v_mov_b32_dpp v29, v27 row_shr:3 row_mask:0xf bank_mask:0xf
	s_and_saveexec_b64 s[22:23], s[2:3]
	s_cbranch_execz .LBB0_235
;     __device__ __forceinline__ void operator()(const f32x4 (&acc)[2][2][4][2], const Unit& u, int wr, int wc, int fr, int fq, LAS unsigned char* hb) const {
;     ...
;                 for (int bn = 0; bn < 4; ++bn) { const int bj = bn >> 1, n = bn & 1; const int co = bj * HALF + 4 * n;
;                     const unsigned woff = (unsigned)(ch0 + co) * 4u;
;                     const f32x4 w0 = *(const f32x4*)((const char*)cw + woff), w1 = *(const f32x4*)((const char*)cw + woff + XBCW * 4), w2 = *(const f32x4*)((const char*)cw + woff + 2 * XBCW * 4), w3 = *(const f32x4*)((const char*)cw + woff + 3 * XBCW * 4), bs = *(const f32x4*)((const char*)cb + woff);
;                     const LAS unsigned char* hp = hb + (prev * H * NCH + chl + co) * 2;
;                     const u32x2 q1 = *(const LAS u32x2*)(hp + hr1 * NCH * 2), q2 = *(const LAS u32x2*)(hp + hr2 * NCH * 2), q3 = *(const LAS u32x2*)(hp + hr3 * NCH * 2);
;                     const float h1[4] = {__builtin_bit_cast(float, q1.x << 16), __builtin_bit_cast(float, q1.x & 0xffff0000u), __builtin_bit_cast(float, q1.y << 16), __builtin_bit_cast(float, q1.y & 0xffff0000u)};
;                     const float h2[4] = {__builtin_bit_cast(float, q2.x << 16), __builtin_bit_cast(float, q2.x & 0xffff0000u), __builtin_bit_cast(float, q2.y << 16), __builtin_bit_cast(float, q2.y & 0xffff0000u)};
;                     const float h3[4] = {__builtin_bit_cast(float, q3.x << 16), __builtin_bit_cast(float, q3.x & 0xffff0000u), __builtin_bit_cast(float, q3.y << 16), __builtin_bit_cast(float, q3.y & 0xffff0000u)};
;                     const f32x4 gv = acc[ai][bj][m][n];
;                     float o[4];
; #pragma unroll
;                     for (int j = 0; j < 4; ++j) { const float g = gv[j];
;                         float g1 = dpp_row_shr<1>(h1[j], g), g2 = dpp_row_shr<2>(h2[j], g), g3 = dpp_row_shr<3>(h3[j], g);
;                         g1 = p >= 1 ? g1 : 0.f; g2 = p >= 2 ? g2 : 0.f; g3 = p >= 3 ? g3 : 0.f;
;                         const float v = bs[j] + w3[j] * g + w2[j] * g1 + w1[j] * g2 + w0[j] * g3;
;                         o[j] = v * __builtin_amdgcn_rcpf(1.f + ex2(-1.4426950408889634f * v)); }
;                     if (ok) { u32x2 w; w.x = pk2e(o[0], o[1]); w.y = pk2e(o[2], o[3]); *(u32x2*)((char*)O + ooff + co * 2) = w; }
;                     asm volatile("" ::: "memory"); }
	v_cndmask_b32_e64 v45, v44, 0, s[8:9]
	s_nop 0
	v_cndmask_b32_e64 v44, v43, 0, s[8:9]
	v_cndmask_b32_e64 v43, 0, v42, s[6:7]
	v_cndmask_b32_e64 v42, 0, v41, s[6:7]
	v_cndmask_b32_e64 v41, 0, v40, s[4:5]
	v_cndmask_b32_e64 v40, 0, v39, s[4:5]
	v_cndmask_b32_e64 v31, 0, v31, s[6:7]
	v_cndmask_b32_e64 v30, 0, v30, s[6:7]
	v_cndmask_b32_e64 v29, 0, v29, s[4:5]
	v_cndmask_b32_e64 v28, 0, v28, s[4:5]
	v_pk_fma_f32 v[24:25], v[24:25], v[212:213], v[208:209]
	v_pk_fma_f32 v[26:27], v[26:27], v[214:215], v[210:211]
	v_pk_fma_f32 v[24:25], v[44:45], v[216:217], v[24:25]
	s_nop 0
	v_pk_fma_f32 v[24:25], v[42:43], v[220:221], v[24:25]
	s_nop 0
	v_pk_fma_f32 v[24:25], v[40:41], v[224:225], v[24:25]
	s_nop 0
	v_mul_f32_e32 v39, 0xbfb8aa3b, v25
	v_exp_f32_e32 v39, v39
	s_nop 0
	v_add_f32_e32 v39, 1.0, v39
	v_rcp_f32_e32 v41, v39
	v_mul_f32_e32 v39, 0xbfb8aa3b, v24
	v_exp_f32_e32 v39, v39
	s_nop 0
	v_add_f32_e32 v39, 1.0, v39
	v_rcp_f32_e32 v40, v39
	v_cndmask_b32_e64 v39, v38, 0, s[8:9]
	v_cndmask_b32_e64 v38, v37, 0, s[8:9]
	v_pk_fma_f32 v[26:27], v[38:39], v[218:219], v[26:27]
	v_pk_mul_f32 v[24:25], v[24:25], v[40:41]
	v_pk_fma_f32 v[26:27], v[30:31], v[222:223], v[26:27]
	v_cvt_pk_bf16_f32 v24, v24, v25
	v_pk_fma_f32 v[26:27], v[28:29], v[226:227], v[26:27]
	s_nop 0
	v_mul_f32_e32 v25, 0xbfb8aa3b, v27
	v_exp_f32_e32 v25, v25
	s_nop 0
	v_add_f32_e32 v25, 1.0, v25
	v_rcp_f32_e32 v29, v25
	v_mul_f32_e32 v25, 0xbfb8aa3b, v26
	v_exp_f32_e32 v25, v25
	s_nop 0
	v_add_f32_e32 v25, 1.0, v25
	v_rcp_f32_e32 v28, v25
	s_nop 0
	v_pk_mul_f32 v[26:27], v[26:27], v[28:29]
	s_nop 0
	v_cvt_pk_bf16_f32 v25, v26, v27
	global_store_dwordx2 v[32:33], v[24:25], off offset:8
.LBB0_235:
	s_or_b64 exec, exec, s[22:23]
	ds_read_b64 v[24:25], v34 offset:1280
	ds_read_b64 v[26:27], v35 offset:768
	ds_read_b64 v[42:43], v36 offset:256
	ds_read_b128 v[208:211], v238 offset:4608
	ds_read_b128 v[212:215], v238 offset:3584
	ds_read_b128 v[216:219], v238 offset:2560
	ds_read_b128 v[220:223], v238 offset:1536
	ds_read_b128 v[224:227], v238 offset:512
	s_waitcnt lgkmcnt(0)
	v_lshlrev_b32_e32 v39, 16, v24
	v_and_b32_e32 v40, 0xffff0000, v24
	v_lshlrev_b32_e32 v28, 16, v25
	v_and_b32_e32 v29, 0xffff0000, v25
	v_lshlrev_b32_e32 v37, 16, v26
	v_and_b32_e32 v38, 0xffff0000, v26
	v_lshlrev_b32_e32 v26, 16, v27
	v_and_b32_e32 v27, 0xffff0000, v27
	v_lshlrev_b32_e32 v30, 16, v42
	v_and_b32_e32 v31, 0xffff0000, v42
	v_lshlrev_b32_e32 v24, 16, v43
	v_and_b32_e32 v25, 0xffff0000, v43
	v_mov_b32_dpp v39, v20 row_shr:1 row_mask:0xf bank_mask:0xf
	v_mov_b32_dpp v37, v20 row_shr:2 row_mask:0xf bank_mask:0xf
	v_mov_b32_dpp v30, v20 row_shr:3 row_mask:0xf bank_mask:0xf
	v_mov_b32_dpp v40, v21 row_shr:1 row_mask:0xf bank_mask:0xf
	v_mov_b32_dpp v38, v21 row_shr:2 row_mask:0xf bank_mask:0xf
	v_mov_b32_dpp v31, v21 row_shr:3 row_mask:0xf bank_mask:0xf
	v_mov_b32_dpp v28, v22 row_shr:1 row_mask:0xf bank_mask:0xf
	v_mov_b32_dpp v26, v22 row_shr:2 row_mask:0xf bank_mask:0xf
	v_mov_b32_dpp v24, v22 row_shr:3 row_mask:0xf bank_mask:0xf
	v_mov_b32_dpp v29, v23 row_shr:1 row_mask:0xf bank_mask:0xf
	v_mov_b32_dpp v27, v23 row_shr:2 row_mask:0xf bank_mask:0xf
	v_mov_b32_dpp v25, v23 row_shr:3 row_mask:0xf bank_mask:0xf
	s_and_saveexec_b64 s[22:23], s[2:3]
	s_cbranch_execz .LBB0_237
	v_cndmask_b32_e64 v41, v40, 0, s[8:9]
	s_nop 0
	v_cndmask_b32_e64 v40, v39, 0, s[8:9]
	v_cndmask_b32_e64 v39, 0, v38, s[6:7]
	v_cndmask_b32_e64 v38, 0, v37, s[6:7]
	v_cndmask_b32_e64 v31, 0, v31, s[4:5]
	v_cndmask_b32_e64 v30, 0, v30, s[4:5]
	v_cndmask_b32_e64 v29, v29, 0, s[8:9]
	v_cndmask_b32_e64 v28, v28, 0, s[8:9]
	v_cndmask_b32_e64 v27, 0, v27, s[6:7]
	v_cndmask_b32_e64 v26, 0, v26, s[6:7]
	v_cndmask_b32_e64 v25, 0, v25, s[4:5]
	v_cndmask_b32_e64 v24, 0, v24, s[4:5]
	v_pk_fma_f32 v[20:21], v[20:21], v[212:213], v[208:209]
	v_pk_fma_f32 v[22:23], v[22:23], v[214:215], v[210:211]
	v_pk_fma_f32 v[20:21], v[40:41], v[216:217], v[20:21]
	v_pk_fma_f32 v[22:23], v[28:29], v[218:219], v[22:23]
	v_pk_fma_f32 v[20:21], v[38:39], v[220:221], v[20:21]
	s_nop 0
	v_pk_fma_f32 v[20:21], v[30:31], v[224:225], v[20:21]
	v_pk_fma_f32 v[22:23], v[26:27], v[222:223], v[22:23]
	v_mul_f32_e32 v30, 0xbfb8aa3b, v21
	v_exp_f32_e32 v30, v30
	v_pk_fma_f32 v[22:23], v[24:25], v[226:227], v[22:23]
	v_add_f32_e32 v30, 1.0, v30
	v_rcp_f32_e32 v31, v30
	v_mul_f32_e32 v30, 0xbfb8aa3b, v20
	v_exp_f32_e32 v30, v30
	s_nop 0
	v_add_f32_e32 v30, 1.0, v30
	v_rcp_f32_e32 v30, v30
	s_nop 0
	v_pk_mul_f32 v[20:21], v[20:21], v[30:31]
	s_nop 0
	v_cvt_pk_bf16_f32 v20, v20, v21
	v_mul_f32_e32 v21, 0xbfb8aa3b, v23
	v_exp_f32_e32 v21, v21
	s_nop 0
	v_add_f32_e32 v21, 1.0, v21
	v_rcp_f32_e32 v25, v21
	v_mul_f32_e32 v21, 0xbfb8aa3b, v22
	v_exp_f32_e32 v21, v21
	s_nop 0
	v_add_f32_e32 v21, 1.0, v21
	v_rcp_f32_e32 v24, v21
	s_nop 0
	v_pk_mul_f32 v[22:23], v[22:23], v[24:25]
	s_nop 0
	v_cvt_pk_bf16_f32 v21, v22, v23
	global_store_dwordx2 v[32:33], v[20:21], off offset:256
;     __device__ __forceinline__ void operator()(const f32x4 (&acc)[2][2][4][2], const Unit& u, int wr, int wc, int fr, int fq, LAS unsigned char* hb) const {
;     ...
;                 const int q = 8 * ai + 4 * wr + m, prev = q > 0 ? q - 1 : 0; const int lr = ai * HALF + wr * 64 + m * 16 + fr, R = R0 + lr;
;                 const int Rc = R < 0 ? 0 : R; const int b = Rc / LL, p = Rc - b * LL;
;                 const bool ok = (lr >= H && R < TT);
;                 const unsigned ooff = ((unsigned)Rc * (unsigned)LDP + (unsigned)(OFF_XBC + ch0)) * 2u;
; #pragma unroll
;                 for (int bn = 0; bn < 4; ++bn) { const int bj = bn >> 1, n = bn & 1; const int co = bj * HALF + 4 * n;
;                     const unsigned woff = (unsigned)(ch0 + co) * 4u;
;                     const f32x4 w0 = *(const f32x4*)((const char*)cw + woff), w1 = *(const f32x4*)((const char*)cw + woff + XBCW * 4), w2 = *(const f32x4*)((const char*)cw + woff + 2 * XBCW * 4), w3 = *(const f32x4*)((const char*)cw + woff + 3 * XBCW * 4), bs = *(const f32x4*)((const char*)cb + woff);
;                     const LAS unsigned char* hp = hb + (prev * H * NCH + chl + co) * 2;
;                     const u32x2 q1 = *(const LAS u32x2*)(hp + hr1 * NCH * 2), q2 = *(const LAS u32x2*)(hp + hr2 * NCH * 2), q3 = *(const LAS u32x2*)(hp + hr3 * NCH * 2);
;                     const float h1[4] = {__builtin_bit_cast(float, q1.x << 16), __builtin_bit_cast(float, q1.x & 0xffff0000u), __builtin_bit_cast(float, q1.y << 16), __builtin_bit_cast(float, q1.y & 0xffff0000u)};
;                     const float h2[4] = {__builtin_bit_cast(float, q2.x << 16), __builtin_bit_cast(float, q2.x & 0xffff0000u), __builtin_bit_cast(float, q2.y << 16), __builtin_bit_cast(float, q2.y & 0xffff0000u)};
;                     const float h3[4] = {__builtin_bit_cast(float, q3.x << 16), __builtin_bit_cast(float, q3.x & 0xffff0000u), __builtin_bit_cast(float, q3.y << 16), __builtin_bit_cast(float, q3.y & 0xffff0000u)};
;                     const f32x4 gv = acc[ai][bj][m][n];
;                     float o[4];
; #pragma unroll
;                     for (int j = 0; j < 4; ++j) { const float g = gv[j];
;                         float g1 = dpp_row_shr<1>(h1[j], g), g2 = dpp_row_shr<2>(h2[j], g), g3 = dpp_row_shr<3>(h3[j], g);
;                         g1 = p >= 1 ? g1 : 0.f; g2 = p >= 2 ? g2 : 0.f; g3 = p >= 3 ? g3 : 0.f;
.LBB0_237:
	s_or_b64 exec, exec, s[22:23]
	ds_read_b64 v[20:21], v34 offset:1288
	ds_read_b64 v[22:23], v35 offset:776
	ds_read_b64 v[34:35], v36 offset:264
	ds_read_b128 v[208:211], v238 offset:4624
	ds_read_b128 v[212:215], v238 offset:3600
	ds_read_b128 v[216:219], v238 offset:2576
	ds_read_b128 v[220:223], v238 offset:1552
	ds_read_b128 v[224:227], v238 offset:528
	s_waitcnt lgkmcnt(0)
	v_lshlrev_b32_e32 v30, 16, v20
	v_and_b32_e32 v31, 0xffff0000, v20
	v_lshlrev_b32_e32 v24, 16, v21
	v_and_b32_e32 v25, 0xffff0000, v21
	v_lshlrev_b32_e32 v28, 16, v22
	v_and_b32_e32 v29, 0xffff0000, v22
	v_lshlrev_b32_e32 v22, 16, v23
	v_and_b32_e32 v23, 0xffff0000, v23
	v_lshlrev_b32_e32 v26, 16, v34
	v_and_b32_e32 v27, 0xffff0000, v34
	v_lshlrev_b32_e32 v20, 16, v35
	v_and_b32_e32 v21, 0xffff0000, v35
	v_mov_b32_dpp v30, v16 row_shr:1 row_mask:0xf bank_mask:0xf
	v_mov_b32_dpp v28, v16 row_shr:2 row_mask:0xf bank_mask:0xf
	v_mov_b32_dpp v26, v16 row_shr:3 row_mask:0xf bank_mask:0xf
	v_mov_b32_dpp v31, v17 row_shr:1 row_mask:0xf bank_mask:0xf
	v_mov_b32_dpp v29, v17 row_shr:2 row_mask:0xf bank_mask:0xf
	v_mov_b32_dpp v27, v17 row_shr:3 row_mask:0xf bank_mask:0xf
	v_mov_b32_dpp v24, v18 row_shr:1 row_mask:0xf bank_mask:0xf
	v_mov_b32_dpp v22, v18 row_shr:2 row_mask:0xf bank_mask:0xf
	v_mov_b32_dpp v20, v18 row_shr:3 row_mask:0xf bank_mask:0xf
	v_mov_b32_dpp v25, v19 row_shr:1 row_mask:0xf bank_mask:0xf
	v_mov_b32_dpp v23, v19 row_shr:2 row_mask:0xf bank_mask:0xf
	v_mov_b32_dpp v21, v19 row_shr:3 row_mask:0xf bank_mask:0xf
	s_and_saveexec_b64 s[22:23], s[2:3]
	s_cbranch_execz .LBB0_239
	v_cndmask_b32_e64 v31, v31, 0, s[8:9]
	s_nop 0
	v_cndmask_b32_e64 v30, v30, 0, s[8:9]
	v_cndmask_b32_e64 v29, 0, v29, s[6:7]
	v_cndmask_b32_e64 v28, 0, v28, s[6:7]
	v_cndmask_b32_e64 v27, 0, v27, s[4:5]
	v_cndmask_b32_e64 v26, 0, v26, s[4:5]
	v_cndmask_b32_e64 v25, v25, 0, s[8:9]
	v_cndmask_b32_e64 v24, v24, 0, s[8:9]
	v_cndmask_b32_e64 v23, 0, v23, s[6:7]
	v_cndmask_b32_e64 v22, 0, v22, s[6:7]
	v_cndmask_b32_e64 v21, 0, v21, s[4:5]
	v_cndmask_b32_e64 v20, 0, v20, s[4:5]
	v_pk_fma_f32 v[16:17], v[16:17], v[212:213], v[208:209]
	v_pk_fma_f32 v[18:19], v[18:19], v[214:215], v[210:211]
	v_pk_fma_f32 v[16:17], v[30:31], v[216:217], v[16:17]
	v_pk_fma_f32 v[18:19], v[24:25], v[218:219], v[18:19]
	v_pk_fma_f32 v[16:17], v[28:29], v[220:221], v[16:17]
	s_nop 0
	v_pk_fma_f32 v[16:17], v[26:27], v[224:225], v[16:17]
	v_pk_fma_f32 v[18:19], v[22:23], v[222:223], v[18:19]
	v_mul_f32_e32 v26, 0xbfb8aa3b, v17
	v_exp_f32_e32 v26, v26
	v_pk_fma_f32 v[18:19], v[20:21], v[226:227], v[18:19]
	v_add_f32_e32 v26, 1.0, v26
	v_rcp_f32_e32 v27, v26
	v_mul_f32_e32 v26, 0xbfb8aa3b, v16
	v_exp_f32_e32 v26, v26
	s_nop 0
	v_add_f32_e32 v26, 1.0, v26
	v_rcp_f32_e32 v26, v26
	s_nop 0
	v_pk_mul_f32 v[16:17], v[16:17], v[26:27]
	s_nop 0
	v_cvt_pk_bf16_f32 v16, v16, v17
	v_mul_f32_e32 v17, 0xbfb8aa3b, v19
	v_exp_f32_e32 v17, v17
	s_nop 0
	v_add_f32_e32 v17, 1.0, v17
	v_rcp_f32_e32 v21, v17
	v_mul_f32_e32 v17, 0xbfb8aa3b, v18
	v_exp_f32_e32 v17, v17
	s_nop 0
	v_add_f32_e32 v17, 1.0, v17
	v_rcp_f32_e32 v20, v17
	s_nop 0
	v_pk_mul_f32 v[18:19], v[18:19], v[20:21]
	s_nop 0
	v_cvt_pk_bf16_f32 v17, v18, v19
	global_store_dwordx2 v[32:33], v[16:17], off offset:264
.LBB0_239:
	s_or_b64 exec, exec, s[22:23]
	v_add_u32_e32 v16, 0xb0, v161
	v_add_u32_e32 v17, s17, v16
	v_max_i32_e32 v18, 0, v17
	v_mul_hi_u32 v19, v18, s56
	v_lshrrev_b32_e32 v19, 11, v19
	v_cmp_lt_i32_e32 vcc, 2, v16
	v_mul_lo_u32 v16, v18, s51
	v_mul_u32_u24_e32 v19, 0x1010, v19
	v_add_lshl_u32 v136, v16, v164, 1
	v_add_u32_e32 v16, s44, v165
	v_sub_u32_e32 v19, v18, v19
	v_cmp_gt_i32_e64 s[4:5], s50, v17
	v_lshl_add_u32 v18, v16, 1, s53
	s_and_b64 s[2:3], vcc, s[4:5]
	v_cmp_eq_u32_e64 s[8:9], 0, v19
	v_cmp_lt_u32_e64 s[6:7], 1, v19
	v_cmp_lt_u32_e64 s[4:5], 2, v19
	v_add_u32_e32 v19, v18, v163
	ds_read_b64 v[16:17], v18 offset:1024
	v_add_u32_e32 v20, v18, v162
	ds_read_b64 v[34:35], v19 offset:512
	ds_read_b64 v[36:37], v20
	ds_read_b128 v[208:211], v238 offset:4096
	ds_read_b128 v[212:215], v238 offset:3072
	ds_read_b128 v[216:219], v238 offset:2048
	ds_read_b128 v[220:223], v238 offset:1024
	ds_read_b128 v[224:227], v238
	v_readlane_b32 s22, v237, 58
	v_readlane_b32 s23, v237, 59
	s_waitcnt lgkmcnt(0)
	v_lshlrev_b32_e32 v31, 16, v16
	v_and_b32_e32 v32, 0xffff0000, v16
	v_lshlrev_b32_e32 v25, 16, v17
	v_and_b32_e32 v26, 0xffff0000, v17
	v_lshlrev_b32_e32 v29, 16, v34
	v_and_b32_e32 v30, 0xffff0000, v34
	v_lshlrev_b32_e32 v23, 16, v35
	v_and_b32_e32 v24, 0xffff0000, v35
	v_lshlrev_b32_e32 v27, 16, v36
	v_and_b32_e32 v28, 0xffff0000, v36
	v_lshlrev_b32_e32 v21, 16, v37
	v_and_b32_e32 v22, 0xffff0000, v37
	v_mov_b32_dpp v31, v12 row_shr:1 row_mask:0xf bank_mask:0xf
	v_mov_b32_dpp v29, v12 row_shr:2 row_mask:0xf bank_mask:0xf
	v_mov_b32_dpp v27, v12 row_shr:3 row_mask:0xf bank_mask:0xf
	v_mov_b32_dpp v32, v13 row_shr:1 row_mask:0xf bank_mask:0xf
	v_mov_b32_dpp v30, v13 row_shr:2 row_mask:0xf bank_mask:0xf
	v_mov_b32_dpp v28, v13 row_shr:3 row_mask:0xf bank_mask:0xf
	v_mov_b32_dpp v25, v14 row_shr:1 row_mask:0xf bank_mask:0xf
	v_mov_b32_dpp v23, v14 row_shr:2 row_mask:0xf bank_mask:0xf
	v_mov_b32_dpp v21, v14 row_shr:3 row_mask:0xf bank_mask:0xf
	v_mov_b32_dpp v26, v15 row_shr:1 row_mask:0xf bank_mask:0xf
	v_mov_b32_dpp v24, v15 row_shr:2 row_mask:0xf bank_mask:0xf
	v_mov_b32_dpp v22, v15 row_shr:3 row_mask:0xf bank_mask:0xf
	v_lshl_add_u64 v[16:17], s[22:23], 0, v[136:137]
	s_and_saveexec_b64 s[22:23], s[2:3]
	s_cbranch_execz .LBB0_241
;     __device__ __forceinline__ void operator()(const f32x4 (&acc)[2][2][4][2], const Unit& u, int wr, int wc, int fr, int fq, LAS unsigned char* hb) const {
;     ...
;                 for (int bn = 0; bn < 4; ++bn) { const int bj = bn >> 1, n = bn & 1; const int co = bj * HALF + 4 * n;
;                     const unsigned woff = (unsigned)(ch0 + co) * 4u;
;                     const f32x4 w0 = *(const f32x4*)((const char*)cw + woff), w1 = *(const f32x4*)((const char*)cw + woff + XBCW * 4), w2 = *(const f32x4*)((const char*)cw + woff + 2 * XBCW * 4), w3 = *(const f32x4*)((const char*)cw + woff + 3 * XBCW * 4), bs = *(const f32x4*)((const char*)cb + woff);
;                     const LAS unsigned char* hp = hb + (prev * H * NCH + chl + co) * 2;
;                     const u32x2 q1 = *(const LAS u32x2*)(hp + hr1 * NCH * 2), q2 = *(const LAS u32x2*)(hp + hr2 * NCH * 2), q3 = *(const LAS u32x2*)(hp + hr3 * NCH * 2);
;                     const float h1[4] = {__builtin_bit_cast(float, q1.x << 16), __builtin_bit_cast(float, q1.x & 0xffff0000u), __builtin_bit_cast(float, q1.y << 16), __builtin_bit_cast(float, q1.y & 0xffff0000u)};
;                     const float h2[4] = {__builtin_bit_cast(float, q2.x << 16), __builtin_bit_cast(float, q2.x & 0xffff0000u), __builtin_bit_cast(float, q2.y << 16), __builtin_bit_cast(float, q2.y & 0xffff0000u)};
;                     const float h3[4] = {__builtin_bit_cast(float, q3.x << 16), __builtin_bit_cast(float, q3.x & 0xffff0000u), __builtin_bit_cast(float, q3.y << 16), __builtin_bit_cast(float, q3.y & 0xffff0000u)};
;                     const f32x4 gv = acc[ai][bj][m][n];
;                     float o[4];
; #pragma unroll
;                     for (int j = 0; j < 4; ++j) { const float g = gv[j];
;                         float g1 = dpp_row_shr<1>(h1[j], g), g2 = dpp_row_shr<2>(h2[j], g), g3 = dpp_row_shr<3>(h3[j], g);
;                         g1 = p >= 1 ? g1 : 0.f; g2 = p >= 2 ? g2 : 0.f; g3 = p >= 3 ? g3 : 0.f;
;                         const float v = bs[j] + w3[j] * g + w2[j] * g1 + w1[j] * g2 + w0[j] * g3;
;                         o[j] = v * __builtin_amdgcn_rcpf(1.f + ex2(-1.4426950408889634f * v)); }
;                     if (ok) { u32x2 w; w.x = pk2e(o[0], o[1]); w.y = pk2e(o[2], o[3]); *(u32x2*)((char*)O + ooff + co * 2) = w; }
;                     asm volatile("" ::: "memory"); }
	v_cndmask_b32_e64 v33, v32, 0, s[8:9]
	s_nop 0
	v_cndmask_b32_e64 v32, v31, 0, s[8:9]
	v_cndmask_b32_e64 v31, 0, v30, s[6:7]
	v_cndmask_b32_e64 v30, 0, v29, s[6:7]
	v_cndmask_b32_e64 v29, 0, v28, s[4:5]
	v_cndmask_b32_e64 v28, 0, v27, s[4:5]
	v_pk_fma_f32 v[12:13], v[12:13], v[212:213], v[208:209]
	v_pk_fma_f32 v[14:15], v[14:15], v[214:215], v[210:211]
	v_pk_fma_f32 v[12:13], v[32:33], v[216:217], v[12:13]
	s_nop 0
	v_pk_fma_f32 v[12:13], v[30:31], v[220:221], v[12:13]
	s_nop 0
	v_pk_fma_f32 v[12:13], v[28:29], v[224:225], v[12:13]
	s_nop 0
	v_mul_f32_e32 v27, 0xbfb8aa3b, v13
	v_exp_f32_e32 v27, v27
	s_nop 0
	v_add_f32_e32 v27, 1.0, v27
	v_rcp_f32_e32 v29, v27
	v_mul_f32_e32 v27, 0xbfb8aa3b, v12
	v_exp_f32_e32 v27, v27
	s_nop 0
	v_add_f32_e32 v27, 1.0, v27
	v_rcp_f32_e32 v28, v27
	v_cndmask_b32_e64 v27, v26, 0, s[8:9]
	v_cndmask_b32_e64 v26, v25, 0, s[8:9]
	v_pk_fma_f32 v[14:15], v[26:27], v[218:219], v[14:15]
	v_cndmask_b32_e64 v25, 0, v24, s[6:7]
	v_cndmask_b32_e64 v24, 0, v23, s[6:7]
	v_pk_fma_f32 v[14:15], v[24:25], v[222:223], v[14:15]
	v_cndmask_b32_e64 v23, 0, v22, s[4:5]
	v_cndmask_b32_e64 v22, 0, v21, s[4:5]
	v_pk_mul_f32 v[12:13], v[12:13], v[28:29]
	v_pk_fma_f32 v[14:15], v[22:23], v[226:227], v[14:15]
	v_cvt_pk_bf16_f32 v12, v12, v13
	v_mul_f32_e32 v13, 0xbfb8aa3b, v15
	v_exp_f32_e32 v13, v13
	s_nop 0
	v_add_f32_e32 v13, 1.0, v13
	v_rcp_f32_e32 v23, v13
	v_mul_f32_e32 v13, 0xbfb8aa3b, v14
	v_exp_f32_e32 v13, v13
	s_nop 0
	v_add_f32_e32 v13, 1.0, v13
	v_rcp_f32_e32 v22, v13
	s_nop 0
	v_pk_mul_f32 v[14:15], v[14:15], v[22:23]
	s_nop 0
	v_cvt_pk_bf16_f32 v13, v14, v15
	global_store_dwordx2 v[16:17], v[12:13], off
.LBB0_241:
	s_or_b64 exec, exec, s[22:23]
	ds_read_b64 v[12:13], v18 offset:1032
	ds_read_b64 v[14:15], v19 offset:520
	ds_read_b64 v[30:31], v20 offset:8
	ds_read_b128 v[208:211], v238 offset:4112
	ds_read_b128 v[212:215], v238 offset:3088
	ds_read_b128 v[216:219], v238 offset:2064
	ds_read_b128 v[220:223], v238 offset:1040
	ds_read_b128 v[224:227], v238 offset:16
	s_waitcnt lgkmcnt(0)
	v_lshlrev_b32_e32 v27, 16, v12
	v_and_b32_e32 v28, 0xffff0000, v12
	v_lshlrev_b32_e32 v21, 16, v13
	v_and_b32_e32 v22, 0xffff0000, v13
	v_lshlrev_b32_e32 v25, 16, v14
	v_and_b32_e32 v26, 0xffff0000, v14
	v_lshlrev_b32_e32 v14, 16, v15
	v_and_b32_e32 v15, 0xffff0000, v15
	v_lshlrev_b32_e32 v23, 16, v30
	v_and_b32_e32 v24, 0xffff0000, v30
	v_lshlrev_b32_e32 v12, 16, v31
	v_and_b32_e32 v13, 0xffff0000, v31
	v_mov_b32_dpp v27, v8 row_shr:1 row_mask:0xf bank_mask:0xf
	v_mov_b32_dpp v25, v8 row_shr:2 row_mask:0xf bank_mask:0xf
	v_mov_b32_dpp v23, v8 row_shr:3 row_mask:0xf bank_mask:0xf
	v_mov_b32_dpp v28, v9 row_shr:1 row_mask:0xf bank_mask:0xf
	v_mov_b32_dpp v26, v9 row_shr:2 row_mask:0xf bank_mask:0xf
	v_mov_b32_dpp v24, v9 row_shr:3 row_mask:0xf bank_mask:0xf
	v_mov_b32_dpp v21, v10 row_shr:1 row_mask:0xf bank_mask:0xf
	v_mov_b32_dpp v14, v10 row_shr:2 row_mask:0xf bank_mask:0xf
	v_mov_b32_dpp v12, v10 row_shr:3 row_mask:0xf bank_mask:0xf
	v_mov_b32_dpp v22, v11 row_shr:1 row_mask:0xf bank_mask:0xf
	v_mov_b32_dpp v15, v11 row_shr:2 row_mask:0xf bank_mask:0xf
	v_mov_b32_dpp v13, v11 row_shr:3 row_mask:0xf bank_mask:0xf
	s_and_saveexec_b64 s[22:23], s[2:3]
	s_cbranch_execz .LBB0_243
	v_cndmask_b32_e64 v29, v28, 0, s[8:9]
	s_nop 0
	v_cndmask_b32_e64 v28, v27, 0, s[8:9]
	v_cndmask_b32_e64 v27, 0, v26, s[6:7]
	v_cndmask_b32_e64 v26, 0, v25, s[6:7]
	v_cndmask_b32_e64 v25, 0, v24, s[4:5]
	v_cndmask_b32_e64 v24, 0, v23, s[4:5]
	v_cndmask_b32_e64 v15, 0, v15, s[6:7]
	v_cndmask_b32_e64 v14, 0, v14, s[6:7]
	v_cndmask_b32_e64 v13, 0, v13, s[4:5]
	v_cndmask_b32_e64 v12, 0, v12, s[4:5]
	v_pk_fma_f32 v[8:9], v[8:9], v[212:213], v[208:209]
	v_pk_fma_f32 v[10:11], v[10:11], v[214:215], v[210:211]
	v_pk_fma_f32 v[8:9], v[28:29], v[216:217], v[8:9]
	s_nop 0
	v_pk_fma_f32 v[8:9], v[26:27], v[220:221], v[8:9]
	s_nop 0
	v_pk_fma_f32 v[8:9], v[24:25], v[224:225], v[8:9]
	s_nop 0
	v_mul_f32_e32 v23, 0xbfb8aa3b, v9
	v_exp_f32_e32 v23, v23
	s_nop 0
	v_add_f32_e32 v23, 1.0, v23
	v_rcp_f32_e32 v25, v23
	v_mul_f32_e32 v23, 0xbfb8aa3b, v8
	v_exp_f32_e32 v23, v23
	s_nop 0
	v_add_f32_e32 v23, 1.0, v23
	v_rcp_f32_e32 v24, v23
	v_cndmask_b32_e64 v23, v22, 0, s[8:9]
	v_cndmask_b32_e64 v22, v21, 0, s[8:9]
	v_pk_fma_f32 v[10:11], v[22:23], v[218:219], v[10:11]
	v_pk_mul_f32 v[8:9], v[8:9], v[24:25]
	v_pk_fma_f32 v[10:11], v[14:15], v[222:223], v[10:11]
	v_cvt_pk_bf16_f32 v8, v8, v9
	v_pk_fma_f32 v[10:11], v[12:13], v[226:227], v[10:11]
	s_nop 0
	v_mul_f32_e32 v9, 0xbfb8aa3b, v11
	v_exp_f32_e32 v9, v9
	s_nop 0
	v_add_f32_e32 v9, 1.0, v9
	v_rcp_f32_e32 v13, v9
	v_mul_f32_e32 v9, 0xbfb8aa3b, v10
	v_exp_f32_e32 v9, v9
	s_nop 0
	v_add_f32_e32 v9, 1.0, v9
	v_rcp_f32_e32 v12, v9
	s_nop 0
	v_pk_mul_f32 v[10:11], v[10:11], v[12:13]
	s_nop 0
	v_cvt_pk_bf16_f32 v9, v10, v11
	global_store_dwordx2 v[16:17], v[8:9], off offset:8
;     __device__ __forceinline__ void operator()(const f32x4 (&acc)[2][2][4][2], const Unit& u, int wr, int wc, int fr, int fq, LAS unsigned char* hb) const {
;     ...
;                 for (int bn = 0; bn < 4; ++bn) { const int bj = bn >> 1, n = bn & 1; const int co = bj * HALF + 4 * n;
;                     const unsigned woff = (unsigned)(ch0 + co) * 4u;
;                     const f32x4 w0 = *(const f32x4*)((const char*)cw + woff), w1 = *(const f32x4*)((const char*)cw + woff + XBCW * 4), w2 = *(const f32x4*)((const char*)cw + woff + 2 * XBCW * 4), w3 = *(const f32x4*)((const char*)cw + woff + 3 * XBCW * 4), bs = *(const f32x4*)((const char*)cb + woff);
;                     const LAS unsigned char* hp = hb + (prev * H * NCH + chl + co) * 2;
;                     const u32x2 q1 = *(const LAS u32x2*)(hp + hr1 * NCH * 2), q2 = *(const LAS u32x2*)(hp + hr2 * NCH * 2), q3 = *(const LAS u32x2*)(hp + hr3 * NCH * 2);
;                     const float h1[4] = {__builtin_bit_cast(float, q1.x << 16), __builtin_bit_cast(float, q1.x & 0xffff0000u), __builtin_bit_cast(float, q1.y << 16), __builtin_bit_cast(float, q1.y & 0xffff0000u)};
;                     const float h2[4] = {__builtin_bit_cast(float, q2.x << 16), __builtin_bit_cast(float, q2.x & 0xffff0000u), __builtin_bit_cast(float, q2.y << 16), __builtin_bit_cast(float, q2.y & 0xffff0000u)};
;                     const float h3[4] = {__builtin_bit_cast(float, q3.x << 16), __builtin_bit_cast(float, q3.x & 0xffff0000u), __builtin_bit_cast(float, q3.y << 16), __builtin_bit_cast(float, q3.y & 0xffff0000u)};
;                     const f32x4 gv = acc[ai][bj][m][n];
;                     float o[4];
; #pragma unroll
;                     for (int j = 0; j < 4; ++j) { const float g = gv[j];
;                         float g1 = dpp_row_shr<1>(h1[j], g), g2 = dpp_row_shr<2>(h2[j], g), g3 = dpp_row_shr<3>(h3[j], g);
;                         g1 = p >= 1 ? g1 : 0.f; g2 = p >= 2 ? g2 : 0.f; g3 = p >= 3 ? g3 : 0.f;
;                         const float v = bs[j] + w3[j] * g + w2[j] * g1 + w1[j] * g2 + w0[j] * g3;
;                         o[j] = v * __builtin_amdgcn_rcpf(1.f + ex2(-1.4426950408889634f * v)); }
;                     if (ok) { u32x2 w; w.x = pk2e(o[0], o[1]); w.y = pk2e(o[2], o[3]); *(u32x2*)((char*)O + ooff + co * 2) = w; }
;                     asm volatile("" ::: "memory"); }
.LBB0_243:
	s_or_b64 exec, exec, s[22:23]
	ds_read_b64 v[8:9], v18 offset:1280
	ds_read_b64 v[10:11], v19 offset:768
	ds_read_b64 v[26:27], v20 offset:256
	ds_read_b128 v[208:211], v238 offset:4608
	ds_read_b128 v[212:215], v238 offset:3584
	ds_read_b128 v[216:219], v238 offset:2560
	ds_read_b128 v[220:223], v238 offset:1536
	ds_read_b128 v[224:227], v238 offset:512
	s_waitcnt lgkmcnt(0)
	v_lshlrev_b32_e32 v23, 16, v8
	v_and_b32_e32 v24, 0xffff0000, v8
	v_lshlrev_b32_e32 v12, 16, v9
	v_and_b32_e32 v13, 0xffff0000, v9
	v_lshlrev_b32_e32 v21, 16, v10
	v_and_b32_e32 v22, 0xffff0000, v10
	v_lshlrev_b32_e32 v10, 16, v11
	v_and_b32_e32 v11, 0xffff0000, v11
	v_lshlrev_b32_e32 v14, 16, v26
	v_and_b32_e32 v15, 0xffff0000, v26
	v_lshlrev_b32_e32 v8, 16, v27
	v_and_b32_e32 v9, 0xffff0000, v27
	v_mov_b32_dpp v23, v4 row_shr:1 row_mask:0xf bank_mask:0xf
	v_mov_b32_dpp v21, v4 row_shr:2 row_mask:0xf bank_mask:0xf
	v_mov_b32_dpp v14, v4 row_shr:3 row_mask:0xf bank_mask:0xf
	v_mov_b32_dpp v24, v5 row_shr:1 row_mask:0xf bank_mask:0xf
	v_mov_b32_dpp v22, v5 row_shr:2 row_mask:0xf bank_mask:0xf
	v_mov_b32_dpp v15, v5 row_shr:3 row_mask:0xf bank_mask:0xf
	v_mov_b32_dpp v12, v6 row_shr:1 row_mask:0xf bank_mask:0xf
	v_mov_b32_dpp v10, v6 row_shr:2 row_mask:0xf bank_mask:0xf
	v_mov_b32_dpp v8, v6 row_shr:3 row_mask:0xf bank_mask:0xf
	v_mov_b32_dpp v13, v7 row_shr:1 row_mask:0xf bank_mask:0xf
	v_mov_b32_dpp v11, v7 row_shr:2 row_mask:0xf bank_mask:0xf
	v_mov_b32_dpp v9, v7 row_shr:3 row_mask:0xf bank_mask:0xf
	s_and_saveexec_b64 s[22:23], s[2:3]
	s_cbranch_execz .LBB0_245
	v_cndmask_b32_e64 v25, v24, 0, s[8:9]
	s_nop 0
	v_cndmask_b32_e64 v24, v23, 0, s[8:9]
	v_cndmask_b32_e64 v23, 0, v22, s[6:7]
	v_cndmask_b32_e64 v22, 0, v21, s[6:7]
	v_cndmask_b32_e64 v15, 0, v15, s[4:5]
	v_cndmask_b32_e64 v14, 0, v14, s[4:5]
	v_cndmask_b32_e64 v13, v13, 0, s[8:9]
	v_cndmask_b32_e64 v12, v12, 0, s[8:9]
	v_cndmask_b32_e64 v11, 0, v11, s[6:7]
	v_cndmask_b32_e64 v10, 0, v10, s[6:7]
	v_cndmask_b32_e64 v9, 0, v9, s[4:5]
	v_cndmask_b32_e64 v8, 0, v8, s[4:5]
	v_pk_fma_f32 v[4:5], v[4:5], v[212:213], v[208:209]
	v_pk_fma_f32 v[6:7], v[6:7], v[214:215], v[210:211]
	v_pk_fma_f32 v[4:5], v[24:25], v[216:217], v[4:5]
	v_pk_fma_f32 v[6:7], v[12:13], v[218:219], v[6:7]
	v_pk_fma_f32 v[4:5], v[22:23], v[220:221], v[4:5]
	s_nop 0
	v_pk_fma_f32 v[4:5], v[14:15], v[224:225], v[4:5]
	v_pk_fma_f32 v[6:7], v[10:11], v[222:223], v[6:7]
	v_mul_f32_e32 v14, 0xbfb8aa3b, v5
	v_exp_f32_e32 v14, v14
	v_pk_fma_f32 v[6:7], v[8:9], v[226:227], v[6:7]
	v_add_f32_e32 v14, 1.0, v14
	v_rcp_f32_e32 v15, v14
	v_mul_f32_e32 v14, 0xbfb8aa3b, v4
	v_exp_f32_e32 v14, v14
	s_nop 0
	v_add_f32_e32 v14, 1.0, v14
	v_rcp_f32_e32 v14, v14
	s_nop 0
	v_pk_mul_f32 v[4:5], v[4:5], v[14:15]
	s_nop 0
	v_cvt_pk_bf16_f32 v4, v4, v5
	v_mul_f32_e32 v5, 0xbfb8aa3b, v7
	v_exp_f32_e32 v5, v5
	s_nop 0
	v_add_f32_e32 v5, 1.0, v5
	v_rcp_f32_e32 v9, v5
	v_mul_f32_e32 v5, 0xbfb8aa3b, v6
	v_exp_f32_e32 v5, v5
	s_nop 0
	v_add_f32_e32 v5, 1.0, v5
	v_rcp_f32_e32 v8, v5
	s_nop 0
	v_pk_mul_f32 v[6:7], v[6:7], v[8:9]
	s_nop 0
	v_cvt_pk_bf16_f32 v5, v6, v7
	global_store_dwordx2 v[16:17], v[4:5], off offset:256
.LBB0_245:
	s_or_b64 exec, exec, s[22:23]
	ds_read_b64 v[4:5], v18 offset:1288
	ds_read_b64 v[6:7], v19 offset:776
	ds_read_b64 v[18:19], v20 offset:264
	ds_read_b128 v[208:211], v238 offset:4624
	ds_read_b128 v[212:215], v238 offset:3600
	ds_read_b128 v[216:219], v238 offset:2576
	ds_read_b128 v[220:223], v238 offset:1552
	ds_read_b128 v[224:227], v238 offset:528
	s_waitcnt lgkmcnt(0)
	v_lshlrev_b32_e32 v14, 16, v4
	v_and_b32_e32 v15, 0xffff0000, v4
	v_lshlrev_b32_e32 v8, 16, v5
	v_and_b32_e32 v9, 0xffff0000, v5
	v_lshlrev_b32_e32 v12, 16, v6
	v_and_b32_e32 v13, 0xffff0000, v6
	v_lshlrev_b32_e32 v6, 16, v7
	v_and_b32_e32 v7, 0xffff0000, v7
	v_lshlrev_b32_e32 v10, 16, v18
	v_and_b32_e32 v11, 0xffff0000, v18
	v_lshlrev_b32_e32 v4, 16, v19
	v_and_b32_e32 v5, 0xffff0000, v19
	v_mov_b32_dpp v14, v0 row_shr:1 row_mask:0xf bank_mask:0xf
	v_mov_b32_dpp v12, v0 row_shr:2 row_mask:0xf bank_mask:0xf
	v_mov_b32_dpp v10, v0 row_shr:3 row_mask:0xf bank_mask:0xf
	v_mov_b32_dpp v15, v1 row_shr:1 row_mask:0xf bank_mask:0xf
	v_mov_b32_dpp v13, v1 row_shr:2 row_mask:0xf bank_mask:0xf
	v_mov_b32_dpp v11, v1 row_shr:3 row_mask:0xf bank_mask:0xf
	v_mov_b32_dpp v8, v2 row_shr:1 row_mask:0xf bank_mask:0xf
	v_mov_b32_dpp v6, v2 row_shr:2 row_mask:0xf bank_mask:0xf
	v_mov_b32_dpp v4, v2 row_shr:3 row_mask:0xf bank_mask:0xf
	v_mov_b32_dpp v9, v3 row_shr:1 row_mask:0xf bank_mask:0xf
	v_mov_b32_dpp v7, v3 row_shr:2 row_mask:0xf bank_mask:0xf
	v_mov_b32_dpp v5, v3 row_shr:3 row_mask:0xf bank_mask:0xf
	s_and_saveexec_b64 s[22:23], s[2:3]
	s_cbranch_execz .LBB0_247
	v_cndmask_b32_e64 v15, v15, 0, s[8:9]
	s_nop 0
	v_cndmask_b32_e64 v14, v14, 0, s[8:9]
	v_cndmask_b32_e64 v13, 0, v13, s[6:7]
	v_cndmask_b32_e64 v12, 0, v12, s[6:7]
	v_cndmask_b32_e64 v11, 0, v11, s[4:5]
	v_cndmask_b32_e64 v10, 0, v10, s[4:5]
	v_cndmask_b32_e64 v9, v9, 0, s[8:9]
	v_cndmask_b32_e64 v8, v8, 0, s[8:9]
	v_cndmask_b32_e64 v7, 0, v7, s[6:7]
	v_cndmask_b32_e64 v6, 0, v6, s[6:7]
	v_cndmask_b32_e64 v5, 0, v5, s[4:5]
	v_cndmask_b32_e64 v4, 0, v4, s[4:5]
	v_pk_fma_f32 v[0:1], v[0:1], v[212:213], v[208:209]
	v_pk_fma_f32 v[2:3], v[2:3], v[214:215], v[210:211]
	v_pk_fma_f32 v[0:1], v[14:15], v[216:217], v[0:1]
	v_pk_fma_f32 v[2:3], v[8:9], v[218:219], v[2:3]
	v_pk_fma_f32 v[0:1], v[12:13], v[220:221], v[0:1]
	s_nop 0
	v_pk_fma_f32 v[0:1], v[10:11], v[224:225], v[0:1]
	v_pk_fma_f32 v[2:3], v[6:7], v[222:223], v[2:3]
	v_mul_f32_e32 v10, 0xbfb8aa3b, v1
	v_exp_f32_e32 v10, v10
	v_pk_fma_f32 v[2:3], v[4:5], v[226:227], v[2:3]
	v_add_f32_e32 v10, 1.0, v10
	v_rcp_f32_e32 v11, v10
	v_mul_f32_e32 v10, 0xbfb8aa3b, v0
	v_exp_f32_e32 v10, v10
	s_nop 0
	v_add_f32_e32 v10, 1.0, v10
	v_rcp_f32_e32 v10, v10
	s_nop 0
	v_pk_mul_f32 v[0:1], v[0:1], v[10:11]
	s_nop 0
	v_cvt_pk_bf16_f32 v0, v0, v1
	v_mul_f32_e32 v1, 0xbfb8aa3b, v3
	v_exp_f32_e32 v1, v1
	s_nop 0
	v_add_f32_e32 v1, 1.0, v1
	v_rcp_f32_e32 v5, v1
	v_mul_f32_e32 v1, 0xbfb8aa3b, v2
	v_exp_f32_e32 v1, v1
	s_nop 0
	v_add_f32_e32 v1, 1.0, v1
	v_rcp_f32_e32 v4, v1
	s_nop 0
	v_pk_mul_f32 v[2:3], v[2:3], v[4:5]
	s_nop 0
	v_cvt_pk_bf16_f32 v1, v2, v3
	global_store_dwordx2 v[16:17], v[0:1], off offset:264
